# v18 + GEMM phases: one static s_setprio raise for the trailing half-workgroup per phase instead of per-MFMA-group priority toggling
# baseline (speedup 1.0000x reference)
.LBB0_135:
	v_writelane_b32 v244, s26, 21
	s_nop 1
	v_writelane_b32 v244, s27, 22
	s_or_b64 exec, exec, s[0:1]
	s_cmpk_lt_i32 s2, 0x69a
	s_cselect_b64 s[0:1], -1, 0
	s_mov_b64 s[46:47], s[62:63]
	s_mov_b64 s[44:45], s[60:61]
	s_waitcnt vmcnt(1)
	v_mov_b32_e32 v8, v220
	s_waitcnt lgkmcnt(0)
	s_barrier
	s_cselect_b32 s99, 1, 0
	v_readfirstlane_b32 s98, v220
	s_lshr_b32 s98, s98, 8
	s_cmp_lg_u32 s98, 0
	s_cbranch_scc0 .Lprio_skip0
	s_setprio 1
.Lprio_skip0:
	s_cmp_lg_u32 s99, 0
	s_and_b64 vcc, exec, s[0:1]
	v_readfirstlane_b32 s10, v8
	s_cbranch_vccz .LBB0_137
	s_ashr_i32 s3, s2, 31
	s_lshr_b32 s3, s3, 29
	s_add_i32 s3, s2, s3
	s_and_b32 s8, s3, -8
	s_sub_i32 s8, s2, s8
	s_mul_i32 s11, s8, 0xd3
	s_add_i32 s11, s11, 2
	s_ashr_i32 s3, s3, 3
	s_mul_i32 s9, s8, 0xd4
	s_cmp_lt_i32 s8, 2
	s_cselect_b32 s8, s9, s11
	s_add_i32 s8, s8, s3
	s_mul_hi_i32 s3, s8, 0x4ec4ec4f
	s_lshr_b32 s9, s3, 31
	s_ashr_i32 s3, s3, 5
	s_add_i32 s3, s3, s9
	s_lshl_b32 s11, s3, 3
	s_sub_i32 s9, 0x82, s11
	s_mulk_i32 s3, 0x68
	s_min_u32 s20, s9, 8
	s_sub_i32 s3, s8, s3
	s_sext_i32_i8 s8, s3
	v_cvt_f32_ubyte0_e32 v1, s20
	v_cvt_f32_i32_e32 v0, s8
	v_rcp_iflag_f32_e32 v2, v1
	s_ashr_i32 s8, s8, 30
	s_or_b32 s21, s8, 1
	v_mul_f32_e32 v2, v0, v2
	v_trunc_f32_e32 v2, v2
	v_fma_f32 v0, -v2, v1, v0
	v_cvt_i32_f32_e32 v2, v2
	v_cmp_ge_f32_e64 s[8:9], |v0|, v1
	s_and_b64 s[8:9], s[8:9], exec
	s_cselect_b32 s8, s21, 0
	v_readfirstlane_b32 s9, v2
	s_add_i32 s8, s9, s8
	s_sext_i32_i8 s58, s8
	s_mul_i32 s8, s8, s20
	s_sub_i32 s3, s3, s8
	s_sext_i32_i8 s3, s3
	s_add_i32 s94, s11, s3

.LBB0_150:
	ds_read_b128 v[128:131], v181
	ds_read_b128 v[132:135], v181 offset:1024
	ds_read_b128 v[166:169], v181 offset:2048
	ds_read_b128 v[170:173], v181 offset:3072
	ds_read_b128 v[174:177], v182
	ds_read_b128 v[186:189], v182 offset:1024
	ds_read_b128 v[190:193], v182 offset:2048
	ds_read_b128 v[194:197], v182 offset:3072
	s_add_u32 s8, s0, 0xfffc0080
	s_addc_u32 s9, s1, -1
	s_cmp_eq_u32 s41, 12
	s_cselect_b32 s11, s20, s9
	s_cselect_b32 s10, s21, s8
	s_cselect_b32 s9, s22, s40
	s_cselect_b32 s8, s23, s33
	v_lshl_add_u64 v[178:179], s[0:1], 0, v[156:157]
	s_add_i32 m0, s59, 0xc000
	ds_read_b128 v[198:201], v183
	ds_read_b128 v[202:205], v183 offset:1024
	ds_read_b128 v[206:209], v183 offset:2048
	ds_read_b128 v[210:213], v183 offset:3072
	ds_read_b128 v[214:217], v183 offset:4096
	ds_read_b128 v[222:225], v183 offset:5120
	ds_read_b128 v[226:229], v183 offset:6144
	ds_read_b128 v[230:233], v183 offset:7168
	global_load_lds_dwordx4 v[178:179], off
	v_lshl_add_u64 v[178:179], s[0:1], 0, v[158:159]
	s_add_i32 m0, s59, 0xe000
	s_nop 0
	global_load_lds_dwordx4 v[178:179], off
	s_waitcnt vmcnt(8)
	s_waitcnt lgkmcnt(0)
	s_barrier
	s_waitcnt lgkmcnt(0)
	v_mfma_f32_16x16x32_bf16 v[124:127], v[128:131], v[198:201], v[124:127]
	v_mfma_f32_16x16x32_bf16 v[120:123], v[166:169], v[198:201], v[120:123]
	v_mfma_f32_16x16x32_bf16 v[112:115], v[128:131], v[206:209], v[112:115]
	v_mfma_f32_16x16x32_bf16 v[104:107], v[166:169], v[206:209], v[104:107]
	v_mfma_f32_16x16x32_bf16 v[96:99], v[128:131], v[214:217], v[96:99]
	v_mfma_f32_16x16x32_bf16 v[88:91], v[166:169], v[214:217], v[88:91]
	v_mfma_f32_16x16x32_bf16 v[80:83], v[128:131], v[226:229], v[80:83]
	v_mfma_f32_16x16x32_bf16 v[72:75], v[166:169], v[226:229], v[72:75]
	v_mfma_f32_16x16x32_bf16 v[124:127], v[132:135], v[202:205], v[124:127]
	v_mfma_f32_16x16x32_bf16 v[120:123], v[170:173], v[202:205], v[120:123]
	v_mfma_f32_16x16x32_bf16 v[112:115], v[132:135], v[210:213], v[112:115]
	v_mfma_f32_16x16x32_bf16 v[104:107], v[170:173], v[210:213], v[104:107]
	v_mfma_f32_16x16x32_bf16 v[96:99], v[132:135], v[222:225], v[96:99]
	v_mfma_f32_16x16x32_bf16 v[88:91], v[170:173], v[222:225], v[88:91]
	v_mfma_f32_16x16x32_bf16 v[80:83], v[132:135], v[230:233], v[80:83]
	v_mfma_f32_16x16x32_bf16 v[72:75], v[170:173], v[230:233], v[72:75]
	v_mfma_f32_16x16x32_bf16 v[116:119], v[174:177], v[198:201], v[116:119]
	v_mfma_f32_16x16x32_bf16 v[108:111], v[190:193], v[198:201], v[108:111]
	v_mfma_f32_16x16x32_bf16 v[100:103], v[174:177], v[206:209], v[100:103]
	v_mfma_f32_16x16x32_bf16 v[92:95], v[190:193], v[206:209], v[92:95]
	v_mfma_f32_16x16x32_bf16 v[84:87], v[174:177], v[214:217], v[84:87]
	v_mfma_f32_16x16x32_bf16 v[76:79], v[190:193], v[214:217], v[76:79]
	v_mfma_f32_16x16x32_bf16 v[68:71], v[174:177], v[226:229], v[68:71]
	v_mfma_f32_16x16x32_bf16 v[64:67], v[190:193], v[226:229], v[64:67]
	v_mfma_f32_16x16x32_bf16 v[116:119], v[186:189], v[202:205], v[116:119]
	v_mfma_f32_16x16x32_bf16 v[108:111], v[194:197], v[202:205], v[108:111]
	v_mfma_f32_16x16x32_bf16 v[100:103], v[186:189], v[210:213], v[100:103]
	v_mfma_f32_16x16x32_bf16 v[92:95], v[194:197], v[210:213], v[92:95]
	v_mfma_f32_16x16x32_bf16 v[84:87], v[186:189], v[222:225], v[84:87]
	v_mfma_f32_16x16x32_bf16 v[76:79], v[194:197], v[222:225], v[76:79]
	v_mfma_f32_16x16x32_bf16 v[68:71], v[186:189], v[230:233], v[68:71]
	v_mfma_f32_16x16x32_bf16 v[64:67], v[194:197], v[230:233], v[64:67]
	s_barrier
	s_add_i32 s42, s56, s83
	v_lshl_add_u64 v[178:179], s[8:9], 0, v[138:139]
	s_mov_b32 m0, s42
	ds_read_b128 v[198:201], v183 offset:16384
	ds_read_b128 v[202:205], v183 offset:17408
	ds_read_b128 v[206:209], v183 offset:18432
	ds_read_b128 v[210:213], v183 offset:19456
	ds_read_b128 v[214:217], v183 offset:20480
	ds_read_b128 v[222:225], v183 offset:21504
	ds_read_b128 v[226:229], v183 offset:22528
	ds_read_b128 v[230:233], v183 offset:23552
	global_load_lds_dwordx4 v[178:179], off
	s_add_i32 m0, s42, 0x2000
	s_add_u32 s42, s8, 0x40000
	v_lshl_add_u64 v[218:219], s[8:9], 0, v[142:143]
	s_addc_u32 s43, s9, 0
	s_add_i32 s49, s57, s83
	global_load_lds_dwordx4 v[218:219], off
	v_lshl_add_u64 v[234:235], s[42:43], 0, v[138:139]
	s_mov_b32 m0, s49
	v_lshl_add_u64 v[236:237], s[10:11], 0, v[140:141]
	global_load_lds_dwordx4 v[234:235], off
	v_lshl_add_u64 v[234:235], s[42:43], 0, v[142:143]
	s_add_i32 m0, s49, 0x2000
	s_nop 0
	global_load_lds_dwordx4 v[234:235], off
	v_lshl_add_u64 v[234:235], s[10:11], 0, v[136:137]
	s_mov_b32 m0, s59
	s_nop 0
	global_load_lds_dwordx4 v[234:235], off
	s_mov_b32 m0, s86
	s_nop 0
	global_load_lds_dwordx4 v[236:237], off
	s_waitcnt vmcnt(8)
	s_waitcnt lgkmcnt(0)
	s_barrier
	s_waitcnt lgkmcnt(0)
	v_mfma_f32_16x16x32_bf16 v[60:63], v[128:131], v[198:201], v[60:63]
	v_mfma_f32_16x16x32_bf16 v[56:59], v[166:169], v[198:201], v[56:59]
	v_mfma_f32_16x16x32_bf16 v[48:51], v[128:131], v[206:209], v[48:51]
	v_mfma_f32_16x16x32_bf16 v[40:43], v[166:169], v[206:209], v[40:43]
	v_mfma_f32_16x16x32_bf16 v[32:35], v[128:131], v[214:217], v[32:35]
	v_mfma_f32_16x16x32_bf16 v[24:27], v[166:169], v[214:217], v[24:27]
	v_mfma_f32_16x16x32_bf16 v[16:19], v[128:131], v[226:229], v[16:19]
	v_mfma_f32_16x16x32_bf16 v[8:11], v[166:169], v[226:229], v[8:11]
	v_mfma_f32_16x16x32_bf16 v[60:63], v[132:135], v[202:205], v[60:63]
	v_mfma_f32_16x16x32_bf16 v[56:59], v[170:173], v[202:205], v[56:59]
	v_mfma_f32_16x16x32_bf16 v[48:51], v[132:135], v[210:213], v[48:51]
	v_mfma_f32_16x16x32_bf16 v[40:43], v[170:173], v[210:213], v[40:43]
	v_mfma_f32_16x16x32_bf16 v[32:35], v[132:135], v[222:225], v[32:35]
	v_mfma_f32_16x16x32_bf16 v[24:27], v[170:173], v[222:225], v[24:27]
	v_mfma_f32_16x16x32_bf16 v[16:19], v[132:135], v[230:233], v[16:19]
	v_mfma_f32_16x16x32_bf16 v[8:11], v[170:173], v[230:233], v[8:11]
	v_mfma_f32_16x16x32_bf16 v[52:55], v[174:177], v[198:201], v[52:55]
	v_mfma_f32_16x16x32_bf16 v[44:47], v[190:193], v[198:201], v[44:47]
	v_mfma_f32_16x16x32_bf16 v[36:39], v[174:177], v[206:209], v[36:39]
	v_mfma_f32_16x16x32_bf16 v[28:31], v[190:193], v[206:209], v[28:31]
	v_mfma_f32_16x16x32_bf16 v[20:23], v[174:177], v[214:217], v[20:23]
	v_mfma_f32_16x16x32_bf16 v[12:15], v[190:193], v[214:217], v[12:15]
	v_mfma_f32_16x16x32_bf16 v[4:7], v[174:177], v[226:229], v[4:7]
	v_mfma_f32_16x16x32_bf16 v[0:3], v[190:193], v[226:229], v[0:3]
	v_mfma_f32_16x16x32_bf16 v[52:55], v[186:189], v[202:205], v[52:55]
	v_mfma_f32_16x16x32_bf16 v[44:47], v[194:197], v[202:205], v[44:47]
	v_mfma_f32_16x16x32_bf16 v[36:39], v[186:189], v[210:213], v[36:39]
	v_mfma_f32_16x16x32_bf16 v[28:31], v[194:197], v[210:213], v[28:31]
	v_mfma_f32_16x16x32_bf16 v[20:23], v[186:189], v[222:225], v[20:23]
	v_mfma_f32_16x16x32_bf16 v[12:15], v[194:197], v[222:225], v[12:15]
	v_mfma_f32_16x16x32_bf16 v[4:7], v[186:189], v[230:233], v[4:7]
	v_mfma_f32_16x16x32_bf16 v[0:3], v[194:197], v[230:233], v[0:3]
	s_barrier
	s_add_i32 s42, 0, 0x18000
	v_add_u32_e32 v144, s42, v180
	s_add_i32 s43, 0, 0x1c000
	ds_read_b128 v[128:131], v144
	ds_read_b128 v[132:135], v144 offset:1024
	ds_read_b128 v[166:169], v144 offset:2048
	ds_read_b128 v[170:173], v144 offset:3072
	v_add_u32_e32 v144, s43, v180
	ds_read_b128 v[174:177], v144
	ds_read_b128 v[186:189], v144 offset:1024
	ds_read_b128 v[190:193], v144 offset:2048
	ds_read_b128 v[194:197], v144 offset:3072
	s_add_u32 s10, s10, 0x40000
	s_addc_u32 s11, s11, 0
	s_mov_b32 m0, s87
	v_lshl_add_u64 v[238:239], s[10:11], 0, v[136:137]
	ds_read_b128 v[198:201], v183 offset:32768
	ds_read_b128 v[202:205], v183 offset:33792
	ds_read_b128 v[206:209], v183 offset:34816
	ds_read_b128 v[210:213], v183 offset:35840
	ds_read_b128 v[214:217], v183 offset:36864
	ds_read_b128 v[222:225], v183 offset:37888
	ds_read_b128 v[226:229], v183 offset:38912
	ds_read_b128 v[230:233], v183 offset:39936
	global_load_lds_dwordx4 v[238:239], off
	v_lshl_add_u64 v[238:239], s[10:11], 0, v[140:141]
	s_mov_b32 m0, s91
	s_nop 0
	global_load_lds_dwordx4 v[238:239], off
	s_waitcnt vmcnt(8)
	s_waitcnt lgkmcnt(0)
	s_barrier
	s_waitcnt lgkmcnt(0)
	v_mfma_f32_16x16x32_bf16 v[124:127], v[128:131], v[198:201], v[124:127]
	v_mfma_f32_16x16x32_bf16 v[120:123], v[166:169], v[198:201], v[120:123]
	v_mfma_f32_16x16x32_bf16 v[112:115], v[128:131], v[206:209], v[112:115]
	v_mfma_f32_16x16x32_bf16 v[104:107], v[166:169], v[206:209], v[104:107]
	v_mfma_f32_16x16x32_bf16 v[96:99], v[128:131], v[214:217], v[96:99]
	v_mfma_f32_16x16x32_bf16 v[88:91], v[166:169], v[214:217], v[88:91]
	v_mfma_f32_16x16x32_bf16 v[80:83], v[128:131], v[226:229], v[80:83]
	v_mfma_f32_16x16x32_bf16 v[72:75], v[166:169], v[226:229], v[72:75]
	v_mfma_f32_16x16x32_bf16 v[124:127], v[132:135], v[202:205], v[124:127]
	v_mfma_f32_16x16x32_bf16 v[120:123], v[170:173], v[202:205], v[120:123]
	v_mfma_f32_16x16x32_bf16 v[112:115], v[132:135], v[210:213], v[112:115]
	v_mfma_f32_16x16x32_bf16 v[104:107], v[170:173], v[210:213], v[104:107]
	v_mfma_f32_16x16x32_bf16 v[96:99], v[132:135], v[222:225], v[96:99]
	v_mfma_f32_16x16x32_bf16 v[88:91], v[170:173], v[222:225], v[88:91]
	v_mfma_f32_16x16x32_bf16 v[80:83], v[132:135], v[230:233], v[80:83]
	v_mfma_f32_16x16x32_bf16 v[72:75], v[170:173], v[230:233], v[72:75]
	v_mfma_f32_16x16x32_bf16 v[116:119], v[174:177], v[198:201], v[116:119]
	v_mfma_f32_16x16x32_bf16 v[108:111], v[190:193], v[198:201], v[108:111]
	v_mfma_f32_16x16x32_bf16 v[100:103], v[174:177], v[206:209], v[100:103]
	v_mfma_f32_16x16x32_bf16 v[92:95], v[190:193], v[206:209], v[92:95]
	v_mfma_f32_16x16x32_bf16 v[84:87], v[174:177], v[214:217], v[84:87]
	v_mfma_f32_16x16x32_bf16 v[76:79], v[190:193], v[214:217], v[76:79]
	v_mfma_f32_16x16x32_bf16 v[68:71], v[174:177], v[226:229], v[68:71]
	v_mfma_f32_16x16x32_bf16 v[64:67], v[190:193], v[226:229], v[64:67]
	v_mfma_f32_16x16x32_bf16 v[116:119], v[186:189], v[202:205], v[116:119]
	v_mfma_f32_16x16x32_bf16 v[108:111], v[194:197], v[202:205], v[108:111]
	v_mfma_f32_16x16x32_bf16 v[100:103], v[186:189], v[210:213], v[100:103]
	v_mfma_f32_16x16x32_bf16 v[92:95], v[194:197], v[210:213], v[92:95]
	v_mfma_f32_16x16x32_bf16 v[84:87], v[186:189], v[222:225], v[84:87]
	v_mfma_f32_16x16x32_bf16 v[76:79], v[194:197], v[222:225], v[76:79]
	v_mfma_f32_16x16x32_bf16 v[68:71], v[186:189], v[230:233], v[68:71]
	v_mfma_f32_16x16x32_bf16 v[64:67], v[194:197], v[230:233], v[64:67]
	s_barrier
	s_add_i32 s10, s42, s83
	v_lshl_add_u64 v[178:179], v[178:179], 0, s[54:55]
	s_mov_b32 m0, s10
	ds_read_b128 v[198:201], v183 offset:49152
	ds_read_b128 v[202:205], v183 offset:50176
	ds_read_b128 v[206:209], v183 offset:51200
	ds_read_b128 v[210:213], v183 offset:52224
	ds_read_b128 v[214:217], v183 offset:53248
	ds_read_b128 v[222:225], v183 offset:54272
	ds_read_b128 v[226:229], v183 offset:55296
	ds_read_b128 v[230:233], v183 offset:56320
	global_load_lds_dwordx4 v[178:179], off
	s_add_i32 m0, s10, 0x2000
	s_add_u32 s8, s8, 0x40080
	v_lshl_add_u64 v[178:179], v[218:219], 0, s[54:55]
	s_addc_u32 s9, s9, 0
	s_add_i32 s10, s43, s83
	global_load_lds_dwordx4 v[178:179], off
	v_lshl_add_u64 v[178:179], s[8:9], 0, v[138:139]
	s_mov_b32 m0, s10
	s_nop 0
	global_load_lds_dwordx4 v[178:179], off
	v_lshl_add_u64 v[178:179], s[8:9], 0, v[142:143]
	s_add_i32 m0, s10, 0x2000
	s_nop 0
	global_load_lds_dwordx4 v[178:179], off
	v_lshl_add_u64 v[178:179], v[234:235], 0, s[54:55]
	s_mov_b32 m0, s82
	s_nop 0
	global_load_lds_dwordx4 v[178:179], off
	v_lshl_add_u64 v[178:179], v[236:237], 0, s[54:55]
	s_mov_b32 m0, s95
	s_nop 0
	global_load_lds_dwordx4 v[178:179], off
	s_waitcnt vmcnt(8)
	s_waitcnt lgkmcnt(0)
	s_barrier
	s_waitcnt lgkmcnt(0)
	v_mfma_f32_16x16x32_bf16 v[60:63], v[128:131], v[198:201], v[60:63]
	v_mfma_f32_16x16x32_bf16 v[56:59], v[166:169], v[198:201], v[56:59]
	v_mfma_f32_16x16x32_bf16 v[48:51], v[128:131], v[206:209], v[48:51]
	v_mfma_f32_16x16x32_bf16 v[40:43], v[166:169], v[206:209], v[40:43]
	v_mfma_f32_16x16x32_bf16 v[32:35], v[128:131], v[214:217], v[32:35]
	v_mfma_f32_16x16x32_bf16 v[24:27], v[166:169], v[214:217], v[24:27]
	v_mfma_f32_16x16x32_bf16 v[16:19], v[128:131], v[226:229], v[16:19]
	v_mfma_f32_16x16x32_bf16 v[8:11], v[166:169], v[226:229], v[8:11]
	v_mfma_f32_16x16x32_bf16 v[60:63], v[132:135], v[202:205], v[60:63]
	v_mfma_f32_16x16x32_bf16 v[56:59], v[170:173], v[202:205], v[56:59]
	v_mfma_f32_16x16x32_bf16 v[48:51], v[132:135], v[210:213], v[48:51]
	v_mfma_f32_16x16x32_bf16 v[40:43], v[170:173], v[210:213], v[40:43]
	v_mfma_f32_16x16x32_bf16 v[32:35], v[132:135], v[222:225], v[32:35]
	v_mfma_f32_16x16x32_bf16 v[24:27], v[170:173], v[222:225], v[24:27]
	v_mfma_f32_16x16x32_bf16 v[16:19], v[132:135], v[230:233], v[16:19]
	v_mfma_f32_16x16x32_bf16 v[8:11], v[170:173], v[230:233], v[8:11]
	v_mfma_f32_16x16x32_bf16 v[52:55], v[174:177], v[198:201], v[52:55]
	v_mfma_f32_16x16x32_bf16 v[44:47], v[190:193], v[198:201], v[44:47]
	v_mfma_f32_16x16x32_bf16 v[36:39], v[174:177], v[206:209], v[36:39]
	v_mfma_f32_16x16x32_bf16 v[28:31], v[190:193], v[206:209], v[28:31]
	v_mfma_f32_16x16x32_bf16 v[20:23], v[174:177], v[214:217], v[20:23]
	v_mfma_f32_16x16x32_bf16 v[12:15], v[190:193], v[214:217], v[12:15]
	v_mfma_f32_16x16x32_bf16 v[4:7], v[174:177], v[226:229], v[4:7]
	v_mfma_f32_16x16x32_bf16 v[0:3], v[190:193], v[226:229], v[0:3]
	v_mfma_f32_16x16x32_bf16 v[52:55], v[186:189], v[202:205], v[52:55]
	v_mfma_f32_16x16x32_bf16 v[44:47], v[194:197], v[202:205], v[44:47]
	v_mfma_f32_16x16x32_bf16 v[36:39], v[186:189], v[210:213], v[36:39]
	v_mfma_f32_16x16x32_bf16 v[28:31], v[194:197], v[210:213], v[28:31]
	v_mfma_f32_16x16x32_bf16 v[20:23], v[186:189], v[222:225], v[20:23]
	v_mfma_f32_16x16x32_bf16 v[12:15], v[194:197], v[222:225], v[12:15]
	v_mfma_f32_16x16x32_bf16 v[4:7], v[186:189], v[230:233], v[4:7]
	v_mfma_f32_16x16x32_bf16 v[0:3], v[194:197], v[230:233], v[0:3]
	s_barrier
	s_add_i32 s41, s41, 2
	s_add_u32 s0, s0, 0x100
	s_addc_u32 s1, s1, 0
	s_add_u32 s33, s33, 0x100
	s_addc_u32 s40, s40, 0
	s_cmp_gt_u32 s41, 13
	s_cbranch_scc0 .LBB0_150
	s_and_b64 vcc, exec, s[68:69]
	s_movk_i32 s49, 0x220
	s_cbranch_vccz .LBB0_153
	s_barrier

.LBB0_482:
	ds_read_b128 v[138:141], v160
	ds_read_b128 v[142:145], v160 offset:1024
	ds_read_b128 v[146:149], v160 offset:2048
	ds_read_b128 v[150:153], v160 offset:3072
	ds_read_b128 v[164:167], v161
	ds_read_b128 v[168:171], v161 offset:1024
	ds_read_b128 v[172:175], v161 offset:2048
	ds_read_b128 v[176:179], v161 offset:3072
	s_add_u32 s64, s38, 0xfffc0080
	s_addc_u32 s65, s39, -1
	s_cmp_eq_u32 s83, 12
	s_cselect_b32 s67, s9, s65
	s_cselect_b32 s66, s11, s64
	s_cselect_b32 s65, s22, s59
	s_cselect_b32 s64, s23, s57
	v_lshl_add_u64 v[154:155], s[38:39], 0, v[134:135]
	s_add_i32 m0, s71, 0xc000
	ds_read_b128 v[180:183], v162
	ds_read_b128 v[184:187], v162 offset:1024
	ds_read_b128 v[188:191], v162 offset:2048
	ds_read_b128 v[192:195], v162 offset:3072
	ds_read_b128 v[196:199], v162 offset:4096
	ds_read_b128 v[200:203], v162 offset:5120
	ds_read_b128 v[204:207], v162 offset:6144
	ds_read_b128 v[208:211], v162 offset:7168
	global_load_lds_dwordx4 v[154:155], off
	v_lshl_add_u64 v[154:155], s[38:39], 0, v[136:137]
	s_add_i32 m0, s71, 0xe000
	s_nop 0
	global_load_lds_dwordx4 v[154:155], off
	s_waitcnt vmcnt(8)
	s_waitcnt lgkmcnt(0)
	s_barrier
	s_waitcnt lgkmcnt(0)
	v_mfma_f32_16x16x32_bf16 v[124:127], v[138:141], v[180:183], v[124:127]
	v_mfma_f32_16x16x32_bf16 v[120:123], v[146:149], v[180:183], v[120:123]
	v_mfma_f32_16x16x32_bf16 v[108:111], v[138:141], v[188:191], v[108:111]
	v_mfma_f32_16x16x32_bf16 v[104:107], v[146:149], v[188:191], v[104:107]
	v_mfma_f32_16x16x32_bf16 v[92:95], v[138:141], v[196:199], v[92:95]
	v_mfma_f32_16x16x32_bf16 v[88:91], v[146:149], v[196:199], v[88:91]
	v_mfma_f32_16x16x32_bf16 v[76:79], v[138:141], v[204:207], v[76:79]
	v_mfma_f32_16x16x32_bf16 v[72:75], v[146:149], v[204:207], v[72:75]
	v_mfma_f32_16x16x32_bf16 v[124:127], v[142:145], v[184:187], v[124:127]
	v_mfma_f32_16x16x32_bf16 v[120:123], v[150:153], v[184:187], v[120:123]
	v_mfma_f32_16x16x32_bf16 v[108:111], v[142:145], v[192:195], v[108:111]
	v_mfma_f32_16x16x32_bf16 v[104:107], v[150:153], v[192:195], v[104:107]
	v_mfma_f32_16x16x32_bf16 v[92:95], v[142:145], v[200:203], v[92:95]
	v_mfma_f32_16x16x32_bf16 v[88:91], v[150:153], v[200:203], v[88:91]
	v_mfma_f32_16x16x32_bf16 v[76:79], v[142:145], v[208:211], v[76:79]
	v_mfma_f32_16x16x32_bf16 v[72:75], v[150:153], v[208:211], v[72:75]
	v_mfma_f32_16x16x32_bf16 v[116:119], v[164:167], v[180:183], v[116:119]
	v_mfma_f32_16x16x32_bf16 v[112:115], v[172:175], v[180:183], v[112:115]
	v_mfma_f32_16x16x32_bf16 v[100:103], v[164:167], v[188:191], v[100:103]
	v_mfma_f32_16x16x32_bf16 v[96:99], v[172:175], v[188:191], v[96:99]
	v_mfma_f32_16x16x32_bf16 v[84:87], v[164:167], v[196:199], v[84:87]
	v_mfma_f32_16x16x32_bf16 v[80:83], v[172:175], v[196:199], v[80:83]
	v_mfma_f32_16x16x32_bf16 v[68:71], v[164:167], v[204:207], v[68:71]
	v_mfma_f32_16x16x32_bf16 v[64:67], v[172:175], v[204:207], v[64:67]
	v_mfma_f32_16x16x32_bf16 v[116:119], v[168:171], v[184:187], v[116:119]
	v_mfma_f32_16x16x32_bf16 v[112:115], v[176:179], v[184:187], v[112:115]
	v_mfma_f32_16x16x32_bf16 v[100:103], v[168:171], v[192:195], v[100:103]
	v_mfma_f32_16x16x32_bf16 v[96:99], v[176:179], v[192:195], v[96:99]
	v_mfma_f32_16x16x32_bf16 v[84:87], v[168:171], v[200:203], v[84:87]
	v_mfma_f32_16x16x32_bf16 v[80:83], v[176:179], v[200:203], v[80:83]
	v_mfma_f32_16x16x32_bf16 v[68:71], v[168:171], v[208:211], v[68:71]
	v_mfma_f32_16x16x32_bf16 v[64:67], v[176:179], v[208:211], v[64:67]
	s_barrier
	s_add_i32 s86, s81, s21
	v_lshl_add_u64 v[154:155], s[64:65], 0, v[128:129]
	s_mov_b32 m0, s86
	ds_read_b128 v[180:183], v162 offset:16384
	ds_read_b128 v[184:187], v162 offset:17408
	ds_read_b128 v[188:191], v162 offset:18432
	ds_read_b128 v[192:195], v162 offset:19456
	ds_read_b128 v[196:199], v162 offset:20480
	ds_read_b128 v[200:203], v162 offset:21504
	ds_read_b128 v[204:207], v162 offset:22528
	ds_read_b128 v[208:211], v162 offset:23552
	global_load_lds_dwordx4 v[154:155], off
	s_add_i32 m0, s86, 0x2000
	s_add_u32 s86, s64, 0x40000
	v_lshl_add_u64 v[212:213], s[64:65], 0, v[130:131]
	s_addc_u32 s87, s65, 0
	s_add_i32 s91, s82, s21
	global_load_lds_dwordx4 v[212:213], off
	v_lshl_add_u64 v[214:215], s[86:87], 0, v[128:129]
	s_mov_b32 m0, s91
	v_lshl_add_u64 v[216:217], s[66:67], 0, v[130:131]
	global_load_lds_dwordx4 v[214:215], off
	v_lshl_add_u64 v[214:215], s[86:87], 0, v[130:131]
	s_add_i32 m0, s91, 0x2000
	s_nop 0
	global_load_lds_dwordx4 v[214:215], off
	v_lshl_add_u64 v[214:215], s[66:67], 0, v[128:129]
	s_mov_b32 m0, s71
	s_nop 0
	global_load_lds_dwordx4 v[214:215], off
	s_mov_b32 m0, s72
	s_nop 0
	global_load_lds_dwordx4 v[216:217], off
	s_waitcnt vmcnt(8)
	s_waitcnt lgkmcnt(0)
	s_barrier
	s_waitcnt lgkmcnt(0)
	v_mfma_f32_16x16x32_bf16 v[60:63], v[138:141], v[180:183], v[60:63]
	v_mfma_f32_16x16x32_bf16 v[56:59], v[146:149], v[180:183], v[56:59]
	v_mfma_f32_16x16x32_bf16 v[44:47], v[138:141], v[188:191], v[44:47]
	v_mfma_f32_16x16x32_bf16 v[40:43], v[146:149], v[188:191], v[40:43]
	v_mfma_f32_16x16x32_bf16 v[28:31], v[138:141], v[196:199], v[28:31]
	v_mfma_f32_16x16x32_bf16 v[24:27], v[146:149], v[196:199], v[24:27]
	v_mfma_f32_16x16x32_bf16 v[12:15], v[138:141], v[204:207], v[12:15]
	v_mfma_f32_16x16x32_bf16 v[8:11], v[146:149], v[204:207], v[8:11]
	v_mfma_f32_16x16x32_bf16 v[60:63], v[142:145], v[184:187], v[60:63]
	v_mfma_f32_16x16x32_bf16 v[56:59], v[150:153], v[184:187], v[56:59]
	v_mfma_f32_16x16x32_bf16 v[44:47], v[142:145], v[192:195], v[44:47]
	v_mfma_f32_16x16x32_bf16 v[40:43], v[150:153], v[192:195], v[40:43]
	v_mfma_f32_16x16x32_bf16 v[28:31], v[142:145], v[200:203], v[28:31]
	v_mfma_f32_16x16x32_bf16 v[24:27], v[150:153], v[200:203], v[24:27]
	v_mfma_f32_16x16x32_bf16 v[12:15], v[142:145], v[208:211], v[12:15]
	v_mfma_f32_16x16x32_bf16 v[8:11], v[150:153], v[208:211], v[8:11]
	v_mfma_f32_16x16x32_bf16 v[52:55], v[164:167], v[180:183], v[52:55]
	v_mfma_f32_16x16x32_bf16 v[48:51], v[172:175], v[180:183], v[48:51]
	v_mfma_f32_16x16x32_bf16 v[36:39], v[164:167], v[188:191], v[36:39]
	v_mfma_f32_16x16x32_bf16 v[32:35], v[172:175], v[188:191], v[32:35]
	v_mfma_f32_16x16x32_bf16 v[20:23], v[164:167], v[196:199], v[20:23]
	v_mfma_f32_16x16x32_bf16 v[16:19], v[172:175], v[196:199], v[16:19]
	v_mfma_f32_16x16x32_bf16 v[4:7], v[164:167], v[204:207], v[4:7]
	v_mfma_f32_16x16x32_bf16 v[0:3], v[172:175], v[204:207], v[0:3]
	v_mfma_f32_16x16x32_bf16 v[52:55], v[168:171], v[184:187], v[52:55]
	v_mfma_f32_16x16x32_bf16 v[48:51], v[176:179], v[184:187], v[48:51]
	v_mfma_f32_16x16x32_bf16 v[36:39], v[168:171], v[192:195], v[36:39]
	v_mfma_f32_16x16x32_bf16 v[32:35], v[176:179], v[192:195], v[32:35]
	v_mfma_f32_16x16x32_bf16 v[20:23], v[168:171], v[200:203], v[20:23]
	v_mfma_f32_16x16x32_bf16 v[16:19], v[176:179], v[200:203], v[16:19]
	v_mfma_f32_16x16x32_bf16 v[4:7], v[168:171], v[208:211], v[4:7]
	v_mfma_f32_16x16x32_bf16 v[0:3], v[176:179], v[208:211], v[0:3]
	s_barrier
	s_add_i32 s86, 0, 0x18000
	v_add_u32_e32 v132, s86, v159
	s_add_i32 s87, 0, 0x1c000
	ds_read_b128 v[138:141], v132
	ds_read_b128 v[142:145], v132 offset:1024
	ds_read_b128 v[146:149], v132 offset:2048
	ds_read_b128 v[150:153], v132 offset:3072
	v_add_u32_e32 v132, s87, v159
	ds_read_b128 v[164:167], v132
	ds_read_b128 v[168:171], v132 offset:1024
	ds_read_b128 v[172:175], v132 offset:2048
	ds_read_b128 v[176:179], v132 offset:3072
	s_add_u32 s66, s66, 0x40000
	s_addc_u32 s67, s67, 0
	s_mov_b32 m0, s73
	v_lshl_add_u64 v[218:219], s[66:67], 0, v[128:129]
	ds_read_b128 v[180:183], v162 offset:32768
	ds_read_b128 v[184:187], v162 offset:33792
	ds_read_b128 v[188:191], v162 offset:34816
	ds_read_b128 v[192:195], v162 offset:35840
	ds_read_b128 v[196:199], v162 offset:36864
	ds_read_b128 v[200:203], v162 offset:37888
	ds_read_b128 v[204:207], v162 offset:38912
	ds_read_b128 v[208:211], v162 offset:39936
	global_load_lds_dwordx4 v[218:219], off
	v_lshl_add_u64 v[218:219], s[66:67], 0, v[130:131]
	s_mov_b32 m0, s74
	s_nop 0
	global_load_lds_dwordx4 v[218:219], off
	s_waitcnt vmcnt(8)
	s_waitcnt lgkmcnt(0)
	s_barrier
	s_waitcnt lgkmcnt(0)
	v_mfma_f32_16x16x32_bf16 v[124:127], v[138:141], v[180:183], v[124:127]
	v_mfma_f32_16x16x32_bf16 v[120:123], v[146:149], v[180:183], v[120:123]
	v_mfma_f32_16x16x32_bf16 v[108:111], v[138:141], v[188:191], v[108:111]
	v_mfma_f32_16x16x32_bf16 v[104:107], v[146:149], v[188:191], v[104:107]
	v_mfma_f32_16x16x32_bf16 v[92:95], v[138:141], v[196:199], v[92:95]
	v_mfma_f32_16x16x32_bf16 v[88:91], v[146:149], v[196:199], v[88:91]
	v_mfma_f32_16x16x32_bf16 v[76:79], v[138:141], v[204:207], v[76:79]
	v_mfma_f32_16x16x32_bf16 v[72:75], v[146:149], v[204:207], v[72:75]
	v_mfma_f32_16x16x32_bf16 v[124:127], v[142:145], v[184:187], v[124:127]
	v_mfma_f32_16x16x32_bf16 v[120:123], v[150:153], v[184:187], v[120:123]
	v_mfma_f32_16x16x32_bf16 v[108:111], v[142:145], v[192:195], v[108:111]
	v_mfma_f32_16x16x32_bf16 v[104:107], v[150:153], v[192:195], v[104:107]
	v_mfma_f32_16x16x32_bf16 v[92:95], v[142:145], v[200:203], v[92:95]
	v_mfma_f32_16x16x32_bf16 v[88:91], v[150:153], v[200:203], v[88:91]
	v_mfma_f32_16x16x32_bf16 v[76:79], v[142:145], v[208:211], v[76:79]
	v_mfma_f32_16x16x32_bf16 v[72:75], v[150:153], v[208:211], v[72:75]
	v_mfma_f32_16x16x32_bf16 v[116:119], v[164:167], v[180:183], v[116:119]
	v_mfma_f32_16x16x32_bf16 v[112:115], v[172:175], v[180:183], v[112:115]
	v_mfma_f32_16x16x32_bf16 v[100:103], v[164:167], v[188:191], v[100:103]
	v_mfma_f32_16x16x32_bf16 v[96:99], v[172:175], v[188:191], v[96:99]
	v_mfma_f32_16x16x32_bf16 v[84:87], v[164:167], v[196:199], v[84:87]
	v_mfma_f32_16x16x32_bf16 v[80:83], v[172:175], v[196:199], v[80:83]
	v_mfma_f32_16x16x32_bf16 v[68:71], v[164:167], v[204:207], v[68:71]
	v_mfma_f32_16x16x32_bf16 v[64:67], v[172:175], v[204:207], v[64:67]
	v_mfma_f32_16x16x32_bf16 v[116:119], v[168:171], v[184:187], v[116:119]
	v_mfma_f32_16x16x32_bf16 v[112:115], v[176:179], v[184:187], v[112:115]
	v_mfma_f32_16x16x32_bf16 v[100:103], v[168:171], v[192:195], v[100:103]
	v_mfma_f32_16x16x32_bf16 v[96:99], v[176:179], v[192:195], v[96:99]
	v_mfma_f32_16x16x32_bf16 v[84:87], v[168:171], v[200:203], v[84:87]
	v_mfma_f32_16x16x32_bf16 v[80:83], v[176:179], v[200:203], v[80:83]
	v_mfma_f32_16x16x32_bf16 v[68:71], v[168:171], v[208:211], v[68:71]
	v_mfma_f32_16x16x32_bf16 v[64:67], v[176:179], v[208:211], v[64:67]
	s_barrier
	s_add_i32 s66, s86, s21
	v_lshl_add_u64 v[154:155], v[154:155], 0, s[48:49]
	s_mov_b32 m0, s66
	ds_read_b128 v[180:183], v162 offset:49152
	ds_read_b128 v[184:187], v162 offset:50176
	ds_read_b128 v[188:191], v162 offset:51200
	ds_read_b128 v[192:195], v162 offset:52224
	ds_read_b128 v[196:199], v162 offset:53248
	ds_read_b128 v[200:203], v162 offset:54272
	ds_read_b128 v[204:207], v162 offset:55296
	ds_read_b128 v[208:211], v162 offset:56320
	global_load_lds_dwordx4 v[154:155], off
	s_add_i32 m0, s66, 0x2000
	s_add_u32 s64, s64, 0x40080
	v_lshl_add_u64 v[154:155], v[212:213], 0, s[48:49]
	s_addc_u32 s65, s65, 0
	s_add_i32 s66, s87, s21
	global_load_lds_dwordx4 v[154:155], off
	v_lshl_add_u64 v[154:155], s[64:65], 0, v[128:129]
	s_mov_b32 m0, s66
	s_nop 0
	global_load_lds_dwordx4 v[154:155], off
	v_lshl_add_u64 v[154:155], s[64:65], 0, v[130:131]
	s_add_i32 m0, s66, 0x2000
	s_nop 0
	global_load_lds_dwordx4 v[154:155], off
	v_lshl_add_u64 v[154:155], v[214:215], 0, s[48:49]
	s_mov_b32 m0, s78
	s_nop 0
	global_load_lds_dwordx4 v[154:155], off
	v_lshl_add_u64 v[154:155], v[216:217], 0, s[48:49]
	s_mov_b32 m0, s79
	s_nop 0
	global_load_lds_dwordx4 v[154:155], off
	s_waitcnt vmcnt(8)
	s_waitcnt lgkmcnt(0)
	s_barrier
	s_waitcnt lgkmcnt(0)
	v_mfma_f32_16x16x32_bf16 v[60:63], v[138:141], v[180:183], v[60:63]
	v_mfma_f32_16x16x32_bf16 v[56:59], v[146:149], v[180:183], v[56:59]
	v_mfma_f32_16x16x32_bf16 v[44:47], v[138:141], v[188:191], v[44:47]
	v_mfma_f32_16x16x32_bf16 v[40:43], v[146:149], v[188:191], v[40:43]
	v_mfma_f32_16x16x32_bf16 v[28:31], v[138:141], v[196:199], v[28:31]
	v_mfma_f32_16x16x32_bf16 v[24:27], v[146:149], v[196:199], v[24:27]
	v_mfma_f32_16x16x32_bf16 v[12:15], v[138:141], v[204:207], v[12:15]
	v_mfma_f32_16x16x32_bf16 v[8:11], v[146:149], v[204:207], v[8:11]
	v_mfma_f32_16x16x32_bf16 v[60:63], v[142:145], v[184:187], v[60:63]
	v_mfma_f32_16x16x32_bf16 v[56:59], v[150:153], v[184:187], v[56:59]
	v_mfma_f32_16x16x32_bf16 v[44:47], v[142:145], v[192:195], v[44:47]
	v_mfma_f32_16x16x32_bf16 v[40:43], v[150:153], v[192:195], v[40:43]
	v_mfma_f32_16x16x32_bf16 v[28:31], v[142:145], v[200:203], v[28:31]
	v_mfma_f32_16x16x32_bf16 v[24:27], v[150:153], v[200:203], v[24:27]
	v_mfma_f32_16x16x32_bf16 v[12:15], v[142:145], v[208:211], v[12:15]
	v_mfma_f32_16x16x32_bf16 v[8:11], v[150:153], v[208:211], v[8:11]
	v_mfma_f32_16x16x32_bf16 v[52:55], v[164:167], v[180:183], v[52:55]
	v_mfma_f32_16x16x32_bf16 v[48:51], v[172:175], v[180:183], v[48:51]
	v_mfma_f32_16x16x32_bf16 v[36:39], v[164:167], v[188:191], v[36:39]
	v_mfma_f32_16x16x32_bf16 v[32:35], v[172:175], v[188:191], v[32:35]
	v_mfma_f32_16x16x32_bf16 v[20:23], v[164:167], v[196:199], v[20:23]
	v_mfma_f32_16x16x32_bf16 v[16:19], v[172:175], v[196:199], v[16:19]
	v_mfma_f32_16x16x32_bf16 v[4:7], v[164:167], v[204:207], v[4:7]
	v_mfma_f32_16x16x32_bf16 v[0:3], v[172:175], v[204:207], v[0:3]
	v_mfma_f32_16x16x32_bf16 v[52:55], v[168:171], v[184:187], v[52:55]
	v_mfma_f32_16x16x32_bf16 v[48:51], v[176:179], v[184:187], v[48:51]
	v_mfma_f32_16x16x32_bf16 v[36:39], v[168:171], v[192:195], v[36:39]
	v_mfma_f32_16x16x32_bf16 v[32:35], v[176:179], v[192:195], v[32:35]
	v_mfma_f32_16x16x32_bf16 v[20:23], v[168:171], v[200:203], v[20:23]
	v_mfma_f32_16x16x32_bf16 v[16:19], v[176:179], v[200:203], v[16:19]
	v_mfma_f32_16x16x32_bf16 v[4:7], v[168:171], v[208:211], v[4:7]
	v_mfma_f32_16x16x32_bf16 v[0:3], v[176:179], v[208:211], v[0:3]
	s_barrier
	s_add_i32 s83, s83, 2
	s_add_u32 s38, s38, 0x100
	s_addc_u32 s39, s39, 0
	s_add_u32 s57, s57, 0x100
	s_addc_u32 s59, s59, 0
	s_cmp_gt_u32 s83, 13
	s_cbranch_scc0 .LBB0_482
	s_and_b64 vcc, exec, s[50:51]
	s_cbranch_vccz .LBB0_485
	s_barrier

.LBB0_669:
	s_or_b64 exec, exec, s[0:1]
	s_mov_b64 s[0:1], s[62:63]
	s_mov_b64 s[8:9], s[60:61]
	s_waitcnt lgkmcnt(0)
	s_barrier
	s_setprio 0
	v_readlane_b32 s98, v245, 4
	v_readlane_b32 s99, v245, 5
	s_mov_b32 s100, 0x66666667
	v_mov_b32_e32 v21, 0x280
	v_mov_b32_e32 v22, 0x201
	v_mov_b32_e32 v23, 0xffffff00
	v_mov_b32_e32 v24, 0x100
	v_add_u32_e32 v1, 0, v220
	v_mul_hi_u32 v2, v1, s100
	v_lshrrev_b32_e32 v2, 8, v2
	v_sub_u32_e32 v3, 0x240, v1
	v_mad_i32_i24 v3, v2, v21, v3
	v_med3_i32 v3, v3, v23, v24
	v_mad_i32_i24 v3, v2, v22, v3
	v_add_u32_e32 v3, 0x100, v3
	v_lshlrev_b32_e32 v3, 2, v3
	global_load_dword v5, v3, s[98:99]
	v_add_u32_e32 v1, 512, v220
	v_mul_hi_u32 v2, v1, s100
	v_lshrrev_b32_e32 v2, 8, v2
	v_sub_u32_e32 v3, 0x240, v1
	v_mad_i32_i24 v3, v2, v21, v3
	v_med3_i32 v3, v3, v23, v24
	v_mad_i32_i24 v3, v2, v22, v3
	v_add_u32_e32 v3, 0x100, v3
	v_lshlrev_b32_e32 v3, 2, v3
	global_load_dword v6, v3, s[98:99]
	v_add_u32_e32 v1, 1024, v220
	v_mul_hi_u32 v2, v1, s100
	v_lshrrev_b32_e32 v2, 8, v2
	v_sub_u32_e32 v3, 0x240, v1
	v_mad_i32_i24 v3, v2, v21, v3
	v_med3_i32 v3, v3, v23, v24
	v_mad_i32_i24 v3, v2, v22, v3
	v_add_u32_e32 v3, 0x100, v3
	v_lshlrev_b32_e32 v3, 2, v3
	global_load_dword v7, v3, s[98:99]
	v_add_u32_e32 v1, 1536, v220
	v_mul_hi_u32 v2, v1, s100
	v_lshrrev_b32_e32 v2, 8, v2
	v_sub_u32_e32 v3, 0x240, v1
	v_mad_i32_i24 v3, v2, v21, v3
	v_med3_i32 v3, v3, v23, v24
	v_mad_i32_i24 v3, v2, v22, v3
	v_add_u32_e32 v3, 0x100, v3
	v_lshlrev_b32_e32 v3, 2, v3
	global_load_dword v8, v3, s[98:99]
	v_add_u32_e32 v1, 2048, v220
	v_mul_hi_u32 v2, v1, s100
	v_lshrrev_b32_e32 v2, 8, v2
	v_sub_u32_e32 v3, 0x240, v1
	v_mad_i32_i24 v3, v2, v21, v3
	v_med3_i32 v3, v3, v23, v24
	v_mad_i32_i24 v3, v2, v22, v3
	v_add_u32_e32 v3, 0x100, v3
	v_lshlrev_b32_e32 v3, 2, v3
	global_load_dword v9, v3, s[98:99]
	v_add_u32_e32 v1, 2560, v220
	v_mul_hi_u32 v2, v1, s100
	v_lshrrev_b32_e32 v2, 8, v2
	v_sub_u32_e32 v3, 0x240, v1
	v_mad_i32_i24 v3, v2, v21, v3
	v_med3_i32 v3, v3, v23, v24
	v_mad_i32_i24 v3, v2, v22, v3
	v_add_u32_e32 v3, 0x100, v3
	v_lshlrev_b32_e32 v3, 2, v3
	global_load_dword v10, v3, s[98:99]
	v_add_u32_e32 v1, 3072, v220
	v_mul_hi_u32 v2, v1, s100
	v_lshrrev_b32_e32 v2, 8, v2
	v_sub_u32_e32 v3, 0x240, v1
	v_mad_i32_i24 v3, v2, v21, v3
	v_med3_i32 v3, v3, v23, v24
	v_mad_i32_i24 v3, v2, v22, v3
	v_add_u32_e32 v3, 0x100, v3
	v_lshlrev_b32_e32 v3, 2, v3
	global_load_dword v11, v3, s[98:99]
	v_add_u32_e32 v1, 3584, v220
	v_mul_hi_u32 v2, v1, s100
	v_lshrrev_b32_e32 v2, 8, v2
	v_sub_u32_e32 v3, 0x240, v1
	v_mad_i32_i24 v3, v2, v21, v3
	v_med3_i32 v3, v3, v23, v24
	v_mad_i32_i24 v3, v2, v22, v3
	v_add_u32_e32 v3, 0x100, v3
	v_lshlrev_b32_e32 v3, 2, v3
	global_load_dword v12, v3, s[98:99]
	v_add_u32_e32 v1, 4096, v220
	v_mul_hi_u32 v2, v1, s100
	v_lshrrev_b32_e32 v2, 8, v2
	v_sub_u32_e32 v3, 0x240, v1
	v_mad_i32_i24 v3, v2, v21, v3
	v_med3_i32 v3, v3, v23, v24
	v_mad_i32_i24 v3, v2, v22, v3
	v_add_u32_e32 v3, 0x100, v3
	v_lshlrev_b32_e32 v3, 2, v3
	global_load_dword v13, v3, s[98:99]
	v_add_u32_e32 v1, 4608, v220
	v_mul_hi_u32 v2, v1, s100
	v_lshrrev_b32_e32 v2, 8, v2
	v_sub_u32_e32 v3, 0x240, v1
	v_mad_i32_i24 v3, v2, v21, v3
	v_med3_i32 v3, v3, v23, v24
	v_mad_i32_i24 v3, v2, v22, v3
	v_add_u32_e32 v3, 0x100, v3
	v_lshlrev_b32_e32 v3, 2, v3
	global_load_dword v14, v3, s[98:99]
	v_lshlrev_b32_e32 v4, 2, v220
	s_waitcnt vmcnt(0)
	v_mul_f32_e32 v5, 0x3fb8aa3b, v5
	ds_write_b32 v4, v5
	v_mul_f32_e32 v6, 0x3fb8aa3b, v6
	ds_write_b32 v4, v6 offset:2048
	v_mul_f32_e32 v7, 0x3fb8aa3b, v7
	ds_write_b32 v4, v7 offset:4096
	v_mul_f32_e32 v8, 0x3fb8aa3b, v8
	ds_write_b32 v4, v8 offset:6144
	v_mul_f32_e32 v9, 0x3fb8aa3b, v9
	ds_write_b32 v4, v9 offset:8192
	v_mul_f32_e32 v10, 0x3fb8aa3b, v10
	ds_write_b32 v4, v10 offset:10240
	v_mul_f32_e32 v11, 0x3fb8aa3b, v11
	ds_write_b32 v4, v11 offset:12288
	v_mul_f32_e32 v12, 0x3fb8aa3b, v12
	ds_write_b32 v4, v12 offset:14336
	v_mul_f32_e32 v13, 0x3fb8aa3b, v13
	ds_write_b32 v4, v13 offset:16384
	v_mul_f32_e32 v14, 0x3fb8aa3b, v14
	ds_write_b32 v4, v14 offset:18432
	v_mov_b32_e32 v2, v220
	s_movk_i32 s8, 0
	s_nop 0
	v_readfirstlane_b32 s20, v2
	v_cmp_gt_i32_e32 vcc, s8, v2
	s_and_saveexec_b64 s[8:9], vcc
	v_readlane_b32 s68, v245, 0
	s_mov_b64 s[16:17], s[84:85]
	v_readlane_b32 s69, v245, 1
	v_readlane_b32 s70, v245, 2
	v_readlane_b32 s71, v245, 3
	v_readlane_b32 s72, v245, 4
	v_readlane_b32 s73, v245, 5
	v_readlane_b32 s74, v245, 6
	v_readlane_b32 s75, v245, 7
	v_readlane_b32 s76, v245, 8
	v_readlane_b32 s77, v245, 9
	v_readlane_b32 s78, v245, 10
	v_readlane_b32 s79, v245, 11
	v_readlane_b32 s80, v245, 12
	v_readlane_b32 s81, v245, 13
	v_readlane_b32 s82, v245, 14
	v_readlane_b32 s83, v245, 15
	s_cbranch_execz .LBB0_681
	v_max_i32_e32 v0, 0x1200, v2
	v_sub_u32_e32 v0, v0, v2
	s_movk_i32 s10, 0x1ff
	v_add_u32_e32 v1, 0x1ff, v0
	v_cmp_lt_u32_e32 vcc, s10, v1
	s_mov_b64 s[38:39], -1
	v_mov_b32_e32 v0, v2
	s_and_saveexec_b64 s[10:11], vcc
	s_cbranch_execz .LBB0_678
	v_lshrrev_b32_e32 v4, 9, v1
	v_add_u32_e32 v3, 0x200, v2
	v_add_u32_e32 v5, -1, v4
	v_cmp_lt_u32_e32 vcc, 1, v5
	v_mov_b32_e32 v6, 0
	v_mov_b64_e32 v[0:1], v[2:3]
	s_and_saveexec_b64 s[38:39], vcc
	s_cbranch_execz .LBB0_675
	v_lshrrev_b32_e32 v0, 1, v5
	v_readlane_b32 s68, v245, 0
	v_add_u32_e32 v0, 1, v0
	v_readlane_b32 s72, v245, 4
	v_readlane_b32 s73, v245, 5
	v_and_b32_e32 v6, -2, v0
	s_mov_b32 s21, 0
	v_lshl_add_u32 v7, v2, 2, 0
	s_mov_b64 s[40:41], 0
	s_mov_b32 s22, 0x66666667
	s_movk_i32 s23, 0x280
	s_movk_i32 s33, 0xff00
	v_mov_b32_e32 v8, 0x100
	s_movk_i32 s43, 0x201
	s_mov_b32 s42, 0x3fb8aa3b
	v_mov_b64_e32 v[0:1], v[2:3]
	s_mov_b64 s[48:49], s[72:73]
	v_readlane_b32 s69, v245, 1
	v_readlane_b32 s70, v245, 2
	v_readlane_b32 s71, v245, 3
	v_readlane_b32 s74, v245, 6
	v_readlane_b32 s75, v245, 7
	v_readlane_b32 s76, v245, 8
	v_readlane_b32 s77, v245, 9
	v_readlane_b32 s78, v245, 10
	v_readlane_b32 s79, v245, 11
	v_readlane_b32 s80, v245, 12
	v_readlane_b32 s81, v245, 13
	v_readlane_b32 s82, v245, 14
	v_readlane_b32 s83, v245, 15

.LBB0_911:
	s_or_b64 exec, exec, s[0:1]
	s_cmpk_lt_i32 s2, 0x200
	s_mov_b64 s[8:9], s[66:67]
	s_waitcnt lgkmcnt(0)
	s_barrier
	s_cselect_b32 s99, 1, 0
	v_readfirstlane_b32 s98, v220
	s_lshr_b32 s98, s98, 8
	s_cmp_lg_u32 s98, 0
	s_cbranch_scc0 .Lprio_skip1
	s_setprio 1
.Lprio_skip1:
	s_cmp_lg_u32 s99, 0
	s_cselect_b64 s[42:43], -1, 0
	s_mov_b64 s[0:1], s[64:65]
	s_add_u32 s10, s8, 0x800000
	v_mov_b32_e32 v14, v220
	s_addc_u32 s11, s9, 0
	s_and_b64 vcc, exec, s[42:43]
	v_readfirstlane_b32 s38, v14
	s_cbranch_vccz .LBB0_931
	v_lshlrev_b32_e32 v0, 4, v14
	v_add_u32_e32 v1, 0x2000, v0
	v_ashrrev_i32_e32 v2, 31, v1
	v_lshrrev_b32_e32 v2, 22, v2
	v_add_u32_e32 v2, v1, v2
	v_ashrrev_i32_e32 v8, 10, v2
	v_mul_i32_i24_e32 v2, 0x400, v8
	v_sub_u32_e32 v1, v1, v2
	v_lshrrev_b32_e32 v2, 4, v1
	v_bitop3_b32 v1, v2, v1, 32 bitop3:0x6c
	v_ashrrev_i32_e32 v2, 31, v1
	v_lshrrev_b32_e32 v2, 26, v2
	v_add_u32_e32 v2, v1, v2
	v_lshlrev_b32_e32 v3, 3, v8
	v_ashrrev_i32_e32 v9, 6, v2
	v_and_b32_e32 v3, -16, v3
	v_add_u32_e32 v3, v9, v3
	v_and_b32_e32 v4, 3, v9
	s_mov_b32 s0, 0x1fffe0
	v_lshrrev_b32_e32 v5, 2, v3
	v_lshlrev_b32_e32 v6, 1, v3
	v_and_b32_e32 v2, 0xc0, v2
	v_and_or_b32 v4, v3, s0, v4
	v_and_b32_e32 v5, 4, v5
	v_and_b32_e32 v6, 24, v6
	v_sub_u32_e32 v1, v1, v2
	v_mov_b32_e32 v2, 1
	v_or3_b32 v4, v4, v5, v6
	v_lshlrev_b32_e32 v5, 5, v8
	v_ashrrev_i16_sdwa v1, v2, sext(v1) dst_sel:DWORD dst_unused:UNUSED_PAD src0_sel:DWORD src1_sel:BYTE_0
	v_and_b32_e32 v5, 32, v5
	v_bfe_i32 v10, v1, 0, 16
	v_add_lshl_u32 v1, v5, v10, 1
	v_lshl_add_u32 v128, v4, 11, v1
	s_waitcnt vmcnt(15)
	v_lshl_add_u32 v130, v3, 11, v1
	v_bfe_i32 v1, v14, 27, 1
	v_lshrrev_b32_e32 v1, 22, v1
	v_add_u32_e32 v1, v0, v1
	v_and_b32_e32 v1, 0xfffffc00, v1
	v_sub_u32_e32 v0, v0, v1
	v_lshrrev_b32_e32 v1, 4, v0
	v_ashrrev_i32_e32 v3, 31, v14
	v_bitop3_b32 v0, v1, v0, 32 bitop3:0x6c
	v_lshrrev_b32_e32 v3, 26, v3
	v_ashrrev_i32_e32 v1, 31, v0
	v_add_u32_e32 v3, v14, v3
	v_lshrrev_b32_e32 v1, 26, v1
	v_ashrrev_i32_e32 v12, 6, v3
	v_add_u32_e32 v1, v0, v1
	v_lshlrev_b32_e32 v3, 3, v12
	v_ashrrev_i32_e32 v11, 6, v1
	v_and_b32_e32 v3, -16, v3
	s_add_u32 s20, s8, 0x7700000
	v_add_u32_e32 v3, v11, v3
	v_and_b32_e32 v4, 3, v11
	s_addc_u32 s21, s9, 0
	v_and_or_b32 v4, v3, s0, v4
	s_lshr_b32 s0, s3, 29
	s_add_i32 s0, s2, s0
	s_and_b32 s1, s0, -8
	s_ashr_i32 s39, s38, 6
	s_sub_i32 s1, s2, s1
	s_ashr_i32 s44, s38, 8
	s_lshl_b32 s22, s39, 10
	s_lshl_b32 s15, s1, 6
	s_ashr_i32 s0, s0, 3
	s_mul_i32 s14, s1, 0x41
	s_cmp_lt_i32 s1, 0
	s_cselect_b32 s1, s14, s15
	s_add_i32 s0, s1, s0
	s_ashr_i32 s1, s0, 31
	s_lshr_b32 s1, s1, 27
	s_add_i32 s1, s0, s1
	s_ashr_i32 s14, s1, 5
	s_andn2_b32 s1, s1, 31
	s_sub_i32 s1, s0, s1
	s_bfe_i32 s0, s1, 0x80000
	s_bfe_u32 s0, s0, 0x3000c
	s_add_i32 s15, s1, s0
	s_bfe_i32 s0, s15, 0x80000
	s_and_b32 s15, s15, 0xf8
	s_sub_i32 s1, s1, s15
	s_lshl_b32 s14, s14, 3
	s_sext_i32_i16 s0, s0
	s_sext_i32_i8 s1, s1
	v_lshrrev_b32_e32 v5, 2, v3
	v_lshlrev_b32_e32 v6, 1, v3
	v_and_b32_e32 v1, 0xc0, v1
	s_lshr_b32 s0, s0, 3
	s_add_i32 s48, s14, s1
	v_and_b32_e32 v5, 4, v5
	v_and_b32_e32 v6, 24, v6
	v_sub_u32_e32 v0, v0, v1
	s_ashr_i32 s49, s48, 31
	s_bfe_i64 s[40:41], s[0:1], 0x100000
	v_or3_b32 v4, v4, v5, v6
	v_lshlrev_b32_e32 v5, 5, v12
	v_ashrrev_i16_sdwa v0, v2, sext(v0) dst_sel:DWORD dst_unused:UNUSED_PAD src0_sel:DWORD src1_sel:BYTE_0
	s_lshl_b64 s[14:15], s[48:49], 19
	s_lshl_b64 s[40:41], s[40:41], 19
	v_and_b32_e32 v5, 32, v5
	v_bfe_i32 v13, v0, 0, 16
	s_add_u32 s60, s10, s40
	v_add_lshl_u32 v0, v5, v13, 1
	s_addc_u32 s61, s11, s41
	s_add_i32 s23, s22, 0
	v_lshl_add_u32 v132, v4, 11, v0
	s_add_i32 m0, s23, 0x10000
	s_waitcnt vmcnt(14)
	v_lshl_add_u32 v134, v3, 11, v0
	global_load_lds_dwordx4 v132, s[60:61]
	s_add_i32 m0, s23, 0x12000
	s_add_u32 s40, s60, 0x40000
	global_load_lds_dwordx4 v128, s[60:61]
	s_addc_u32 s41, s61, 0
	s_add_i32 m0, s23, 0x14000
	v_mov_b32_e32 v133, 0
	global_load_lds_dwordx4 v132, s[40:41]
	s_add_i32 m0, s23, 0x16000
	s_add_u32 s58, s20, s14
	s_addc_u32 s59, s21, s15
	s_add_i32 s33, s23, 0x2000
	global_load_lds_dwordx4 v128, s[40:41]
	s_mov_b32 m0, s23
	s_add_u32 s14, s58, 0x40000
	global_load_lds_dwordx4 v134, s[58:59]
	s_mov_b32 m0, s33
	s_addc_u32 s15, s59, 0
	s_add_i32 s64, s23, 0x4000
	global_load_lds_dwordx4 v130, s[58:59]
	s_mov_b32 m0, s64
	s_add_i32 s65, s23, 0x6000
	global_load_lds_dwordx4 v134, s[14:15]
	s_mov_b32 m0, s65
	v_mov_b32_e32 v129, v133
	global_load_lds_dwordx4 v130, s[14:15]
	v_mov_b32_e32 v135, v133
	v_mov_b32_e32 v131, v133
	s_cmp_eq_u32 s44, 1
	s_mov_b32 s1, 0
	v_lshl_add_u64 v[6:7], s[60:61], 0, v[132:133]
	v_lshl_add_u64 v[4:5], s[60:61], 0, v[128:129]
	v_lshl_add_u64 v[0:1], s[58:59], 0, v[134:135]
	s_cselect_b64 s[14:15], -1, 0
	s_cmp_lg_u32 s44, 1
	v_lshl_add_u64 v[2:3], s[58:59], 0, v[130:131]
	s_cbranch_scc1 .LBB0_914
	s_barrier

.LBB0_924:
	ds_read_b128 v[150:153], v147
	ds_read_b128 v[154:157], v147 offset:1024
	ds_read_b128 v[158:161], v147 offset:2048
	ds_read_b128 v[162:165], v147 offset:3072
	ds_read_b128 v[166:169], v148
	ds_read_b128 v[170:173], v148 offset:1024
	ds_read_b128 v[174:177], v148 offset:2048
	ds_read_b128 v[178:181], v148 offset:3072
	s_add_u32 s60, s58, 0xfffc0080
	s_addc_u32 s61, s59, -1
	s_cmp_eq_u32 s76, 12
	s_cselect_b32 s63, s53, s61
	s_cselect_b32 s62, s72, s60
	s_cselect_b32 s61, s51, s75
	s_cselect_b32 s60, s73, s74
	v_lshl_add_u64 v[214:215], s[58:59], 0, v[136:137]
	s_add_i32 m0, s23, 0xc000
	ds_read_b128 v[182:185], v149
	ds_read_b128 v[186:189], v149 offset:1024
	ds_read_b128 v[190:193], v149 offset:2048
	ds_read_b128 v[194:197], v149 offset:3072
	ds_read_b128 v[198:201], v149 offset:4096
	ds_read_b128 v[202:205], v149 offset:5120
	ds_read_b128 v[206:209], v149 offset:6144
	ds_read_b128 v[210:213], v149 offset:7168
	global_load_lds_dwordx4 v[214:215], off
	v_lshl_add_u64 v[214:215], s[58:59], 0, v[138:139]
	s_add_i32 m0, s23, 0xe000
	s_nop 0
	global_load_lds_dwordx4 v[214:215], off
	s_waitcnt vmcnt(8)
	s_waitcnt lgkmcnt(0)
	s_barrier
	s_waitcnt lgkmcnt(0)
	v_mfma_f32_16x16x32_bf16 v[124:127], v[150:153], v[182:185], v[124:127]
	v_mfma_f32_16x16x32_bf16 v[120:123], v[158:161], v[182:185], v[120:123]
	v_mfma_f32_16x16x32_bf16 v[116:119], v[150:153], v[190:193], v[116:119]
	v_mfma_f32_16x16x32_bf16 v[108:111], v[158:161], v[190:193], v[108:111]
	v_mfma_f32_16x16x32_bf16 v[100:103], v[150:153], v[198:201], v[100:103]
	v_mfma_f32_16x16x32_bf16 v[92:95], v[158:161], v[198:201], v[92:95]
	v_mfma_f32_16x16x32_bf16 v[84:87], v[150:153], v[206:209], v[84:87]
	v_mfma_f32_16x16x32_bf16 v[76:79], v[158:161], v[206:209], v[76:79]
	v_mfma_f32_16x16x32_bf16 v[124:127], v[154:157], v[186:189], v[124:127]
	v_mfma_f32_16x16x32_bf16 v[120:123], v[162:165], v[186:189], v[120:123]
	v_mfma_f32_16x16x32_bf16 v[116:119], v[154:157], v[194:197], v[116:119]
	v_mfma_f32_16x16x32_bf16 v[108:111], v[162:165], v[194:197], v[108:111]
	v_mfma_f32_16x16x32_bf16 v[100:103], v[154:157], v[202:205], v[100:103]
	v_mfma_f32_16x16x32_bf16 v[92:95], v[162:165], v[202:205], v[92:95]
	v_mfma_f32_16x16x32_bf16 v[84:87], v[154:157], v[210:213], v[84:87]
	v_mfma_f32_16x16x32_bf16 v[76:79], v[162:165], v[210:213], v[76:79]
	v_mfma_f32_16x16x32_bf16 v[112:115], v[166:169], v[182:185], v[112:115]
	v_mfma_f32_16x16x32_bf16 v[104:107], v[174:177], v[182:185], v[104:107]
	v_mfma_f32_16x16x32_bf16 v[96:99], v[166:169], v[190:193], v[96:99]
	v_mfma_f32_16x16x32_bf16 v[88:91], v[174:177], v[190:193], v[88:91]
	v_mfma_f32_16x16x32_bf16 v[80:83], v[166:169], v[198:201], v[80:83]
	v_mfma_f32_16x16x32_bf16 v[72:75], v[174:177], v[198:201], v[72:75]
	v_mfma_f32_16x16x32_bf16 v[68:71], v[166:169], v[206:209], v[68:71]
	v_mfma_f32_16x16x32_bf16 v[64:67], v[174:177], v[206:209], v[64:67]
	v_mfma_f32_16x16x32_bf16 v[112:115], v[170:173], v[186:189], v[112:115]
	v_mfma_f32_16x16x32_bf16 v[104:107], v[178:181], v[186:189], v[104:107]
	v_mfma_f32_16x16x32_bf16 v[96:99], v[170:173], v[194:197], v[96:99]
	v_mfma_f32_16x16x32_bf16 v[88:91], v[178:181], v[194:197], v[88:91]
	v_mfma_f32_16x16x32_bf16 v[80:83], v[170:173], v[202:205], v[80:83]
	v_mfma_f32_16x16x32_bf16 v[72:75], v[178:181], v[202:205], v[72:75]
	v_mfma_f32_16x16x32_bf16 v[68:71], v[170:173], v[210:213], v[68:71]
	v_mfma_f32_16x16x32_bf16 v[64:67], v[178:181], v[210:213], v[64:67]
	s_barrier
	s_add_i32 s77, s69, s22
	v_lshl_add_u64 v[214:215], s[60:61], 0, v[132:133]
	s_mov_b32 m0, s77
	ds_read_b128 v[182:185], v149 offset:16384
	ds_read_b128 v[186:189], v149 offset:17408
	ds_read_b128 v[190:193], v149 offset:18432
	ds_read_b128 v[194:197], v149 offset:19456
	ds_read_b128 v[198:201], v149 offset:20480
	ds_read_b128 v[202:205], v149 offset:21504
	ds_read_b128 v[206:209], v149 offset:22528
	ds_read_b128 v[210:213], v149 offset:23552
	global_load_lds_dwordx4 v[214:215], off
	s_add_i32 m0, s77, 0x2000
	s_add_u32 s78, s60, 0x40000
	v_lshl_add_u64 v[216:217], s[60:61], 0, v[128:129]
	s_addc_u32 s79, s61, 0
	s_add_i32 s77, s70, s22
	global_load_lds_dwordx4 v[216:217], off
	v_lshl_add_u64 v[218:219], s[78:79], 0, v[132:133]
	s_mov_b32 m0, s77
	v_lshl_add_u64 v[222:223], s[62:63], 0, v[130:131]
	global_load_lds_dwordx4 v[218:219], off
	v_lshl_add_u64 v[218:219], s[78:79], 0, v[128:129]
	s_add_i32 m0, s77, 0x2000
	s_nop 0
	global_load_lds_dwordx4 v[218:219], off
	v_lshl_add_u64 v[218:219], s[62:63], 0, v[134:135]
	s_mov_b32 m0, s23
	s_nop 0
	global_load_lds_dwordx4 v[218:219], off
	s_mov_b32 m0, s33
	s_nop 0
	global_load_lds_dwordx4 v[222:223], off
	s_waitcnt vmcnt(8)
	s_waitcnt lgkmcnt(0)
	s_barrier
	s_waitcnt lgkmcnt(0)
	v_mfma_f32_16x16x32_bf16 v[60:63], v[150:153], v[182:185], v[60:63]
	v_mfma_f32_16x16x32_bf16 v[56:59], v[158:161], v[182:185], v[56:59]
	v_mfma_f32_16x16x32_bf16 v[52:55], v[150:153], v[190:193], v[52:55]
	v_mfma_f32_16x16x32_bf16 v[44:47], v[158:161], v[190:193], v[44:47]
	v_mfma_f32_16x16x32_bf16 v[36:39], v[150:153], v[198:201], v[36:39]
	v_mfma_f32_16x16x32_bf16 v[28:31], v[158:161], v[198:201], v[28:31]
	v_mfma_f32_16x16x32_bf16 v[20:23], v[150:153], v[206:209], v[20:23]
	v_mfma_f32_16x16x32_bf16 v[12:15], v[158:161], v[206:209], v[12:15]
	v_mfma_f32_16x16x32_bf16 v[60:63], v[154:157], v[186:189], v[60:63]
	v_mfma_f32_16x16x32_bf16 v[56:59], v[162:165], v[186:189], v[56:59]
	v_mfma_f32_16x16x32_bf16 v[52:55], v[154:157], v[194:197], v[52:55]
	v_mfma_f32_16x16x32_bf16 v[44:47], v[162:165], v[194:197], v[44:47]
	v_mfma_f32_16x16x32_bf16 v[36:39], v[154:157], v[202:205], v[36:39]
	v_mfma_f32_16x16x32_bf16 v[28:31], v[162:165], v[202:205], v[28:31]
	v_mfma_f32_16x16x32_bf16 v[20:23], v[154:157], v[210:213], v[20:23]
	v_mfma_f32_16x16x32_bf16 v[12:15], v[162:165], v[210:213], v[12:15]
	v_mfma_f32_16x16x32_bf16 v[48:51], v[166:169], v[182:185], v[48:51]
	v_mfma_f32_16x16x32_bf16 v[40:43], v[174:177], v[182:185], v[40:43]
	v_mfma_f32_16x16x32_bf16 v[32:35], v[166:169], v[190:193], v[32:35]
	v_mfma_f32_16x16x32_bf16 v[24:27], v[174:177], v[190:193], v[24:27]
	v_mfma_f32_16x16x32_bf16 v[16:19], v[166:169], v[198:201], v[16:19]
	v_mfma_f32_16x16x32_bf16 v[8:11], v[174:177], v[198:201], v[8:11]
	v_mfma_f32_16x16x32_bf16 v[4:7], v[166:169], v[206:209], v[4:7]
	v_mfma_f32_16x16x32_bf16 v[0:3], v[174:177], v[206:209], v[0:3]
	v_mfma_f32_16x16x32_bf16 v[48:51], v[170:173], v[186:189], v[48:51]
	v_mfma_f32_16x16x32_bf16 v[40:43], v[178:181], v[186:189], v[40:43]
	v_mfma_f32_16x16x32_bf16 v[32:35], v[170:173], v[194:197], v[32:35]
	v_mfma_f32_16x16x32_bf16 v[24:27], v[178:181], v[194:197], v[24:27]
	v_mfma_f32_16x16x32_bf16 v[16:19], v[170:173], v[202:205], v[16:19]
	v_mfma_f32_16x16x32_bf16 v[8:11], v[178:181], v[202:205], v[8:11]
	v_mfma_f32_16x16x32_bf16 v[4:7], v[170:173], v[210:213], v[4:7]
	v_mfma_f32_16x16x32_bf16 v[0:3], v[178:181], v[210:213], v[0:3]
	s_barrier
	s_add_i32 s77, 0, 0x18000
	s_add_i32 s78, 0, 0x1c000
	v_add_u32_e32 v162, s77, v146
	v_add_u32_e32 v178, s78, v146
	ds_read_b128 v[150:153], v162
	ds_read_b128 v[154:157], v162 offset:1024
	ds_read_b128 v[158:161], v162 offset:2048
	ds_read_b128 v[162:165], v162 offset:3072
	ds_read_b128 v[166:169], v178
	ds_read_b128 v[170:173], v178 offset:1024
	ds_read_b128 v[174:177], v178 offset:2048
	ds_read_b128 v[178:181], v178 offset:3072
	s_add_u32 s62, s62, 0x40000
	s_addc_u32 s63, s63, 0
	s_mov_b32 m0, s64
	v_lshl_add_u64 v[224:225], s[62:63], 0, v[134:135]
	ds_read_b128 v[182:185], v149 offset:32768
	ds_read_b128 v[186:189], v149 offset:33792
	ds_read_b128 v[190:193], v149 offset:34816
	ds_read_b128 v[194:197], v149 offset:35840
	ds_read_b128 v[198:201], v149 offset:36864
	ds_read_b128 v[202:205], v149 offset:37888
	ds_read_b128 v[206:209], v149 offset:38912
	ds_read_b128 v[210:213], v149 offset:39936
	global_load_lds_dwordx4 v[224:225], off
	v_lshl_add_u64 v[224:225], s[62:63], 0, v[130:131]
	s_mov_b32 m0, s65
	s_nop 0
	global_load_lds_dwordx4 v[224:225], off
	s_waitcnt vmcnt(8)
	s_waitcnt lgkmcnt(0)
	s_barrier
	s_waitcnt lgkmcnt(0)
	v_mfma_f32_16x16x32_bf16 v[124:127], v[150:153], v[182:185], v[124:127]
	v_mfma_f32_16x16x32_bf16 v[120:123], v[158:161], v[182:185], v[120:123]
	v_mfma_f32_16x16x32_bf16 v[116:119], v[150:153], v[190:193], v[116:119]
	v_mfma_f32_16x16x32_bf16 v[108:111], v[158:161], v[190:193], v[108:111]
	v_mfma_f32_16x16x32_bf16 v[100:103], v[150:153], v[198:201], v[100:103]
	v_mfma_f32_16x16x32_bf16 v[92:95], v[158:161], v[198:201], v[92:95]
	v_mfma_f32_16x16x32_bf16 v[84:87], v[150:153], v[206:209], v[84:87]
	v_mfma_f32_16x16x32_bf16 v[76:79], v[158:161], v[206:209], v[76:79]
	v_mfma_f32_16x16x32_bf16 v[124:127], v[154:157], v[186:189], v[124:127]
	v_mfma_f32_16x16x32_bf16 v[120:123], v[162:165], v[186:189], v[120:123]
	v_mfma_f32_16x16x32_bf16 v[116:119], v[154:157], v[194:197], v[116:119]
	v_mfma_f32_16x16x32_bf16 v[108:111], v[162:165], v[194:197], v[108:111]
	v_mfma_f32_16x16x32_bf16 v[100:103], v[154:157], v[202:205], v[100:103]
	v_mfma_f32_16x16x32_bf16 v[92:95], v[162:165], v[202:205], v[92:95]
	v_mfma_f32_16x16x32_bf16 v[84:87], v[154:157], v[210:213], v[84:87]
	v_mfma_f32_16x16x32_bf16 v[76:79], v[162:165], v[210:213], v[76:79]
	v_mfma_f32_16x16x32_bf16 v[112:115], v[166:169], v[182:185], v[112:115]
	v_mfma_f32_16x16x32_bf16 v[104:107], v[174:177], v[182:185], v[104:107]
	v_mfma_f32_16x16x32_bf16 v[96:99], v[166:169], v[190:193], v[96:99]
	v_mfma_f32_16x16x32_bf16 v[88:91], v[174:177], v[190:193], v[88:91]
	v_mfma_f32_16x16x32_bf16 v[80:83], v[166:169], v[198:201], v[80:83]
	v_mfma_f32_16x16x32_bf16 v[72:75], v[174:177], v[198:201], v[72:75]
	v_mfma_f32_16x16x32_bf16 v[68:71], v[166:169], v[206:209], v[68:71]
	v_mfma_f32_16x16x32_bf16 v[64:67], v[174:177], v[206:209], v[64:67]
	v_mfma_f32_16x16x32_bf16 v[112:115], v[170:173], v[186:189], v[112:115]
	v_mfma_f32_16x16x32_bf16 v[104:107], v[178:181], v[186:189], v[104:107]
	v_mfma_f32_16x16x32_bf16 v[96:99], v[170:173], v[194:197], v[96:99]
	v_mfma_f32_16x16x32_bf16 v[88:91], v[178:181], v[194:197], v[88:91]
	v_mfma_f32_16x16x32_bf16 v[80:83], v[170:173], v[202:205], v[80:83]
	v_mfma_f32_16x16x32_bf16 v[72:75], v[178:181], v[202:205], v[72:75]
	v_mfma_f32_16x16x32_bf16 v[68:71], v[170:173], v[210:213], v[68:71]
	v_mfma_f32_16x16x32_bf16 v[64:67], v[178:181], v[210:213], v[64:67]
	s_barrier
	s_add_i32 s62, s77, s22
	v_lshl_add_u64 v[214:215], v[214:215], 0, s[44:45]
	s_mov_b32 m0, s62
	ds_read_b128 v[182:185], v149 offset:49152
	ds_read_b128 v[186:189], v149 offset:50176
	ds_read_b128 v[190:193], v149 offset:51200
	ds_read_b128 v[194:197], v149 offset:52224
	ds_read_b128 v[198:201], v149 offset:53248
	ds_read_b128 v[202:205], v149 offset:54272
	ds_read_b128 v[206:209], v149 offset:55296
	ds_read_b128 v[210:213], v149 offset:56320
	global_load_lds_dwordx4 v[214:215], off
	s_add_i32 m0, s62, 0x2000
	s_add_u32 s60, s60, 0x40080
	v_lshl_add_u64 v[214:215], v[216:217], 0, s[44:45]
	s_addc_u32 s61, s61, 0
	s_add_i32 s62, s78, s22
	global_load_lds_dwordx4 v[214:215], off
	v_lshl_add_u64 v[214:215], s[60:61], 0, v[132:133]
	s_mov_b32 m0, s62
	s_nop 0
	global_load_lds_dwordx4 v[214:215], off
	v_lshl_add_u64 v[214:215], s[60:61], 0, v[128:129]
	s_add_i32 m0, s62, 0x2000
	s_nop 0
	global_load_lds_dwordx4 v[214:215], off
	v_lshl_add_u64 v[214:215], v[218:219], 0, s[44:45]
	s_mov_b32 m0, s67
	s_nop 0
	global_load_lds_dwordx4 v[214:215], off
	v_lshl_add_u64 v[214:215], v[222:223], 0, s[44:45]
	s_mov_b32 m0, s68
	s_nop 0
	global_load_lds_dwordx4 v[214:215], off
	s_waitcnt vmcnt(8)
	s_waitcnt lgkmcnt(0)
	s_barrier
	s_waitcnt lgkmcnt(0)
	v_mfma_f32_16x16x32_bf16 v[60:63], v[150:153], v[182:185], v[60:63]
	v_mfma_f32_16x16x32_bf16 v[56:59], v[158:161], v[182:185], v[56:59]
	v_mfma_f32_16x16x32_bf16 v[52:55], v[150:153], v[190:193], v[52:55]
	v_mfma_f32_16x16x32_bf16 v[44:47], v[158:161], v[190:193], v[44:47]
	v_mfma_f32_16x16x32_bf16 v[36:39], v[150:153], v[198:201], v[36:39]
	v_mfma_f32_16x16x32_bf16 v[28:31], v[158:161], v[198:201], v[28:31]
	v_mfma_f32_16x16x32_bf16 v[20:23], v[150:153], v[206:209], v[20:23]
	v_mfma_f32_16x16x32_bf16 v[12:15], v[158:161], v[206:209], v[12:15]
	v_mfma_f32_16x16x32_bf16 v[60:63], v[154:157], v[186:189], v[60:63]
	v_mfma_f32_16x16x32_bf16 v[56:59], v[162:165], v[186:189], v[56:59]
	v_mfma_f32_16x16x32_bf16 v[52:55], v[154:157], v[194:197], v[52:55]
	v_mfma_f32_16x16x32_bf16 v[44:47], v[162:165], v[194:197], v[44:47]
	v_mfma_f32_16x16x32_bf16 v[36:39], v[154:157], v[202:205], v[36:39]
	v_mfma_f32_16x16x32_bf16 v[28:31], v[162:165], v[202:205], v[28:31]
	v_mfma_f32_16x16x32_bf16 v[20:23], v[154:157], v[210:213], v[20:23]
	v_mfma_f32_16x16x32_bf16 v[12:15], v[162:165], v[210:213], v[12:15]
	v_mfma_f32_16x16x32_bf16 v[48:51], v[166:169], v[182:185], v[48:51]
	v_mfma_f32_16x16x32_bf16 v[40:43], v[174:177], v[182:185], v[40:43]
	v_mfma_f32_16x16x32_bf16 v[32:35], v[166:169], v[190:193], v[32:35]
	v_mfma_f32_16x16x32_bf16 v[24:27], v[174:177], v[190:193], v[24:27]
	v_mfma_f32_16x16x32_bf16 v[16:19], v[166:169], v[198:201], v[16:19]
	v_mfma_f32_16x16x32_bf16 v[8:11], v[174:177], v[198:201], v[8:11]
	v_mfma_f32_16x16x32_bf16 v[4:7], v[166:169], v[206:209], v[4:7]
	v_mfma_f32_16x16x32_bf16 v[0:3], v[174:177], v[206:209], v[0:3]
	v_mfma_f32_16x16x32_bf16 v[48:51], v[170:173], v[186:189], v[48:51]
	v_mfma_f32_16x16x32_bf16 v[40:43], v[178:181], v[186:189], v[40:43]
	v_mfma_f32_16x16x32_bf16 v[32:35], v[170:173], v[194:197], v[32:35]
	v_mfma_f32_16x16x32_bf16 v[24:27], v[178:181], v[194:197], v[24:27]
	v_mfma_f32_16x16x32_bf16 v[16:19], v[170:173], v[202:205], v[16:19]
	v_mfma_f32_16x16x32_bf16 v[8:11], v[178:181], v[202:205], v[8:11]
	v_mfma_f32_16x16x32_bf16 v[4:7], v[170:173], v[210:213], v[4:7]
	v_mfma_f32_16x16x32_bf16 v[0:3], v[178:181], v[210:213], v[0:3]
	s_barrier
	s_add_i32 s76, s76, 2
	s_add_u32 s58, s58, 0x100
	s_addc_u32 s59, s59, 0
	s_add_u32 s74, s74, 0x100
	s_addc_u32 s75, s75, 0
	s_cmp_gt_u32 s76, 13
	s_cbranch_scc0 .LBB0_924
	s_and_b64 vcc, exec, s[46:47]
	s_cbranch_vccz .LBB0_927
	s_barrier

.LBB0_986:
	s_or_b64 exec, exec, s[0:1]
	s_mov_b64 s[8:9], s[66:67]
	s_mov_b64 s[0:1], s[64:65]
	v_mov_b32_e32 v33, v220
	s_waitcnt lgkmcnt(0)
	s_barrier
	s_setprio 0
	v_readlane_b32 s44, v245, 0
	v_lshlrev_b32_e32 v0, 3, v33
	v_and_b32_e32 v32, 0x1f8, v0
	v_lshlrev_b32_e32 v96, 2, v32
	v_readlane_b32 s58, v245, 14
	v_readlane_b32 s59, v245, 15
	v_readlane_b32 s45, v245, 1
	v_readlane_b32 s46, v245, 2
	v_readlane_b32 s47, v245, 3
	v_readlane_b32 s48, v245, 4
	v_readlane_b32 s49, v245, 5
	global_load_dwordx4 v[0:3], v96, s[58:59]
	v_readlane_b32 s50, v245, 6
	v_readlane_b32 s51, v245, 7
	v_readlane_b32 s52, v245, 8
	v_readlane_b32 s53, v245, 9
	v_readlane_b32 s54, v245, 10
	v_readlane_b32 s55, v245, 11
	v_readlane_b32 s56, v245, 12
	v_readlane_b32 s57, v245, 13
	s_mov_b64 s[14:15], s[58:59]
	v_readlane_b32 s44, v245, 21
	v_readlane_b32 s45, v245, 22
	v_mov_b32_e32 v4, 0
	s_cmp_lg_u64 s[44:45], 0
	v_mov_b32_e32 v97, v4
	s_cselect_b64 s[0:1], -1, 0
	s_cmp_eq_u64 s[44:45], 0
	v_readfirstlane_b32 s10, v33
	v_lshl_add_u64 v[28:29], s[14:15], 0, v[96:97]
	v_lshl_add_u64 v[30:31], s[44:45], 0, v[96:97]
	v_mov_b32_e32 v8, 0
	v_mov_b32_e32 v9, v4
	v_mov_b32_e32 v10, 0
	v_mov_b32_e32 v11, v4
	v_mov_b32_e32 v12, 0
	v_mov_b32_e32 v13, v4
	v_mov_b32_e32 v14, 0
	v_mov_b32_e32 v15, v4
	v_readlane_b32 s46, v245, 23
	v_readlane_b32 s47, v245, 24
	v_readlane_b32 s48, v245, 25
	v_readlane_b32 s49, v245, 26
	v_readlane_b32 s50, v245, 27
	v_readlane_b32 s51, v245, 28
	v_readlane_b32 s52, v245, 29
	v_readlane_b32 s53, v245, 30
	v_readlane_b32 s54, v245, 31
	v_readlane_b32 s55, v245, 32
	v_readlane_b32 s56, v245, 33
	v_readlane_b32 s57, v245, 34
	v_readlane_b32 s58, v245, 35
	v_readlane_b32 s59, v245, 36
	s_cbranch_scc1 .LBB0_988
	global_load_dwordx4 v[8:11], v[30:31], off
	global_load_dwordx4 v[12:15], v[30:31], off offset:16

.LBB0_1053:
	s_or_b64 exec, exec, s[0:1]
	s_mov_b64 s[4:5], s[66:67]
	s_mov_b64 s[0:1], s[64:65]
	s_waitcnt lgkmcnt(0)
	s_barrier
	s_cselect_b32 s99, 1, 0
	v_readfirstlane_b32 s98, v220
	s_lshr_b32 s98, s98, 8
	s_cmp_lg_u32 s98, 0
	s_cbranch_scc0 .Lprio_skip2
	s_setprio 1
.Lprio_skip2:
	s_cmp_lg_u32 s99, 0
	s_waitcnt vmcnt(4)
	v_mov_b32_e32 v11, v220
	s_waitcnt vmcnt(3)
	v_cndmask_b32_e64 v0, 0, 1, s[42:43]
	v_cmp_ne_u32_e64 s[0:1], 1, v0
	s_andn2_b64 vcc, exec, s[42:43]
	v_readfirstlane_b32 s20, v11
	s_cbranch_vccnz .LBB0_1055
	s_lshr_b32 s6, s3, 29
	s_add_i32 s6, s2, s6
	s_and_b32 s7, s6, -8
	s_sub_i32 s7, s2, s7
	s_lshl_b32 s9, s7, 6
	s_ashr_i32 s6, s6, 3
	s_mul_i32 s8, s7, 0x41
	s_cmp_lt_i32 s7, 0
	s_cselect_b32 s7, s8, s9
	s_add_i32 s6, s7, s6
	s_ashr_i32 s7, s6, 31
	s_lshr_b32 s7, s7, 27
	s_add_i32 s7, s6, s7
	s_ashr_i32 s8, s7, 5
	s_andn2_b32 s7, s7, 31
	s_sub_i32 s6, s6, s7
	s_bfe_i32 s7, s6, 0x80000
	s_bfe_u32 s7, s7, 0x3000c
	s_add_i32 s7, s6, s7
	s_bfe_i32 s9, s7, 0x80000
	s_and_b32 s7, s7, 0xf8
	s_sub_i32 s6, s6, s7
	s_lshl_b32 s8, s8, 3
	s_sext_i32_i16 s9, s9
	s_sext_i32_i8 s6, s6
	s_add_i32 s60, s8, s6
	s_ashr_i32 s6, s9, 3
	s_cmp_gt_i32 s60, 63
	s_cselect_b32 s7, 4, 0
	s_add_i32 s58, s7, s6

.LBB0_1068:
	ds_read_b128 v[144:147], v151
	ds_read_b128 v[156:159], v151 offset:1024
	ds_read_b128 v[160:163], v151 offset:2048
	ds_read_b128 v[164:167], v151 offset:3072
	ds_read_b128 v[168:171], v152
	ds_read_b128 v[172:175], v152 offset:1024
	ds_read_b128 v[176:179], v152 offset:2048
	ds_read_b128 v[180:183], v152 offset:3072
	s_add_u32 s10, s8, 0xfffc0080
	s_addc_u32 s11, s9, -1
	s_cmp_eq_u32 s61, 12
	s_cselect_b32 s63, s0, s11
	s_cselect_b32 s62, s22, s10
	s_cselect_b32 s11, s23, s53
	s_cselect_b32 s10, s49, s51
	v_lshl_add_u64 v[216:217], s[8:9], 0, v[136:137]
	s_add_i32 m0, s59, 0xc000
	ds_read_b128 v[184:187], v153
	ds_read_b128 v[188:191], v153 offset:1024
	ds_read_b128 v[192:195], v153 offset:2048
	ds_read_b128 v[196:199], v153 offset:3072
	ds_read_b128 v[200:203], v153 offset:4096
	ds_read_b128 v[204:207], v153 offset:5120
	ds_read_b128 v[208:211], v153 offset:6144
	ds_read_b128 v[212:215], v153 offset:7168
	global_load_lds_dwordx4 v[216:217], off
	v_lshl_add_u64 v[216:217], s[8:9], 0, v[138:139]
	s_add_i32 m0, s59, 0xe000
	s_nop 0
	global_load_lds_dwordx4 v[216:217], off
	s_waitcnt vmcnt(8)
	s_waitcnt lgkmcnt(0)
	s_barrier
	s_waitcnt lgkmcnt(0)
	v_mfma_f32_16x16x32_bf16 v[124:127], v[144:147], v[184:187], v[124:127]
	v_mfma_f32_16x16x32_bf16 v[120:123], v[160:163], v[184:187], v[120:123]
	v_mfma_f32_16x16x32_bf16 v[108:111], v[144:147], v[192:195], v[108:111]
	v_mfma_f32_16x16x32_bf16 v[104:107], v[160:163], v[192:195], v[104:107]
	v_mfma_f32_16x16x32_bf16 v[92:95], v[144:147], v[200:203], v[92:95]
	v_mfma_f32_16x16x32_bf16 v[88:91], v[160:163], v[200:203], v[88:91]
	v_mfma_f32_16x16x32_bf16 v[76:79], v[144:147], v[208:211], v[76:79]
	v_mfma_f32_16x16x32_bf16 v[72:75], v[160:163], v[208:211], v[72:75]
	v_mfma_f32_16x16x32_bf16 v[124:127], v[156:159], v[188:191], v[124:127]
	v_mfma_f32_16x16x32_bf16 v[120:123], v[164:167], v[188:191], v[120:123]
	v_mfma_f32_16x16x32_bf16 v[108:111], v[156:159], v[196:199], v[108:111]
	v_mfma_f32_16x16x32_bf16 v[104:107], v[164:167], v[196:199], v[104:107]
	v_mfma_f32_16x16x32_bf16 v[92:95], v[156:159], v[204:207], v[92:95]
	v_mfma_f32_16x16x32_bf16 v[88:91], v[164:167], v[204:207], v[88:91]
	v_mfma_f32_16x16x32_bf16 v[76:79], v[156:159], v[212:215], v[76:79]
	v_mfma_f32_16x16x32_bf16 v[72:75], v[164:167], v[212:215], v[72:75]
	v_mfma_f32_16x16x32_bf16 v[116:119], v[168:171], v[184:187], v[116:119]
	v_mfma_f32_16x16x32_bf16 v[112:115], v[176:179], v[184:187], v[112:115]
	v_mfma_f32_16x16x32_bf16 v[100:103], v[168:171], v[192:195], v[100:103]
	v_mfma_f32_16x16x32_bf16 v[96:99], v[176:179], v[192:195], v[96:99]
	v_mfma_f32_16x16x32_bf16 v[84:87], v[168:171], v[200:203], v[84:87]
	v_mfma_f32_16x16x32_bf16 v[80:83], v[176:179], v[200:203], v[80:83]
	v_mfma_f32_16x16x32_bf16 v[68:71], v[168:171], v[208:211], v[68:71]
	v_mfma_f32_16x16x32_bf16 v[64:67], v[176:179], v[208:211], v[64:67]
	v_mfma_f32_16x16x32_bf16 v[116:119], v[172:175], v[188:191], v[116:119]
	v_mfma_f32_16x16x32_bf16 v[112:115], v[180:183], v[188:191], v[112:115]
	v_mfma_f32_16x16x32_bf16 v[100:103], v[172:175], v[196:199], v[100:103]
	v_mfma_f32_16x16x32_bf16 v[96:99], v[180:183], v[196:199], v[96:99]
	v_mfma_f32_16x16x32_bf16 v[84:87], v[172:175], v[204:207], v[84:87]
	v_mfma_f32_16x16x32_bf16 v[80:83], v[180:183], v[204:207], v[80:83]
	v_mfma_f32_16x16x32_bf16 v[68:71], v[172:175], v[212:215], v[68:71]
	v_mfma_f32_16x16x32_bf16 v[64:67], v[180:183], v[212:215], v[64:67]
	s_barrier
	s_add_i32 s80, s20, s66
	v_lshl_add_u64 v[216:217], s[10:11], 0, v[130:131]
	s_mov_b32 m0, s80
	ds_read_b128 v[184:187], v153 offset:16384
	ds_read_b128 v[188:191], v153 offset:17408
	ds_read_b128 v[192:195], v153 offset:18432
	ds_read_b128 v[196:199], v153 offset:19456
	ds_read_b128 v[200:203], v153 offset:20480
	ds_read_b128 v[204:207], v153 offset:21504
	ds_read_b128 v[208:211], v153 offset:22528
	ds_read_b128 v[212:215], v153 offset:23552
	global_load_lds_dwordx4 v[216:217], off
	s_add_i32 m0, s80, 0x2000
	s_add_u32 s80, s10, 0x40000
	v_lshl_add_u64 v[218:219], s[10:11], 0, v[134:135]
	s_addc_u32 s81, s11, 0
	s_add_i32 s82, s21, s66
	global_load_lds_dwordx4 v[218:219], off
	v_lshl_add_u64 v[222:223], s[80:81], 0, v[130:131]
	s_mov_b32 m0, s82
	v_lshl_add_u64 v[224:225], s[62:63], 0, v[132:133]
	global_load_lds_dwordx4 v[222:223], off
	v_lshl_add_u64 v[222:223], s[80:81], 0, v[134:135]
	s_add_i32 m0, s82, 0x2000
	s_nop 0
	global_load_lds_dwordx4 v[222:223], off
	v_lshl_add_u64 v[222:223], s[62:63], 0, v[128:129]
	s_mov_b32 m0, s59
	s_nop 0
	global_load_lds_dwordx4 v[222:223], off
	s_mov_b32 m0, s67
	s_nop 0
	global_load_lds_dwordx4 v[224:225], off
	s_waitcnt vmcnt(8)
	s_waitcnt lgkmcnt(0)
	s_barrier
	s_waitcnt lgkmcnt(0)
	v_mfma_f32_16x16x32_bf16 v[60:63], v[144:147], v[184:187], v[60:63]
	v_mfma_f32_16x16x32_bf16 v[56:59], v[160:163], v[184:187], v[56:59]
	v_mfma_f32_16x16x32_bf16 v[44:47], v[144:147], v[192:195], v[44:47]
	v_mfma_f32_16x16x32_bf16 v[40:43], v[160:163], v[192:195], v[40:43]
	v_mfma_f32_16x16x32_bf16 v[28:31], v[144:147], v[200:203], v[28:31]
	v_mfma_f32_16x16x32_bf16 v[24:27], v[160:163], v[200:203], v[24:27]
	v_mfma_f32_16x16x32_bf16 v[12:15], v[144:147], v[208:211], v[12:15]
	v_mfma_f32_16x16x32_bf16 v[8:11], v[160:163], v[208:211], v[8:11]
	v_mfma_f32_16x16x32_bf16 v[60:63], v[156:159], v[188:191], v[60:63]
	v_mfma_f32_16x16x32_bf16 v[56:59], v[164:167], v[188:191], v[56:59]
	v_mfma_f32_16x16x32_bf16 v[44:47], v[156:159], v[196:199], v[44:47]
	v_mfma_f32_16x16x32_bf16 v[40:43], v[164:167], v[196:199], v[40:43]
	v_mfma_f32_16x16x32_bf16 v[28:31], v[156:159], v[204:207], v[28:31]
	v_mfma_f32_16x16x32_bf16 v[24:27], v[164:167], v[204:207], v[24:27]
	v_mfma_f32_16x16x32_bf16 v[12:15], v[156:159], v[212:215], v[12:15]
	v_mfma_f32_16x16x32_bf16 v[8:11], v[164:167], v[212:215], v[8:11]
	v_mfma_f32_16x16x32_bf16 v[52:55], v[168:171], v[184:187], v[52:55]
	v_mfma_f32_16x16x32_bf16 v[48:51], v[176:179], v[184:187], v[48:51]
	v_mfma_f32_16x16x32_bf16 v[36:39], v[168:171], v[192:195], v[36:39]
	v_mfma_f32_16x16x32_bf16 v[32:35], v[176:179], v[192:195], v[32:35]
	v_mfma_f32_16x16x32_bf16 v[20:23], v[168:171], v[200:203], v[20:23]
	v_mfma_f32_16x16x32_bf16 v[16:19], v[176:179], v[200:203], v[16:19]
	v_mfma_f32_16x16x32_bf16 v[4:7], v[168:171], v[208:211], v[4:7]
	v_mfma_f32_16x16x32_bf16 v[0:3], v[176:179], v[208:211], v[0:3]
	v_mfma_f32_16x16x32_bf16 v[52:55], v[172:175], v[188:191], v[52:55]
	v_mfma_f32_16x16x32_bf16 v[48:51], v[180:183], v[188:191], v[48:51]
	v_mfma_f32_16x16x32_bf16 v[36:39], v[172:175], v[196:199], v[36:39]
	v_mfma_f32_16x16x32_bf16 v[32:35], v[180:183], v[196:199], v[32:35]
	v_mfma_f32_16x16x32_bf16 v[20:23], v[172:175], v[204:207], v[20:23]
	v_mfma_f32_16x16x32_bf16 v[16:19], v[180:183], v[204:207], v[16:19]
	v_mfma_f32_16x16x32_bf16 v[4:7], v[172:175], v[212:215], v[4:7]
	v_mfma_f32_16x16x32_bf16 v[0:3], v[180:183], v[212:215], v[0:3]
	s_barrier
	s_add_i32 s80, 0, 0x18000
	v_add_u32_e32 v155, s80, v150
	s_add_i32 s81, 0, 0x1c000
	ds_read_b128 v[144:147], v155
	ds_read_b128 v[156:159], v155 offset:1024
	ds_read_b128 v[160:163], v155 offset:2048
	ds_read_b128 v[164:167], v155 offset:3072
	v_add_u32_e32 v155, s81, v150
	ds_read_b128 v[168:171], v155
	ds_read_b128 v[172:175], v155 offset:1024
	ds_read_b128 v[176:179], v155 offset:2048
	ds_read_b128 v[180:183], v155 offset:3072
	s_add_u32 s62, s62, 0x40000
	s_addc_u32 s63, s63, 0
	s_mov_b32 m0, s68
	v_lshl_add_u64 v[226:227], s[62:63], 0, v[128:129]
	ds_read_b128 v[184:187], v153 offset:32768
	ds_read_b128 v[188:191], v153 offset:33792
	ds_read_b128 v[192:195], v153 offset:34816
	ds_read_b128 v[196:199], v153 offset:35840
	ds_read_b128 v[200:203], v153 offset:36864
	ds_read_b128 v[204:207], v153 offset:37888
	ds_read_b128 v[208:211], v153 offset:38912
	ds_read_b128 v[212:215], v153 offset:39936
	global_load_lds_dwordx4 v[226:227], off
	v_lshl_add_u64 v[226:227], s[62:63], 0, v[132:133]
	s_mov_b32 m0, s69
	s_nop 0
	global_load_lds_dwordx4 v[226:227], off
	s_waitcnt vmcnt(8)
	s_waitcnt lgkmcnt(0)
	s_barrier
	s_waitcnt lgkmcnt(0)
	v_mfma_f32_16x16x32_bf16 v[124:127], v[144:147], v[184:187], v[124:127]
	v_mfma_f32_16x16x32_bf16 v[120:123], v[160:163], v[184:187], v[120:123]
	v_mfma_f32_16x16x32_bf16 v[108:111], v[144:147], v[192:195], v[108:111]
	v_mfma_f32_16x16x32_bf16 v[104:107], v[160:163], v[192:195], v[104:107]
	v_mfma_f32_16x16x32_bf16 v[92:95], v[144:147], v[200:203], v[92:95]
	v_mfma_f32_16x16x32_bf16 v[88:91], v[160:163], v[200:203], v[88:91]
	v_mfma_f32_16x16x32_bf16 v[76:79], v[144:147], v[208:211], v[76:79]
	v_mfma_f32_16x16x32_bf16 v[72:75], v[160:163], v[208:211], v[72:75]
	v_mfma_f32_16x16x32_bf16 v[124:127], v[156:159], v[188:191], v[124:127]
	v_mfma_f32_16x16x32_bf16 v[120:123], v[164:167], v[188:191], v[120:123]
	v_mfma_f32_16x16x32_bf16 v[108:111], v[156:159], v[196:199], v[108:111]
	v_mfma_f32_16x16x32_bf16 v[104:107], v[164:167], v[196:199], v[104:107]
	v_mfma_f32_16x16x32_bf16 v[92:95], v[156:159], v[204:207], v[92:95]
	v_mfma_f32_16x16x32_bf16 v[88:91], v[164:167], v[204:207], v[88:91]
	v_mfma_f32_16x16x32_bf16 v[76:79], v[156:159], v[212:215], v[76:79]
	v_mfma_f32_16x16x32_bf16 v[72:75], v[164:167], v[212:215], v[72:75]
	v_mfma_f32_16x16x32_bf16 v[116:119], v[168:171], v[184:187], v[116:119]
	v_mfma_f32_16x16x32_bf16 v[112:115], v[176:179], v[184:187], v[112:115]
	v_mfma_f32_16x16x32_bf16 v[100:103], v[168:171], v[192:195], v[100:103]
	v_mfma_f32_16x16x32_bf16 v[96:99], v[176:179], v[192:195], v[96:99]
	v_mfma_f32_16x16x32_bf16 v[84:87], v[168:171], v[200:203], v[84:87]
	v_mfma_f32_16x16x32_bf16 v[80:83], v[176:179], v[200:203], v[80:83]
	v_mfma_f32_16x16x32_bf16 v[68:71], v[168:171], v[208:211], v[68:71]
	v_mfma_f32_16x16x32_bf16 v[64:67], v[176:179], v[208:211], v[64:67]
	v_mfma_f32_16x16x32_bf16 v[116:119], v[172:175], v[188:191], v[116:119]
	v_mfma_f32_16x16x32_bf16 v[112:115], v[180:183], v[188:191], v[112:115]
	v_mfma_f32_16x16x32_bf16 v[100:103], v[172:175], v[196:199], v[100:103]
	v_mfma_f32_16x16x32_bf16 v[96:99], v[180:183], v[196:199], v[96:99]
	v_mfma_f32_16x16x32_bf16 v[84:87], v[172:175], v[204:207], v[84:87]
	v_mfma_f32_16x16x32_bf16 v[80:83], v[180:183], v[204:207], v[80:83]
	v_mfma_f32_16x16x32_bf16 v[68:71], v[172:175], v[212:215], v[68:71]
	v_mfma_f32_16x16x32_bf16 v[64:67], v[180:183], v[212:215], v[64:67]
	s_barrier
	s_add_i32 s62, s80, s66
	v_lshl_add_u64 v[216:217], v[216:217], 0, s[44:45]
	s_mov_b32 m0, s62
	ds_read_b128 v[184:187], v153 offset:49152
	ds_read_b128 v[188:191], v153 offset:50176
	ds_read_b128 v[192:195], v153 offset:51200
	ds_read_b128 v[196:199], v153 offset:52224
	ds_read_b128 v[200:203], v153 offset:53248
	ds_read_b128 v[204:207], v153 offset:54272
	ds_read_b128 v[208:211], v153 offset:55296
	ds_read_b128 v[212:215], v153 offset:56320
	global_load_lds_dwordx4 v[216:217], off
	s_add_i32 m0, s62, 0x2000
	s_add_u32 s10, s10, 0x40080
	v_lshl_add_u64 v[216:217], v[218:219], 0, s[44:45]
	s_addc_u32 s11, s11, 0
	s_add_i32 s62, s81, s66
	global_load_lds_dwordx4 v[216:217], off
	v_lshl_add_u64 v[216:217], s[10:11], 0, v[130:131]
	s_mov_b32 m0, s62
	s_nop 0
	global_load_lds_dwordx4 v[216:217], off
	v_lshl_add_u64 v[216:217], s[10:11], 0, v[134:135]
	s_add_i32 m0, s62, 0x2000
	s_nop 0
	global_load_lds_dwordx4 v[216:217], off
	v_lshl_add_u64 v[216:217], v[222:223], 0, s[44:45]
	s_mov_b32 m0, s73
	s_nop 0
	global_load_lds_dwordx4 v[216:217], off
	v_lshl_add_u64 v[216:217], v[224:225], 0, s[44:45]
	s_mov_b32 m0, s76
	s_nop 0
	global_load_lds_dwordx4 v[216:217], off
	s_waitcnt vmcnt(8)
	s_waitcnt lgkmcnt(0)
	s_barrier
	s_waitcnt lgkmcnt(0)
	v_mfma_f32_16x16x32_bf16 v[60:63], v[144:147], v[184:187], v[60:63]
	v_mfma_f32_16x16x32_bf16 v[56:59], v[160:163], v[184:187], v[56:59]
	v_mfma_f32_16x16x32_bf16 v[44:47], v[144:147], v[192:195], v[44:47]
	v_mfma_f32_16x16x32_bf16 v[40:43], v[160:163], v[192:195], v[40:43]
	v_mfma_f32_16x16x32_bf16 v[28:31], v[144:147], v[200:203], v[28:31]
	v_mfma_f32_16x16x32_bf16 v[24:27], v[160:163], v[200:203], v[24:27]
	v_mfma_f32_16x16x32_bf16 v[12:15], v[144:147], v[208:211], v[12:15]
	v_mfma_f32_16x16x32_bf16 v[8:11], v[160:163], v[208:211], v[8:11]
	v_mfma_f32_16x16x32_bf16 v[60:63], v[156:159], v[188:191], v[60:63]
	v_mfma_f32_16x16x32_bf16 v[56:59], v[164:167], v[188:191], v[56:59]
	v_mfma_f32_16x16x32_bf16 v[44:47], v[156:159], v[196:199], v[44:47]
	v_mfma_f32_16x16x32_bf16 v[40:43], v[164:167], v[196:199], v[40:43]
	v_mfma_f32_16x16x32_bf16 v[28:31], v[156:159], v[204:207], v[28:31]
	v_mfma_f32_16x16x32_bf16 v[24:27], v[164:167], v[204:207], v[24:27]
	v_mfma_f32_16x16x32_bf16 v[12:15], v[156:159], v[212:215], v[12:15]
	v_mfma_f32_16x16x32_bf16 v[8:11], v[164:167], v[212:215], v[8:11]
	v_mfma_f32_16x16x32_bf16 v[52:55], v[168:171], v[184:187], v[52:55]
	v_mfma_f32_16x16x32_bf16 v[48:51], v[176:179], v[184:187], v[48:51]
	v_mfma_f32_16x16x32_bf16 v[36:39], v[168:171], v[192:195], v[36:39]
	v_mfma_f32_16x16x32_bf16 v[32:35], v[176:179], v[192:195], v[32:35]
	v_mfma_f32_16x16x32_bf16 v[20:23], v[168:171], v[200:203], v[20:23]
	v_mfma_f32_16x16x32_bf16 v[16:19], v[176:179], v[200:203], v[16:19]
	v_mfma_f32_16x16x32_bf16 v[4:7], v[168:171], v[208:211], v[4:7]
	v_mfma_f32_16x16x32_bf16 v[0:3], v[176:179], v[208:211], v[0:3]
	v_mfma_f32_16x16x32_bf16 v[52:55], v[172:175], v[188:191], v[52:55]
	v_mfma_f32_16x16x32_bf16 v[48:51], v[180:183], v[188:191], v[48:51]
	v_mfma_f32_16x16x32_bf16 v[36:39], v[172:175], v[196:199], v[36:39]
	v_mfma_f32_16x16x32_bf16 v[32:35], v[180:183], v[196:199], v[32:35]
	v_mfma_f32_16x16x32_bf16 v[20:23], v[172:175], v[204:207], v[20:23]
	v_mfma_f32_16x16x32_bf16 v[16:19], v[180:183], v[204:207], v[16:19]
	v_mfma_f32_16x16x32_bf16 v[4:7], v[172:175], v[212:215], v[4:7]
	v_mfma_f32_16x16x32_bf16 v[0:3], v[180:183], v[212:215], v[0:3]
	s_barrier
	s_add_i32 s61, s61, 2
	s_add_u32 s8, s8, 0x100
	s_addc_u32 s9, s9, 0
	s_add_u32 s51, s51, 0x100
	s_addc_u32 s53, s53, 0
	s_cmp_gt_u32 s61, 13
	s_cbranch_scc0 .LBB0_1068
	s_and_b64 vcc, exec, s[46:47]
	s_cbranch_vccz .LBB0_1071
	s_barrier

.LBB0_1162:
	s_or_b64 exec, exec, s[0:1]
	s_cmp_gt_i32 s2, 63
	s_mov_b64 s[0:1], s[66:67]
	s_mov_b64 s[4:5], s[64:65]
	s_waitcnt lgkmcnt(0)
	v_mov_b32_e32 v0, v220
	s_barrier
	s_setprio 0
	s_cbranch_scc1 .LBB0_1169
	v_ashrrev_i32_e32 v6, 5, v0
	v_ashrrev_i32_e32 v7, 31, v6
	v_lshlrev_b64 v[100:101], 10, v[6:7]
	s_mov_b64 s[4:5], 0x4000
	s_add_u32 s8, s0, 0x2600000
	v_and_b32_e32 v5, 31, v0
	v_lshl_add_u64 v[102:103], v[100:101], 0, s[4:5]
	s_movk_i32 s4, 0x210
	s_addc_u32 s9, s1, 0
	v_mul_lo_u32 v6, v6, s4
	v_lshl_add_u32 v108, v5, 2, 0
	s_movk_i32 s4, 0x20c
	s_add_u32 s10, s0, 0x7700000
	v_ashrrev_i32_e32 v1, 6, v0
	v_mad_u32_u24 v10, v5, s4, v108
	s_movk_i32 s5, 0xfdf4
	s_addc_u32 s11, s1, 0
	v_lshl_or_b32 v2, v1, 5, v5
	v_mad_i32_i24 v112, v5, s5, v10
	s_add_u32 s15, s0, 0xb800000
	v_bfe_u32 v9, v0, 5, 1
	v_ashrrev_i32_e32 v3, 31, v2
	v_mbcnt_hi_u32_b32 v11, -1, v221
	v_mad_u32_u24 v113, v5, s4, v112
	v_and_b32_e32 v0, 0xffffffc0, v0
	s_addc_u32 s20, s1, 0
	v_lshlrev_b32_e32 v8, 3, v5
	v_lshlrev_b32_e32 v7, 4, v5
	v_and_b32_e32 v13, 64, v11
	v_lshlrev_b32_e32 v111, 7, v1
	v_add_u32_e32 v5, v113, v0
	s_lshl_b64 s[4:5], s[2:3], 17
	v_lshlrev_b64 v[0:1], 9, v[2:3]
	v_lshlrev_b32_e32 v109, 4, v9
	v_xor_b32_e32 v12, 32, v11
	v_add_u32_e32 v13, 64, v13
	v_lshl_add_u64 v[0:1], s[4:5], 0, v[0:1]
	v_cmp_lt_i32_e32 vcc, v12, v13
	v_or_b32_e32 v0, v0, v109
	v_lshlrev_b32_e32 v4, 3, v9
	v_mov_b32_e32 v99, 0
	v_add_u32_e32 v6, 0, v6
	v_cndmask_b32_e32 v11, v11, v12, vcc
	v_lshl_add_u64 v[0:1], s[0:1], 0, v[0:1]
	s_mov_b64 s[0:1], 0x2e00100
	v_lshlrev_b64 v[96:97], 11, v[2:3]
	v_lshlrev_b32_e32 v110, 2, v11
	v_cmp_eq_u32_e64 s[40:41], 0, v9
	s_lshl_b32 s21, s2, 8
	s_lshl_b32 s22, s96, 8
	v_lshl_add_u64 v[104:105], v[0:1], 0, s[0:1]
	s_lshl_b64 s[0:1], s[96:97], 17
	v_lshlrev_b32_e32 v106, 1, v4
	v_mov_b32_e32 v107, v99
	v_lshlrev_b32_e32 v98, 1, v8
	v_add_u32_e32 v114, v6, v7
	v_add_u32_e32 v115, v10, v109
	v_add_u32_e32 v116, v5, v4
	s_mov_b32 s23, s2
	s_branch .LBB0_1165

.Lb8p_done:
.LBB0_1221:
	s_or_b64 exec, exec, s[0:1]
	s_mov_b64 s[4:5], s[66:67]
	s_mov_b64 s[0:1], s[64:65]
	v_mov_b32_e32 v13, v220
	s_waitcnt lgkmcnt(0)
	s_barrier
	s_cselect_b32 s99, 1, 0
	v_readfirstlane_b32 s98, v220
	s_lshr_b32 s98, s98, 8
	s_cmp_lg_u32 s98, 0
	s_cbranch_scc0 .Lprio_skip3
	s_setprio 1
.Lprio_skip3:
	s_cmp_lg_u32 s99, 0
	s_and_b64 vcc, exec, s[42:43]
	v_readfirstlane_b32 s40, v13
	s_cbranch_vccz .LBB0_1241
	v_lshlrev_b32_e32 v0, 4, v13
	v_add_u32_e32 v1, 0x2000, v0
	v_ashrrev_i32_e32 v2, 31, v1
	v_lshrrev_b32_e32 v2, 22, v2
	v_add_u32_e32 v2, v1, v2
	v_ashrrev_i32_e32 v8, 10, v2
	v_mul_i32_i24_e32 v2, 0x400, v8
	v_sub_u32_e32 v1, v1, v2
	v_lshrrev_b32_e32 v2, 4, v1
	v_bitop3_b32 v1, v2, v1, 32 bitop3:0x6c
	v_ashrrev_i32_e32 v2, 31, v1
	v_lshrrev_b32_e32 v2, 26, v2
	v_add_u32_e32 v2, v1, v2
	v_lshlrev_b32_e32 v3, 3, v8
	v_ashrrev_i32_e32 v9, 6, v2
	v_and_b32_e32 v3, -16, v3
	v_add_u32_e32 v3, v9, v3
	v_and_b32_e32 v4, 3, v9
	s_mov_b32 s0, 0x1fffe0
	v_lshrrev_b32_e32 v5, 2, v3
	v_lshlrev_b32_e32 v6, 1, v3
	v_and_b32_e32 v2, 0xc0, v2
	v_and_or_b32 v4, v3, s0, v4
	v_and_b32_e32 v5, 4, v5
	v_and_b32_e32 v6, 24, v6
	v_sub_u32_e32 v1, v1, v2
	v_mov_b32_e32 v2, 1
	v_or3_b32 v4, v4, v5, v6
	v_lshlrev_b32_e32 v5, 5, v8
	v_ashrrev_i16_sdwa v1, v2, sext(v1) dst_sel:DWORD dst_unused:UNUSED_PAD src0_sel:DWORD src1_sel:BYTE_0
	v_and_b32_e32 v5, 32, v5
	v_bfe_i32 v10, v1, 0, 16
	v_add_lshl_u32 v1, v5, v10, 1
	v_lshl_add_u32 v128, v4, 11, v1
	v_lshl_add_u32 v130, v3, 11, v1
	v_bfe_i32 v1, v13, 27, 1
	v_lshrrev_b32_e32 v1, 22, v1
	v_add_u32_e32 v1, v0, v1
	v_and_b32_e32 v1, 0xfffffc00, v1
	v_sub_u32_e32 v0, v0, v1
	v_lshrrev_b32_e32 v1, 4, v0
	v_ashrrev_i32_e32 v3, 31, v13
	v_bitop3_b32 v0, v1, v0, 32 bitop3:0x6c
	v_lshrrev_b32_e32 v3, 26, v3
	v_ashrrev_i32_e32 v1, 31, v0
	v_add_u32_e32 v3, v13, v3
	v_lshrrev_b32_e32 v1, 26, v1
	v_ashrrev_i32_e32 v12, 6, v3
	s_add_u32 s15, s4, 0xb800000
	v_add_u32_e32 v1, v0, v1
	v_lshlrev_b32_e32 v3, 3, v12
	s_addc_u32 s20, s5, 0
	v_ashrrev_i32_e32 v11, 6, v1
	v_and_b32_e32 v3, -16, v3
	s_add_u32 s21, s4, 0x1f080000
	v_add_u32_e32 v3, v11, v3
	v_and_b32_e32 v4, 3, v11
	s_addc_u32 s22, s5, 0
	v_and_or_b32 v4, v3, s0, v4
	s_lshr_b32 s0, s3, 29
	s_add_i32 s0, s2, s0
	s_and_b32 s1, s0, -8
	s_ashr_i32 s10, s40, 6
	s_sub_i32 s1, s2, s1
	s_ashr_i32 s11, s40, 8
	s_lshl_b32 s23, s10, 10
	s_lshl_b32 s7, s1, 6
	s_ashr_i32 s0, s0, 3
	s_mul_i32 s6, s1, 0x41
	s_cmp_lt_i32 s1, 0
	s_cselect_b32 s1, s6, s7
	s_add_i32 s0, s1, s0
	s_ashr_i32 s1, s0, 31
	s_lshr_b32 s1, s1, 27
	s_add_i32 s1, s0, s1
	s_ashr_i32 s6, s1, 5
	s_andn2_b32 s1, s1, 31
	s_sub_i32 s0, s0, s1
	s_bfe_i32 s1, s0, 0x80000
	s_bfe_u32 s1, s1, 0x3000c
	s_add_i32 s1, s0, s1
	s_bfe_i32 s7, s1, 0x80000
	s_and_b32 s1, s1, 0xf8
	s_sub_i32 s0, s0, s1
	s_lshl_b32 s6, s6, 3
	s_sext_i32_i16 s7, s7
	s_sext_i32_i8 s0, s0
	s_add_i32 s48, s6, s0
	s_ashr_i32 s0, s7, 3
	s_cmp_gt_i32 s48, 63
	s_cselect_b32 s1, 4, 0
	v_lshrrev_b32_e32 v5, 2, v3
	v_lshlrev_b32_e32 v6, 1, v3
	v_and_b32_e32 v1, 0xc0, v1
	s_add_i32 s0, s1, s0
	v_and_b32_e32 v5, 4, v5
	v_and_b32_e32 v6, 24, v6
	v_sub_u32_e32 v0, v0, v1
	s_ashr_i32 s49, s48, 31
	s_ashr_i32 s1, s0, 31
	v_or3_b32 v4, v4, v5, v6
	v_lshlrev_b32_e32 v5, 5, v12
	v_ashrrev_i16_sdwa v0, v2, sext(v0) dst_sel:DWORD dst_unused:UNUSED_PAD src0_sel:DWORD src1_sel:BYTE_0
	s_lshl_b64 s[6:7], s[48:49], 19
	s_lshl_b64 s[8:9], s[0:1], 19
	v_and_b32_e32 v5, 32, v5
	v_bfe_i32 v14, v0, 0, 16
	s_add_u32 s60, s21, s8
	v_add_lshl_u32 v0, v5, v14, 1
	s_addc_u32 s61, s22, s9
	s_add_i32 s33, s23, 0
	v_lshl_add_u32 v132, v4, 11, v0
	s_add_i32 m0, s33, 0x10000
	v_lshl_add_u32 v134, v3, 11, v0
	global_load_lds_dwordx4 v132, s[60:61]
	s_add_i32 m0, s33, 0x12000
	s_add_u32 s8, s60, 0x40000
	global_load_lds_dwordx4 v128, s[60:61]
	s_addc_u32 s9, s61, 0
	s_add_i32 m0, s33, 0x14000
	v_mov_b32_e32 v133, 0
	global_load_lds_dwordx4 v132, s[8:9]
	s_add_i32 m0, s33, 0x16000
	s_add_u32 s58, s15, s6
	s_addc_u32 s59, s20, s7
	s_add_i32 s49, s33, 0x2000
	global_load_lds_dwordx4 v128, s[8:9]
	s_mov_b32 m0, s33
	s_add_u32 s6, s58, 0x40000
	global_load_lds_dwordx4 v134, s[58:59]
	s_mov_b32 m0, s49
	s_addc_u32 s7, s59, 0
	s_add_i32 s64, s33, 0x4000
	global_load_lds_dwordx4 v130, s[58:59]
	s_mov_b32 m0, s64
	s_add_i32 s65, s33, 0x6000
	global_load_lds_dwordx4 v134, s[6:7]
	s_mov_b32 m0, s65
	v_mov_b32_e32 v129, v133
	global_load_lds_dwordx4 v130, s[6:7]
	v_mov_b32_e32 v135, v133
	v_mov_b32_e32 v131, v133
	s_cmp_eq_u32 s11, 1
	s_mov_b32 s1, 0
	v_lshl_add_u64 v[6:7], s[60:61], 0, v[132:133]
	v_lshl_add_u64 v[4:5], s[60:61], 0, v[128:129]
	v_lshl_add_u64 v[0:1], s[58:59], 0, v[134:135]
	s_cselect_b64 s[6:7], -1, 0
	s_cmp_lg_u32 s11, 1
	v_lshl_add_u64 v[2:3], s[58:59], 0, v[130:131]
	s_cbranch_scc1 .LBB0_1224
	s_barrier

.LBB0_1234:
	ds_read_b128 v[150:153], v147
	ds_read_b128 v[154:157], v147 offset:1024
	ds_read_b128 v[158:161], v147 offset:2048
	ds_read_b128 v[162:165], v147 offset:3072
	ds_read_b128 v[166:169], v148
	ds_read_b128 v[170:173], v148 offset:1024
	ds_read_b128 v[174:177], v148 offset:2048
	ds_read_b128 v[178:181], v148 offset:3072
	s_add_u32 s60, s58, 0xfffc0080
	s_addc_u32 s61, s59, -1
	s_cmp_eq_u32 s75, 12
	s_cselect_b32 s63, s47, s61
	s_cselect_b32 s62, s51, s60
	s_cselect_b32 s61, s53, s74
	s_cselect_b32 s60, s72, s73
	v_lshl_add_u64 v[214:215], s[58:59], 0, v[136:137]
	s_add_i32 m0, s33, 0xc000
	ds_read_b128 v[182:185], v149
	ds_read_b128 v[186:189], v149 offset:1024
	ds_read_b128 v[190:193], v149 offset:2048
	ds_read_b128 v[194:197], v149 offset:3072
	ds_read_b128 v[198:201], v149 offset:4096
	ds_read_b128 v[202:205], v149 offset:5120
	ds_read_b128 v[206:209], v149 offset:6144
	ds_read_b128 v[210:213], v149 offset:7168
	global_load_lds_dwordx4 v[214:215], off
	v_lshl_add_u64 v[214:215], s[58:59], 0, v[138:139]
	s_add_i32 m0, s33, 0xe000
	s_nop 0
	global_load_lds_dwordx4 v[214:215], off
	s_waitcnt vmcnt(8)
	s_waitcnt lgkmcnt(0)
	s_barrier
	s_waitcnt lgkmcnt(0)
	v_mfma_f32_16x16x32_bf16 v[124:127], v[150:153], v[182:185], v[124:127]
	v_mfma_f32_16x16x32_bf16 v[120:123], v[158:161], v[182:185], v[120:123]
	v_mfma_f32_16x16x32_bf16 v[116:119], v[150:153], v[190:193], v[116:119]
	v_mfma_f32_16x16x32_bf16 v[108:111], v[158:161], v[190:193], v[108:111]
	v_mfma_f32_16x16x32_bf16 v[100:103], v[150:153], v[198:201], v[100:103]
	v_mfma_f32_16x16x32_bf16 v[92:95], v[158:161], v[198:201], v[92:95]
	v_mfma_f32_16x16x32_bf16 v[84:87], v[150:153], v[206:209], v[84:87]
	v_mfma_f32_16x16x32_bf16 v[76:79], v[158:161], v[206:209], v[76:79]
	v_mfma_f32_16x16x32_bf16 v[124:127], v[154:157], v[186:189], v[124:127]
	v_mfma_f32_16x16x32_bf16 v[120:123], v[162:165], v[186:189], v[120:123]
	v_mfma_f32_16x16x32_bf16 v[116:119], v[154:157], v[194:197], v[116:119]
	v_mfma_f32_16x16x32_bf16 v[108:111], v[162:165], v[194:197], v[108:111]
	v_mfma_f32_16x16x32_bf16 v[100:103], v[154:157], v[202:205], v[100:103]
	v_mfma_f32_16x16x32_bf16 v[92:95], v[162:165], v[202:205], v[92:95]
	v_mfma_f32_16x16x32_bf16 v[84:87], v[154:157], v[210:213], v[84:87]
	v_mfma_f32_16x16x32_bf16 v[76:79], v[162:165], v[210:213], v[76:79]
	v_mfma_f32_16x16x32_bf16 v[112:115], v[166:169], v[182:185], v[112:115]
	v_mfma_f32_16x16x32_bf16 v[104:107], v[174:177], v[182:185], v[104:107]
	v_mfma_f32_16x16x32_bf16 v[96:99], v[166:169], v[190:193], v[96:99]
	v_mfma_f32_16x16x32_bf16 v[88:91], v[174:177], v[190:193], v[88:91]
	v_mfma_f32_16x16x32_bf16 v[80:83], v[166:169], v[198:201], v[80:83]
	v_mfma_f32_16x16x32_bf16 v[72:75], v[174:177], v[198:201], v[72:75]
	v_mfma_f32_16x16x32_bf16 v[68:71], v[166:169], v[206:209], v[68:71]
	v_mfma_f32_16x16x32_bf16 v[64:67], v[174:177], v[206:209], v[64:67]
	v_mfma_f32_16x16x32_bf16 v[112:115], v[170:173], v[186:189], v[112:115]
	v_mfma_f32_16x16x32_bf16 v[104:107], v[178:181], v[186:189], v[104:107]
	v_mfma_f32_16x16x32_bf16 v[96:99], v[170:173], v[194:197], v[96:99]
	v_mfma_f32_16x16x32_bf16 v[88:91], v[178:181], v[194:197], v[88:91]
	v_mfma_f32_16x16x32_bf16 v[80:83], v[170:173], v[202:205], v[80:83]
	v_mfma_f32_16x16x32_bf16 v[72:75], v[178:181], v[202:205], v[72:75]
	v_mfma_f32_16x16x32_bf16 v[68:71], v[170:173], v[210:213], v[68:71]
	v_mfma_f32_16x16x32_bf16 v[64:67], v[178:181], v[210:213], v[64:67]
	s_barrier
	s_add_i32 s76, s69, s23
	v_lshl_add_u64 v[214:215], s[60:61], 0, v[132:133]
	s_mov_b32 m0, s76
	ds_read_b128 v[182:185], v149 offset:16384
	ds_read_b128 v[186:189], v149 offset:17408
	ds_read_b128 v[190:193], v149 offset:18432
	ds_read_b128 v[194:197], v149 offset:19456
	ds_read_b128 v[198:201], v149 offset:20480
	ds_read_b128 v[202:205], v149 offset:21504
	ds_read_b128 v[206:209], v149 offset:22528
	ds_read_b128 v[210:213], v149 offset:23552
	global_load_lds_dwordx4 v[214:215], off
	s_add_i32 m0, s76, 0x2000
	s_add_u32 s76, s60, 0x40000
	v_lshl_add_u64 v[216:217], s[60:61], 0, v[128:129]
	s_addc_u32 s77, s61, 0
	s_add_i32 s78, s70, s23
	global_load_lds_dwordx4 v[216:217], off
	v_lshl_add_u64 v[218:219], s[76:77], 0, v[132:133]
	s_mov_b32 m0, s78
	v_lshl_add_u64 v[222:223], s[62:63], 0, v[130:131]
	global_load_lds_dwordx4 v[218:219], off
	v_lshl_add_u64 v[218:219], s[76:77], 0, v[128:129]
	s_add_i32 m0, s78, 0x2000
	s_nop 0
	global_load_lds_dwordx4 v[218:219], off
	v_lshl_add_u64 v[218:219], s[62:63], 0, v[134:135]
	s_mov_b32 m0, s33
	s_nop 0
	global_load_lds_dwordx4 v[218:219], off
	s_mov_b32 m0, s49
	s_nop 0
	global_load_lds_dwordx4 v[222:223], off
	s_waitcnt vmcnt(8)
	s_waitcnt lgkmcnt(0)
	s_barrier
	s_waitcnt lgkmcnt(0)
	v_mfma_f32_16x16x32_bf16 v[60:63], v[150:153], v[182:185], v[60:63]
	v_mfma_f32_16x16x32_bf16 v[56:59], v[158:161], v[182:185], v[56:59]
	v_mfma_f32_16x16x32_bf16 v[52:55], v[150:153], v[190:193], v[52:55]
	v_mfma_f32_16x16x32_bf16 v[44:47], v[158:161], v[190:193], v[44:47]
	v_mfma_f32_16x16x32_bf16 v[36:39], v[150:153], v[198:201], v[36:39]
	v_mfma_f32_16x16x32_bf16 v[28:31], v[158:161], v[198:201], v[28:31]
	v_mfma_f32_16x16x32_bf16 v[20:23], v[150:153], v[206:209], v[20:23]
	v_mfma_f32_16x16x32_bf16 v[12:15], v[158:161], v[206:209], v[12:15]
	v_mfma_f32_16x16x32_bf16 v[60:63], v[154:157], v[186:189], v[60:63]
	v_mfma_f32_16x16x32_bf16 v[56:59], v[162:165], v[186:189], v[56:59]
	v_mfma_f32_16x16x32_bf16 v[52:55], v[154:157], v[194:197], v[52:55]
	v_mfma_f32_16x16x32_bf16 v[44:47], v[162:165], v[194:197], v[44:47]
	v_mfma_f32_16x16x32_bf16 v[36:39], v[154:157], v[202:205], v[36:39]
	v_mfma_f32_16x16x32_bf16 v[28:31], v[162:165], v[202:205], v[28:31]
	v_mfma_f32_16x16x32_bf16 v[20:23], v[154:157], v[210:213], v[20:23]
	v_mfma_f32_16x16x32_bf16 v[12:15], v[162:165], v[210:213], v[12:15]
	v_mfma_f32_16x16x32_bf16 v[48:51], v[166:169], v[182:185], v[48:51]
	v_mfma_f32_16x16x32_bf16 v[40:43], v[174:177], v[182:185], v[40:43]
	v_mfma_f32_16x16x32_bf16 v[32:35], v[166:169], v[190:193], v[32:35]
	v_mfma_f32_16x16x32_bf16 v[24:27], v[174:177], v[190:193], v[24:27]
	v_mfma_f32_16x16x32_bf16 v[16:19], v[166:169], v[198:201], v[16:19]
	v_mfma_f32_16x16x32_bf16 v[8:11], v[174:177], v[198:201], v[8:11]
	v_mfma_f32_16x16x32_bf16 v[4:7], v[166:169], v[206:209], v[4:7]
	v_mfma_f32_16x16x32_bf16 v[0:3], v[174:177], v[206:209], v[0:3]
	v_mfma_f32_16x16x32_bf16 v[48:51], v[170:173], v[186:189], v[48:51]
	v_mfma_f32_16x16x32_bf16 v[40:43], v[178:181], v[186:189], v[40:43]
	v_mfma_f32_16x16x32_bf16 v[32:35], v[170:173], v[194:197], v[32:35]
	v_mfma_f32_16x16x32_bf16 v[24:27], v[178:181], v[194:197], v[24:27]
	v_mfma_f32_16x16x32_bf16 v[16:19], v[170:173], v[202:205], v[16:19]
	v_mfma_f32_16x16x32_bf16 v[8:11], v[178:181], v[202:205], v[8:11]
	v_mfma_f32_16x16x32_bf16 v[4:7], v[170:173], v[210:213], v[4:7]
	v_mfma_f32_16x16x32_bf16 v[0:3], v[178:181], v[210:213], v[0:3]
	s_barrier
	s_add_i32 s76, 0, 0x18000
	s_add_i32 s77, 0, 0x1c000
	v_add_u32_e32 v162, s76, v146
	v_add_u32_e32 v178, s77, v146
	ds_read_b128 v[150:153], v162
	ds_read_b128 v[154:157], v162 offset:1024
	ds_read_b128 v[158:161], v162 offset:2048
	ds_read_b128 v[162:165], v162 offset:3072
	ds_read_b128 v[166:169], v178
	ds_read_b128 v[170:173], v178 offset:1024
	ds_read_b128 v[174:177], v178 offset:2048
	ds_read_b128 v[178:181], v178 offset:3072
	s_add_u32 s62, s62, 0x40000
	s_addc_u32 s63, s63, 0
	s_mov_b32 m0, s64
	v_lshl_add_u64 v[224:225], s[62:63], 0, v[134:135]
	ds_read_b128 v[182:185], v149 offset:32768
	ds_read_b128 v[186:189], v149 offset:33792
	ds_read_b128 v[190:193], v149 offset:34816
	ds_read_b128 v[194:197], v149 offset:35840
	ds_read_b128 v[198:201], v149 offset:36864
	ds_read_b128 v[202:205], v149 offset:37888
	ds_read_b128 v[206:209], v149 offset:38912
	ds_read_b128 v[210:213], v149 offset:39936
	global_load_lds_dwordx4 v[224:225], off
	v_lshl_add_u64 v[224:225], s[62:63], 0, v[130:131]
	s_mov_b32 m0, s65
	s_nop 0
	global_load_lds_dwordx4 v[224:225], off
	s_waitcnt vmcnt(8)
	s_waitcnt lgkmcnt(0)
	s_barrier
	s_waitcnt lgkmcnt(0)
	v_mfma_f32_16x16x32_bf16 v[124:127], v[150:153], v[182:185], v[124:127]
	v_mfma_f32_16x16x32_bf16 v[120:123], v[158:161], v[182:185], v[120:123]
	v_mfma_f32_16x16x32_bf16 v[116:119], v[150:153], v[190:193], v[116:119]
	v_mfma_f32_16x16x32_bf16 v[108:111], v[158:161], v[190:193], v[108:111]
	v_mfma_f32_16x16x32_bf16 v[100:103], v[150:153], v[198:201], v[100:103]
	v_mfma_f32_16x16x32_bf16 v[92:95], v[158:161], v[198:201], v[92:95]
	v_mfma_f32_16x16x32_bf16 v[84:87], v[150:153], v[206:209], v[84:87]
	v_mfma_f32_16x16x32_bf16 v[76:79], v[158:161], v[206:209], v[76:79]
	v_mfma_f32_16x16x32_bf16 v[124:127], v[154:157], v[186:189], v[124:127]
	v_mfma_f32_16x16x32_bf16 v[120:123], v[162:165], v[186:189], v[120:123]
	v_mfma_f32_16x16x32_bf16 v[116:119], v[154:157], v[194:197], v[116:119]
	v_mfma_f32_16x16x32_bf16 v[108:111], v[162:165], v[194:197], v[108:111]
	v_mfma_f32_16x16x32_bf16 v[100:103], v[154:157], v[202:205], v[100:103]
	v_mfma_f32_16x16x32_bf16 v[92:95], v[162:165], v[202:205], v[92:95]
	v_mfma_f32_16x16x32_bf16 v[84:87], v[154:157], v[210:213], v[84:87]
	v_mfma_f32_16x16x32_bf16 v[76:79], v[162:165], v[210:213], v[76:79]
	v_mfma_f32_16x16x32_bf16 v[112:115], v[166:169], v[182:185], v[112:115]
	v_mfma_f32_16x16x32_bf16 v[104:107], v[174:177], v[182:185], v[104:107]
	v_mfma_f32_16x16x32_bf16 v[96:99], v[166:169], v[190:193], v[96:99]
	v_mfma_f32_16x16x32_bf16 v[88:91], v[174:177], v[190:193], v[88:91]
	v_mfma_f32_16x16x32_bf16 v[80:83], v[166:169], v[198:201], v[80:83]
	v_mfma_f32_16x16x32_bf16 v[72:75], v[174:177], v[198:201], v[72:75]
	v_mfma_f32_16x16x32_bf16 v[68:71], v[166:169], v[206:209], v[68:71]
	v_mfma_f32_16x16x32_bf16 v[64:67], v[174:177], v[206:209], v[64:67]
	v_mfma_f32_16x16x32_bf16 v[112:115], v[170:173], v[186:189], v[112:115]
	v_mfma_f32_16x16x32_bf16 v[104:107], v[178:181], v[186:189], v[104:107]
	v_mfma_f32_16x16x32_bf16 v[96:99], v[170:173], v[194:197], v[96:99]
	v_mfma_f32_16x16x32_bf16 v[88:91], v[178:181], v[194:197], v[88:91]
	v_mfma_f32_16x16x32_bf16 v[80:83], v[170:173], v[202:205], v[80:83]
	v_mfma_f32_16x16x32_bf16 v[72:75], v[178:181], v[202:205], v[72:75]
	v_mfma_f32_16x16x32_bf16 v[68:71], v[170:173], v[210:213], v[68:71]
	v_mfma_f32_16x16x32_bf16 v[64:67], v[178:181], v[210:213], v[64:67]
	s_barrier
	s_add_i32 s62, s76, s23
	v_lshl_add_u64 v[214:215], v[214:215], 0, s[10:11]
	s_mov_b32 m0, s62
	ds_read_b128 v[182:185], v149 offset:49152
	ds_read_b128 v[186:189], v149 offset:50176
	ds_read_b128 v[190:193], v149 offset:51200
	ds_read_b128 v[194:197], v149 offset:52224
	ds_read_b128 v[198:201], v149 offset:53248
	ds_read_b128 v[202:205], v149 offset:54272
	ds_read_b128 v[206:209], v149 offset:55296
	ds_read_b128 v[210:213], v149 offset:56320
	global_load_lds_dwordx4 v[214:215], off
	s_add_i32 m0, s62, 0x2000
	s_add_u32 s60, s60, 0x40080
	v_lshl_add_u64 v[214:215], v[216:217], 0, s[10:11]
	s_addc_u32 s61, s61, 0
	s_add_i32 s62, s77, s23
	global_load_lds_dwordx4 v[214:215], off
	v_lshl_add_u64 v[214:215], s[60:61], 0, v[132:133]
	s_mov_b32 m0, s62
	s_nop 0
	global_load_lds_dwordx4 v[214:215], off
	v_lshl_add_u64 v[214:215], s[60:61], 0, v[128:129]
	s_add_i32 m0, s62, 0x2000
	s_nop 0
	global_load_lds_dwordx4 v[214:215], off
	v_lshl_add_u64 v[214:215], v[218:219], 0, s[10:11]
	s_mov_b32 m0, s67
	s_nop 0
	global_load_lds_dwordx4 v[214:215], off
	v_lshl_add_u64 v[214:215], v[222:223], 0, s[10:11]
	s_mov_b32 m0, s68
	s_nop 0
	global_load_lds_dwordx4 v[214:215], off
	s_waitcnt vmcnt(8)
	s_waitcnt lgkmcnt(0)
	s_barrier
	s_waitcnt lgkmcnt(0)
	v_mfma_f32_16x16x32_bf16 v[60:63], v[150:153], v[182:185], v[60:63]
	v_mfma_f32_16x16x32_bf16 v[56:59], v[158:161], v[182:185], v[56:59]
	v_mfma_f32_16x16x32_bf16 v[52:55], v[150:153], v[190:193], v[52:55]
	v_mfma_f32_16x16x32_bf16 v[44:47], v[158:161], v[190:193], v[44:47]
	v_mfma_f32_16x16x32_bf16 v[36:39], v[150:153], v[198:201], v[36:39]
	v_mfma_f32_16x16x32_bf16 v[28:31], v[158:161], v[198:201], v[28:31]
	v_mfma_f32_16x16x32_bf16 v[20:23], v[150:153], v[206:209], v[20:23]
	v_mfma_f32_16x16x32_bf16 v[12:15], v[158:161], v[206:209], v[12:15]
	v_mfma_f32_16x16x32_bf16 v[60:63], v[154:157], v[186:189], v[60:63]
	v_mfma_f32_16x16x32_bf16 v[56:59], v[162:165], v[186:189], v[56:59]
	v_mfma_f32_16x16x32_bf16 v[52:55], v[154:157], v[194:197], v[52:55]
	v_mfma_f32_16x16x32_bf16 v[44:47], v[162:165], v[194:197], v[44:47]
	v_mfma_f32_16x16x32_bf16 v[36:39], v[154:157], v[202:205], v[36:39]
	v_mfma_f32_16x16x32_bf16 v[28:31], v[162:165], v[202:205], v[28:31]
	v_mfma_f32_16x16x32_bf16 v[20:23], v[154:157], v[210:213], v[20:23]
	v_mfma_f32_16x16x32_bf16 v[12:15], v[162:165], v[210:213], v[12:15]
	v_mfma_f32_16x16x32_bf16 v[48:51], v[166:169], v[182:185], v[48:51]
	v_mfma_f32_16x16x32_bf16 v[40:43], v[174:177], v[182:185], v[40:43]
	v_mfma_f32_16x16x32_bf16 v[32:35], v[166:169], v[190:193], v[32:35]
	v_mfma_f32_16x16x32_bf16 v[24:27], v[174:177], v[190:193], v[24:27]
	v_mfma_f32_16x16x32_bf16 v[16:19], v[166:169], v[198:201], v[16:19]
	v_mfma_f32_16x16x32_bf16 v[8:11], v[174:177], v[198:201], v[8:11]
	v_mfma_f32_16x16x32_bf16 v[4:7], v[166:169], v[206:209], v[4:7]
	v_mfma_f32_16x16x32_bf16 v[0:3], v[174:177], v[206:209], v[0:3]
	v_mfma_f32_16x16x32_bf16 v[48:51], v[170:173], v[186:189], v[48:51]
	v_mfma_f32_16x16x32_bf16 v[40:43], v[178:181], v[186:189], v[40:43]
	v_mfma_f32_16x16x32_bf16 v[32:35], v[170:173], v[194:197], v[32:35]
	v_mfma_f32_16x16x32_bf16 v[24:27], v[178:181], v[194:197], v[24:27]
	v_mfma_f32_16x16x32_bf16 v[16:19], v[170:173], v[202:205], v[16:19]
	v_mfma_f32_16x16x32_bf16 v[8:11], v[178:181], v[202:205], v[8:11]
	v_mfma_f32_16x16x32_bf16 v[4:7], v[170:173], v[210:213], v[4:7]
	v_mfma_f32_16x16x32_bf16 v[0:3], v[178:181], v[210:213], v[0:3]
	s_barrier
	s_add_i32 s75, s75, 2
	s_add_u32 s58, s58, 0x100
	s_addc_u32 s59, s59, 0
	s_add_u32 s73, s73, 0x100
	s_addc_u32 s74, s74, 0
	s_cmp_gt_u32 s75, 13
	s_cbranch_scc0 .LBB0_1234
	s_and_b64 vcc, exec, s[44:45]
	s_cbranch_vccz .LBB0_1237
	s_barrier

.LBB0_1296:
	s_or_b64 exec, exec, s[0:1]
	s_mov_b64 s[0:1], s[66:67]
	s_mov_b64 s[4:5], s[64:65]
	v_mov_b32_e32 v33, v220
	s_waitcnt lgkmcnt(0)
	s_barrier
	s_setprio 0
	s_mov_b64 s[46:47], s[12:13]
	v_lshlrev_b32_e32 v0, 3, v33
	s_mov_b64 s[44:45], s[16:17]
	v_and_b32_e32 v32, 0x1f8, v0
	v_readlane_b32 s8, v245, 21
	v_lshlrev_b32_e32 v6, 2, v32
	v_readlane_b32 s20, v245, 33
	v_readlane_b32 s21, v245, 34
	v_readlane_b32 s22, v245, 35
	v_readlane_b32 s23, v245, 36
	s_cmp_lg_u64 s[22:23], 0
	v_mov_b32_e32 v4, 0
	s_cselect_b64 s[4:5], -1, 0
	global_load_dwordx4 v[0:3], v6, s[20:21]
	v_mov_b32_e32 v7, v4
	v_readfirstlane_b32 s6, v33
	v_lshl_add_u64 v[28:29], s[20:21], 0, v[6:7]
	v_lshl_add_u64 v[30:31], s[22:23], 0, v[6:7]
	s_and_b64 vcc, exec, s[4:5]
	v_mov_b32_e32 v8, 0
	v_mov_b32_e32 v9, v4
	v_mov_b32_e32 v10, 0
	v_mov_b32_e32 v11, v4
	v_mov_b32_e32 v12, 0
	v_mov_b32_e32 v13, v4
	v_mov_b32_e32 v14, 0
	v_mov_b32_e32 v15, v4
	v_readlane_b32 s9, v245, 22
	v_readlane_b32 s10, v245, 23
	v_readlane_b32 s11, v245, 24
	v_readlane_b32 s12, v245, 25
	v_readlane_b32 s13, v245, 26
	v_readlane_b32 s14, v245, 27
	v_readlane_b32 s15, v245, 28
	v_readlane_b32 s16, v245, 29
	v_readlane_b32 s17, v245, 30
	v_readlane_b32 s18, v245, 31
	v_readlane_b32 s19, v245, 32
	s_cbranch_vccz .LBB0_1298
	global_load_dwordx4 v[8:11], v[30:31], off
	global_load_dwordx4 v[12:15], v[30:31], off offset:16

.LBB0_1363:
	s_or_b64 exec, exec, s[0:1]
	s_mov_b64 s[6:7], s[66:67]
	s_mov_b64 s[0:1], s[64:65]
	s_waitcnt vmcnt(3)
	v_mov_b32_e32 v14, v220
	s_waitcnt lgkmcnt(0)
	s_barrier
	s_cselect_b32 s99, 1, 0
	v_readfirstlane_b32 s98, v220
	s_lshr_b32 s98, s98, 8
	s_cmp_lg_u32 s98, 0
	s_cbranch_scc0 .Lprio_skip4
	s_setprio 1
.Lprio_skip4:
	s_cmp_lg_u32 s99, 0
	s_cmpk_gt_i32 s2, 0xb2b
	s_nop 0
	v_readfirstlane_b32 s10, v14
	s_cbranch_scc1 .LBB0_1383
	v_lshlrev_b32_e32 v0, 4, v14
	v_add_u32_e32 v1, 0x2000, v0
	v_ashrrev_i32_e32 v2, 31, v1
	v_lshrrev_b32_e32 v2, 22, v2
	v_add_u32_e32 v2, v1, v2
	v_ashrrev_i32_e32 v8, 10, v2
	v_mul_i32_i24_e32 v2, 0x400, v8
	v_sub_u32_e32 v1, v1, v2
	v_lshrrev_b32_e32 v2, 4, v1
	v_bitop3_b32 v1, v2, v1, 32 bitop3:0x6c
	v_ashrrev_i32_e32 v2, 31, v1
	v_lshrrev_b32_e32 v2, 26, v2
	v_add_u32_e32 v2, v1, v2
	v_lshlrev_b32_e32 v3, 3, v8
	v_ashrrev_i32_e32 v9, 6, v2
	v_and_b32_e32 v3, -16, v3
	v_add_u32_e32 v3, v9, v3
	s_waitcnt vmcnt(2)
	v_and_b32_e32 v4, 3, v9
	s_mov_b32 s0, 0x1fffe0
	v_lshrrev_b32_e32 v5, 2, v3
	v_lshlrev_b32_e32 v6, 1, v3
	v_and_b32_e32 v2, 0xc0, v2
	v_and_or_b32 v4, v3, s0, v4
	v_and_b32_e32 v5, 4, v5
	v_and_b32_e32 v6, 24, v6
	v_sub_u32_e32 v1, v1, v2
	v_mov_b32_e32 v2, 1
	v_or3_b32 v4, v4, v5, v6
	v_lshlrev_b32_e32 v5, 5, v8
	v_ashrrev_i16_sdwa v1, v2, sext(v1) dst_sel:DWORD dst_unused:UNUSED_PAD src0_sel:DWORD src1_sel:BYTE_0
	v_and_b32_e32 v5, 32, v5
	v_bfe_i32 v10, v1, 0, 16
	v_add_lshl_u32 v1, v5, v10, 1
	v_lshl_add_u32 v128, v4, 11, v1
	v_lshl_add_u32 v130, v3, 11, v1
	v_bfe_i32 v1, v14, 27, 1
	v_lshrrev_b32_e32 v1, 22, v1
	v_add_u32_e32 v1, v0, v1
	v_and_b32_e32 v1, 0xfffffc00, v1
	v_sub_u32_e32 v0, v0, v1
	v_lshrrev_b32_e32 v1, 4, v0
	v_ashrrev_i32_e32 v3, 31, v14
	v_bitop3_b32 v0, v1, v0, 32 bitop3:0x6c
	v_lshrrev_b32_e32 v3, 26, v3
	v_ashrrev_i32_e32 v1, 31, v0
	v_add_u32_e32 v3, v14, v3
	v_lshrrev_b32_e32 v1, 26, v1
	v_ashrrev_i32_e32 v12, 6, v3
	s_add_u32 s15, s6, 0x1200000
	v_add_u32_e32 v1, v0, v1
	v_lshlrev_b32_e32 v3, 3, v12
	s_addc_u32 s20, s7, 0
	v_ashrrev_i32_e32 v11, 6, v1
	v_and_b32_e32 v3, -16, v3
	s_add_u32 s21, s6, 0x3600000
	v_add_u32_e32 v3, v11, v3
	v_and_b32_e32 v4, 3, v11
	s_addc_u32 s33, s7, 0
	v_and_or_b32 v4, v3, s0, v4
	s_lshr_b32 s0, s3, 29
	s_add_i32 s0, s2, s0
	s_and_b32 s1, s0, -8
	s_sub_i32 s1, s2, s1
	s_ashr_i32 s8, s10, 6
	s_mul_i32 s5, s1, 0x165
	s_ashr_i32 s9, s10, 8
	s_lshl_b32 s60, s8, 10
	s_add_i32 s5, s5, 4
	s_ashr_i32 s0, s0, 3
	s_mul_i32 s4, s1, 0x166
	s_cmp_lt_i32 s1, 4
	s_cselect_b32 s1, s4, s5
	s_add_i32 s1, s1, s0
	s_mul_hi_i32 s0, s1, 0x2e8ba2e9
	s_lshr_b32 s4, s0, 31
	s_ashr_i32 s0, s0, 5
	v_lshrrev_b32_e32 v5, 2, v3
	v_lshlrev_b32_e32 v6, 1, v3
	v_and_b32_e32 v1, 0xc0, v1
	s_add_i32 s0, s0, s4
	v_and_b32_e32 v5, 4, v5
	v_and_b32_e32 v6, 24, v6
	v_sub_u32_e32 v0, v0, v1
	s_lshl_b32 s4, s0, 3
	v_or3_b32 v4, v4, v5, v6
	v_lshlrev_b32_e32 v5, 5, v12
	v_ashrrev_i16_sdwa v0, v2, sext(v0) dst_sel:DWORD dst_unused:UNUSED_PAD src0_sel:DWORD src1_sel:BYTE_0
	s_sub_i32 s5, 0x82, s4
	s_mulk_i32 s0, 0xb0
	v_and_b32_e32 v5, 32, v5
	v_bfe_i32 v13, v0, 0, 16
	s_min_u32 s5, s5, 8
	s_sub_i32 s11, s1, s0
	v_add_lshl_u32 v0, v5, v13, 1
	s_sext_i32_i16 s0, s11
	v_cvt_f32_ubyte0_e32 v2, s5
	v_lshl_add_u32 v132, v4, 11, v0
	v_cvt_f32_i32_e32 v1, s0
	v_rcp_iflag_f32_e32 v4, v2
	v_lshl_add_u32 v134, v3, 11, v0
	s_ashr_i32 s0, s0, 30
	s_or_b32 s22, s0, 1
	v_mul_f32_e32 v0, v1, v4
	v_trunc_f32_e32 v0, v0
	v_fma_f32 v1, -v0, v2, v1
	v_cvt_i32_f32_e32 v0, v0
	v_cmp_ge_f32_e64 s[0:1], |v1|, v2
	s_and_b64 s[0:1], s[0:1], exec
	s_cselect_b32 s0, s22, 0
	v_readfirstlane_b32 s1, v0
	s_add_i32 s0, s1, s0
	s_mul_i32 s1, s0, s5
	s_sub_i32 s1, s11, s1
	s_sext_i32_i16 s1, s1
	s_add_i32 s52, s4, s1
	s_ashr_i32 s53, s52, 31
	s_bfe_i64 s[22:23], s[0:1], 0x100000
	s_lshl_b64 s[4:5], s[52:53], 19
	s_lshl_b64 s[22:23], s[22:23], 19
	s_add_u32 s56, s15, s22
	s_addc_u32 s57, s20, s23
	s_add_i32 s61, s60, 0
	s_add_i32 m0, s61, 0x10000
	v_mov_b32_e32 v133, 0
	global_load_lds_dwordx4 v132, s[56:57]
	s_add_i32 m0, s61, 0x12000
	s_add_u32 s22, s56, 0x40000
	global_load_lds_dwordx4 v128, s[56:57]
	s_addc_u32 s23, s57, 0
	s_add_i32 m0, s61, 0x14000
	v_mov_b32_e32 v129, v133
	global_load_lds_dwordx4 v132, s[22:23]
	s_add_i32 m0, s61, 0x16000
	s_add_u32 s54, s21, s4
	global_load_lds_dwordx4 v128, s[22:23]
	s_addc_u32 s55, s33, s5
	s_add_i32 s22, s61, 0x2000
	s_mov_b32 m0, s61
	s_add_u32 s4, s54, 0x40000
	global_load_lds_dwordx4 v134, s[54:55]
	s_mov_b32 m0, s22
	s_addc_u32 s5, s55, 0
	s_add_i32 s23, s61, 0x4000
	global_load_lds_dwordx4 v130, s[54:55]
	s_mov_b32 m0, s23
	s_add_i32 s62, s61, 0x6000
	global_load_lds_dwordx4 v134, s[4:5]
	s_mov_b32 m0, s62
	v_mov_b32_e32 v135, v133
	global_load_lds_dwordx4 v130, s[4:5]
	v_mov_b32_e32 v131, v133
	s_cmp_eq_u32 s9, 1
	s_mov_b32 s1, 0
	v_lshl_add_u64 v[6:7], s[56:57], 0, v[132:133]
	v_lshl_add_u64 v[4:5], s[56:57], 0, v[128:129]
	v_lshl_add_u64 v[0:1], s[54:55], 0, v[134:135]
	s_cselect_b64 s[4:5], -1, 0
	s_cmp_lg_u32 s9, 1
	v_lshl_add_u64 v[2:3], s[54:55], 0, v[130:131]
	s_cbranch_scc1 .LBB0_1366
	s_barrier

.LBB0_1376:
	ds_read_b128 v[150:153], v147
	ds_read_b128 v[154:157], v147 offset:1024
	ds_read_b128 v[158:161], v147 offset:2048
	ds_read_b128 v[162:165], v147 offset:3072
	ds_read_b128 v[166:169], v148
	ds_read_b128 v[170:173], v148 offset:1024
	ds_read_b128 v[174:177], v148 offset:2048
	ds_read_b128 v[178:181], v148 offset:3072
	s_add_u32 s56, s54, 0xfffc0080
	s_addc_u32 s57, s55, -1
	s_cmp_eq_u32 s74, 12
	s_cselect_b32 s59, s47, s57
	s_cselect_b32 s58, s70, s56
	s_cselect_b32 s57, s45, s73
	s_cselect_b32 s56, s71, s72
	v_lshl_add_u64 v[214:215], s[54:55], 0, v[136:137]
	s_add_i32 m0, s61, 0xc000
	ds_read_b128 v[182:185], v149
	ds_read_b128 v[186:189], v149 offset:1024
	ds_read_b128 v[190:193], v149 offset:2048
	ds_read_b128 v[194:197], v149 offset:3072
	ds_read_b128 v[198:201], v149 offset:4096
	ds_read_b128 v[202:205], v149 offset:5120
	ds_read_b128 v[206:209], v149 offset:6144
	ds_read_b128 v[210:213], v149 offset:7168
	global_load_lds_dwordx4 v[214:215], off
	v_lshl_add_u64 v[214:215], s[54:55], 0, v[138:139]
	s_add_i32 m0, s61, 0xe000
	s_nop 0
	global_load_lds_dwordx4 v[214:215], off
	s_waitcnt vmcnt(8)
	s_waitcnt lgkmcnt(0)
	s_barrier
	s_waitcnt lgkmcnt(0)
	v_mfma_f32_16x16x32_bf16 v[124:127], v[150:153], v[182:185], v[124:127]
	v_mfma_f32_16x16x32_bf16 v[120:123], v[158:161], v[182:185], v[120:123]
	v_mfma_f32_16x16x32_bf16 v[108:111], v[150:153], v[190:193], v[108:111]
	v_mfma_f32_16x16x32_bf16 v[104:107], v[158:161], v[190:193], v[104:107]
	v_mfma_f32_16x16x32_bf16 v[92:95], v[150:153], v[198:201], v[92:95]
	v_mfma_f32_16x16x32_bf16 v[88:91], v[158:161], v[198:201], v[88:91]
	v_mfma_f32_16x16x32_bf16 v[76:79], v[150:153], v[206:209], v[76:79]
	v_mfma_f32_16x16x32_bf16 v[72:75], v[158:161], v[206:209], v[72:75]
	v_mfma_f32_16x16x32_bf16 v[124:127], v[154:157], v[186:189], v[124:127]
	v_mfma_f32_16x16x32_bf16 v[120:123], v[162:165], v[186:189], v[120:123]
	v_mfma_f32_16x16x32_bf16 v[108:111], v[154:157], v[194:197], v[108:111]
	v_mfma_f32_16x16x32_bf16 v[104:107], v[162:165], v[194:197], v[104:107]
	v_mfma_f32_16x16x32_bf16 v[92:95], v[154:157], v[202:205], v[92:95]
	v_mfma_f32_16x16x32_bf16 v[88:91], v[162:165], v[202:205], v[88:91]
	v_mfma_f32_16x16x32_bf16 v[76:79], v[154:157], v[210:213], v[76:79]
	v_mfma_f32_16x16x32_bf16 v[72:75], v[162:165], v[210:213], v[72:75]
	v_mfma_f32_16x16x32_bf16 v[116:119], v[166:169], v[182:185], v[116:119]
	v_mfma_f32_16x16x32_bf16 v[112:115], v[174:177], v[182:185], v[112:115]
	v_mfma_f32_16x16x32_bf16 v[100:103], v[166:169], v[190:193], v[100:103]
	v_mfma_f32_16x16x32_bf16 v[96:99], v[174:177], v[190:193], v[96:99]
	v_mfma_f32_16x16x32_bf16 v[84:87], v[166:169], v[198:201], v[84:87]
	v_mfma_f32_16x16x32_bf16 v[80:83], v[174:177], v[198:201], v[80:83]
	v_mfma_f32_16x16x32_bf16 v[68:71], v[166:169], v[206:209], v[68:71]
	v_mfma_f32_16x16x32_bf16 v[64:67], v[174:177], v[206:209], v[64:67]
	v_mfma_f32_16x16x32_bf16 v[116:119], v[170:173], v[186:189], v[116:119]
	v_mfma_f32_16x16x32_bf16 v[112:115], v[178:181], v[186:189], v[112:115]
	v_mfma_f32_16x16x32_bf16 v[100:103], v[170:173], v[194:197], v[100:103]
	v_mfma_f32_16x16x32_bf16 v[96:99], v[178:181], v[194:197], v[96:99]
	v_mfma_f32_16x16x32_bf16 v[84:87], v[170:173], v[202:205], v[84:87]
	v_mfma_f32_16x16x32_bf16 v[80:83], v[178:181], v[202:205], v[80:83]
	v_mfma_f32_16x16x32_bf16 v[68:71], v[170:173], v[210:213], v[68:71]
	v_mfma_f32_16x16x32_bf16 v[64:67], v[178:181], v[210:213], v[64:67]
	s_barrier
	s_add_i32 s75, s66, s60
	v_lshl_add_u64 v[214:215], s[56:57], 0, v[132:133]
	s_mov_b32 m0, s75
	ds_read_b128 v[182:185], v149 offset:16384
	ds_read_b128 v[186:189], v149 offset:17408
	ds_read_b128 v[190:193], v149 offset:18432
	ds_read_b128 v[194:197], v149 offset:19456
	ds_read_b128 v[198:201], v149 offset:20480
	ds_read_b128 v[202:205], v149 offset:21504
	ds_read_b128 v[206:209], v149 offset:22528
	ds_read_b128 v[210:213], v149 offset:23552
	global_load_lds_dwordx4 v[214:215], off
	s_add_i32 m0, s75, 0x2000
	s_add_u32 s76, s56, 0x40000
	v_lshl_add_u64 v[216:217], s[56:57], 0, v[128:129]
	s_addc_u32 s77, s57, 0
	s_add_i32 s75, s67, s60
	global_load_lds_dwordx4 v[216:217], off
	v_lshl_add_u64 v[218:219], s[76:77], 0, v[132:133]
	s_mov_b32 m0, s75
	v_lshl_add_u64 v[222:223], s[58:59], 0, v[130:131]
	global_load_lds_dwordx4 v[218:219], off
	v_lshl_add_u64 v[218:219], s[76:77], 0, v[128:129]
	s_add_i32 m0, s75, 0x2000
	s_nop 0
	global_load_lds_dwordx4 v[218:219], off
	v_lshl_add_u64 v[218:219], s[58:59], 0, v[134:135]
	s_mov_b32 m0, s61
	s_nop 0
	global_load_lds_dwordx4 v[218:219], off
	s_mov_b32 m0, s22
	s_nop 0
	global_load_lds_dwordx4 v[222:223], off
	s_waitcnt vmcnt(8)
	s_waitcnt lgkmcnt(0)
	s_barrier
	s_waitcnt lgkmcnt(0)
	v_mfma_f32_16x16x32_bf16 v[60:63], v[150:153], v[182:185], v[60:63]
	v_mfma_f32_16x16x32_bf16 v[56:59], v[158:161], v[182:185], v[56:59]
	v_mfma_f32_16x16x32_bf16 v[44:47], v[150:153], v[190:193], v[44:47]
	v_mfma_f32_16x16x32_bf16 v[40:43], v[158:161], v[190:193], v[40:43]
	v_mfma_f32_16x16x32_bf16 v[28:31], v[150:153], v[198:201], v[28:31]
	v_mfma_f32_16x16x32_bf16 v[24:27], v[158:161], v[198:201], v[24:27]
	v_mfma_f32_16x16x32_bf16 v[12:15], v[150:153], v[206:209], v[12:15]
	v_mfma_f32_16x16x32_bf16 v[8:11], v[158:161], v[206:209], v[8:11]
	v_mfma_f32_16x16x32_bf16 v[60:63], v[154:157], v[186:189], v[60:63]
	v_mfma_f32_16x16x32_bf16 v[56:59], v[162:165], v[186:189], v[56:59]
	v_mfma_f32_16x16x32_bf16 v[44:47], v[154:157], v[194:197], v[44:47]
	v_mfma_f32_16x16x32_bf16 v[40:43], v[162:165], v[194:197], v[40:43]
	v_mfma_f32_16x16x32_bf16 v[28:31], v[154:157], v[202:205], v[28:31]
	v_mfma_f32_16x16x32_bf16 v[24:27], v[162:165], v[202:205], v[24:27]
	v_mfma_f32_16x16x32_bf16 v[12:15], v[154:157], v[210:213], v[12:15]
	v_mfma_f32_16x16x32_bf16 v[8:11], v[162:165], v[210:213], v[8:11]
	v_mfma_f32_16x16x32_bf16 v[52:55], v[166:169], v[182:185], v[52:55]
	v_mfma_f32_16x16x32_bf16 v[48:51], v[174:177], v[182:185], v[48:51]
	v_mfma_f32_16x16x32_bf16 v[36:39], v[166:169], v[190:193], v[36:39]
	v_mfma_f32_16x16x32_bf16 v[32:35], v[174:177], v[190:193], v[32:35]
	v_mfma_f32_16x16x32_bf16 v[20:23], v[166:169], v[198:201], v[20:23]
	v_mfma_f32_16x16x32_bf16 v[16:19], v[174:177], v[198:201], v[16:19]
	v_mfma_f32_16x16x32_bf16 v[4:7], v[166:169], v[206:209], v[4:7]
	v_mfma_f32_16x16x32_bf16 v[0:3], v[174:177], v[206:209], v[0:3]
	v_mfma_f32_16x16x32_bf16 v[52:55], v[170:173], v[186:189], v[52:55]
	v_mfma_f32_16x16x32_bf16 v[48:51], v[178:181], v[186:189], v[48:51]
	v_mfma_f32_16x16x32_bf16 v[36:39], v[170:173], v[194:197], v[36:39]
	v_mfma_f32_16x16x32_bf16 v[32:35], v[178:181], v[194:197], v[32:35]
	v_mfma_f32_16x16x32_bf16 v[20:23], v[170:173], v[202:205], v[20:23]
	v_mfma_f32_16x16x32_bf16 v[16:19], v[178:181], v[202:205], v[16:19]
	v_mfma_f32_16x16x32_bf16 v[4:7], v[170:173], v[210:213], v[4:7]
	v_mfma_f32_16x16x32_bf16 v[0:3], v[178:181], v[210:213], v[0:3]
	s_barrier
	s_add_i32 s75, 0, 0x18000
	s_add_i32 s76, 0, 0x1c000
	v_add_u32_e32 v162, s75, v146
	v_add_u32_e32 v178, s76, v146
	ds_read_b128 v[150:153], v162
	ds_read_b128 v[154:157], v162 offset:1024
	ds_read_b128 v[158:161], v162 offset:2048
	ds_read_b128 v[162:165], v162 offset:3072
	ds_read_b128 v[166:169], v178
	ds_read_b128 v[170:173], v178 offset:1024
	ds_read_b128 v[174:177], v178 offset:2048
	ds_read_b128 v[178:181], v178 offset:3072
	s_add_u32 s58, s58, 0x40000
	s_addc_u32 s59, s59, 0
	s_mov_b32 m0, s23
	v_lshl_add_u64 v[224:225], s[58:59], 0, v[134:135]
	ds_read_b128 v[182:185], v149 offset:32768
	ds_read_b128 v[186:189], v149 offset:33792
	ds_read_b128 v[190:193], v149 offset:34816
	ds_read_b128 v[194:197], v149 offset:35840
	ds_read_b128 v[198:201], v149 offset:36864
	ds_read_b128 v[202:205], v149 offset:37888
	ds_read_b128 v[206:209], v149 offset:38912
	ds_read_b128 v[210:213], v149 offset:39936
	global_load_lds_dwordx4 v[224:225], off
	v_lshl_add_u64 v[224:225], s[58:59], 0, v[130:131]
	s_mov_b32 m0, s62
	s_nop 0
	global_load_lds_dwordx4 v[224:225], off
	s_waitcnt vmcnt(8)
	s_waitcnt lgkmcnt(0)
	s_barrier
	s_waitcnt lgkmcnt(0)
	v_mfma_f32_16x16x32_bf16 v[124:127], v[150:153], v[182:185], v[124:127]
	v_mfma_f32_16x16x32_bf16 v[120:123], v[158:161], v[182:185], v[120:123]
	v_mfma_f32_16x16x32_bf16 v[108:111], v[150:153], v[190:193], v[108:111]
	v_mfma_f32_16x16x32_bf16 v[104:107], v[158:161], v[190:193], v[104:107]
	v_mfma_f32_16x16x32_bf16 v[92:95], v[150:153], v[198:201], v[92:95]
	v_mfma_f32_16x16x32_bf16 v[88:91], v[158:161], v[198:201], v[88:91]
	v_mfma_f32_16x16x32_bf16 v[76:79], v[150:153], v[206:209], v[76:79]
	v_mfma_f32_16x16x32_bf16 v[72:75], v[158:161], v[206:209], v[72:75]
	v_mfma_f32_16x16x32_bf16 v[124:127], v[154:157], v[186:189], v[124:127]
	v_mfma_f32_16x16x32_bf16 v[120:123], v[162:165], v[186:189], v[120:123]
	v_mfma_f32_16x16x32_bf16 v[108:111], v[154:157], v[194:197], v[108:111]
	v_mfma_f32_16x16x32_bf16 v[104:107], v[162:165], v[194:197], v[104:107]
	v_mfma_f32_16x16x32_bf16 v[92:95], v[154:157], v[202:205], v[92:95]
	v_mfma_f32_16x16x32_bf16 v[88:91], v[162:165], v[202:205], v[88:91]
	v_mfma_f32_16x16x32_bf16 v[76:79], v[154:157], v[210:213], v[76:79]
	v_mfma_f32_16x16x32_bf16 v[72:75], v[162:165], v[210:213], v[72:75]
	v_mfma_f32_16x16x32_bf16 v[116:119], v[166:169], v[182:185], v[116:119]
	v_mfma_f32_16x16x32_bf16 v[112:115], v[174:177], v[182:185], v[112:115]
	v_mfma_f32_16x16x32_bf16 v[100:103], v[166:169], v[190:193], v[100:103]
	v_mfma_f32_16x16x32_bf16 v[96:99], v[174:177], v[190:193], v[96:99]
	v_mfma_f32_16x16x32_bf16 v[84:87], v[166:169], v[198:201], v[84:87]
	v_mfma_f32_16x16x32_bf16 v[80:83], v[174:177], v[198:201], v[80:83]
	v_mfma_f32_16x16x32_bf16 v[68:71], v[166:169], v[206:209], v[68:71]
	v_mfma_f32_16x16x32_bf16 v[64:67], v[174:177], v[206:209], v[64:67]
	v_mfma_f32_16x16x32_bf16 v[116:119], v[170:173], v[186:189], v[116:119]
	v_mfma_f32_16x16x32_bf16 v[112:115], v[178:181], v[186:189], v[112:115]
	v_mfma_f32_16x16x32_bf16 v[100:103], v[170:173], v[194:197], v[100:103]
	v_mfma_f32_16x16x32_bf16 v[96:99], v[178:181], v[194:197], v[96:99]
	v_mfma_f32_16x16x32_bf16 v[84:87], v[170:173], v[202:205], v[84:87]
	v_mfma_f32_16x16x32_bf16 v[80:83], v[178:181], v[202:205], v[80:83]
	v_mfma_f32_16x16x32_bf16 v[68:71], v[170:173], v[210:213], v[68:71]
	v_mfma_f32_16x16x32_bf16 v[64:67], v[178:181], v[210:213], v[64:67]
	s_barrier
	s_add_i32 s58, s75, s60
	v_lshl_add_u64 v[214:215], v[214:215], 0, s[8:9]
	s_mov_b32 m0, s58
	ds_read_b128 v[182:185], v149 offset:49152
	ds_read_b128 v[186:189], v149 offset:50176
	ds_read_b128 v[190:193], v149 offset:51200
	ds_read_b128 v[194:197], v149 offset:52224
	ds_read_b128 v[198:201], v149 offset:53248
	ds_read_b128 v[202:205], v149 offset:54272
	ds_read_b128 v[206:209], v149 offset:55296
	ds_read_b128 v[210:213], v149 offset:56320
	global_load_lds_dwordx4 v[214:215], off
	s_add_i32 m0, s58, 0x2000
	s_add_u32 s56, s56, 0x40080
	v_lshl_add_u64 v[214:215], v[216:217], 0, s[8:9]
	s_addc_u32 s57, s57, 0
	s_add_i32 s58, s76, s60
	global_load_lds_dwordx4 v[214:215], off
	v_lshl_add_u64 v[214:215], s[56:57], 0, v[132:133]
	s_mov_b32 m0, s58
	s_nop 0
	global_load_lds_dwordx4 v[214:215], off
	v_lshl_add_u64 v[214:215], s[56:57], 0, v[128:129]
	s_add_i32 m0, s58, 0x2000
	s_nop 0
	global_load_lds_dwordx4 v[214:215], off
	v_lshl_add_u64 v[214:215], v[218:219], 0, s[8:9]
	s_mov_b32 m0, s64
	s_nop 0
	global_load_lds_dwordx4 v[214:215], off
	v_lshl_add_u64 v[214:215], v[222:223], 0, s[8:9]
	s_mov_b32 m0, s65
	s_nop 0
	global_load_lds_dwordx4 v[214:215], off
	s_waitcnt vmcnt(8)
	s_waitcnt lgkmcnt(0)
	s_barrier
	s_waitcnt lgkmcnt(0)
	v_mfma_f32_16x16x32_bf16 v[60:63], v[150:153], v[182:185], v[60:63]
	v_mfma_f32_16x16x32_bf16 v[56:59], v[158:161], v[182:185], v[56:59]
	v_mfma_f32_16x16x32_bf16 v[44:47], v[150:153], v[190:193], v[44:47]
	v_mfma_f32_16x16x32_bf16 v[40:43], v[158:161], v[190:193], v[40:43]
	v_mfma_f32_16x16x32_bf16 v[28:31], v[150:153], v[198:201], v[28:31]
	v_mfma_f32_16x16x32_bf16 v[24:27], v[158:161], v[198:201], v[24:27]
	v_mfma_f32_16x16x32_bf16 v[12:15], v[150:153], v[206:209], v[12:15]
	v_mfma_f32_16x16x32_bf16 v[8:11], v[158:161], v[206:209], v[8:11]
	v_mfma_f32_16x16x32_bf16 v[60:63], v[154:157], v[186:189], v[60:63]
	v_mfma_f32_16x16x32_bf16 v[56:59], v[162:165], v[186:189], v[56:59]
	v_mfma_f32_16x16x32_bf16 v[44:47], v[154:157], v[194:197], v[44:47]
	v_mfma_f32_16x16x32_bf16 v[40:43], v[162:165], v[194:197], v[40:43]
	v_mfma_f32_16x16x32_bf16 v[28:31], v[154:157], v[202:205], v[28:31]
	v_mfma_f32_16x16x32_bf16 v[24:27], v[162:165], v[202:205], v[24:27]
	v_mfma_f32_16x16x32_bf16 v[12:15], v[154:157], v[210:213], v[12:15]
	v_mfma_f32_16x16x32_bf16 v[8:11], v[162:165], v[210:213], v[8:11]
	v_mfma_f32_16x16x32_bf16 v[52:55], v[166:169], v[182:185], v[52:55]
	v_mfma_f32_16x16x32_bf16 v[48:51], v[174:177], v[182:185], v[48:51]
	v_mfma_f32_16x16x32_bf16 v[36:39], v[166:169], v[190:193], v[36:39]
	v_mfma_f32_16x16x32_bf16 v[32:35], v[174:177], v[190:193], v[32:35]
	v_mfma_f32_16x16x32_bf16 v[20:23], v[166:169], v[198:201], v[20:23]
	v_mfma_f32_16x16x32_bf16 v[16:19], v[174:177], v[198:201], v[16:19]
	v_mfma_f32_16x16x32_bf16 v[4:7], v[166:169], v[206:209], v[4:7]
	v_mfma_f32_16x16x32_bf16 v[0:3], v[174:177], v[206:209], v[0:3]
	v_mfma_f32_16x16x32_bf16 v[52:55], v[170:173], v[186:189], v[52:55]
	v_mfma_f32_16x16x32_bf16 v[48:51], v[178:181], v[186:189], v[48:51]
	v_mfma_f32_16x16x32_bf16 v[36:39], v[170:173], v[194:197], v[36:39]
	v_mfma_f32_16x16x32_bf16 v[32:35], v[178:181], v[194:197], v[32:35]
	v_mfma_f32_16x16x32_bf16 v[20:23], v[170:173], v[202:205], v[20:23]
	v_mfma_f32_16x16x32_bf16 v[16:19], v[178:181], v[202:205], v[16:19]
	v_mfma_f32_16x16x32_bf16 v[4:7], v[170:173], v[210:213], v[4:7]
	v_mfma_f32_16x16x32_bf16 v[0:3], v[178:181], v[210:213], v[0:3]
	s_barrier
	s_add_i32 s74, s74, 2
	s_add_u32 s54, s54, 0x100
	s_addc_u32 s55, s55, 0
	s_add_u32 s72, s72, 0x100
	s_addc_u32 s73, s73, 0
	s_cmp_gt_u32 s74, 13
	s_cbranch_scc0 .LBB0_1376
	v_readlane_b32 s70, v244, 36
	s_and_b64 vcc, exec, s[10:11]
	v_readlane_b32 s71, v244, 37
	s_cbranch_vccz .LBB0_1379
	s_barrier

.Lprio_skip5:
	s_cmp_lg_u32 s99, 0
	s_add_u32 s6, s4, 0x1d00000
	v_mov_b32_e32 v16, v220
	s_addc_u32 s7, s5, 0
	s_and_b64 vcc, exec, s[42:43]
	v_readfirstlane_b32 s0, v16
	s_cbranch_vccz .LBB0_1459
	v_lshlrev_b32_e32 v0, 4, v16
	v_add_u32_e32 v1, 0x2000, v0
	v_ashrrev_i32_e32 v2, 31, v1
	v_lshrrev_b32_e32 v2, 22, v2
	v_add_u32_e32 v2, v1, v2
	v_ashrrev_i32_e32 v8, 10, v2
	v_mul_i32_i24_e32 v2, 0x400, v8
	v_sub_u32_e32 v1, v1, v2
	v_lshrrev_b32_e32 v2, 4, v1
	v_bitop3_b32 v1, v2, v1, 32 bitop3:0x6c
	v_ashrrev_i32_e32 v2, 31, v1
	v_lshrrev_b32_e32 v2, 26, v2
	v_add_u32_e32 v2, v1, v2
	v_lshlrev_b32_e32 v3, 3, v8
	v_ashrrev_i32_e32 v9, 6, v2
	v_and_b32_e32 v3, -16, v3
	v_add_u32_e32 v3, v9, v3
	v_and_b32_e32 v4, 3, v9
	s_mov_b32 s9, 0xffffe0
	v_lshrrev_b32_e32 v5, 2, v3
	v_lshlrev_b32_e32 v6, 1, v3
	v_and_b32_e32 v2, 0xc0, v2
	v_and_or_b32 v4, v3, s9, v4
	v_and_b32_e32 v5, 4, v5
	v_and_b32_e32 v6, 24, v6
	v_sub_u32_e32 v1, v1, v2
	v_mov_b32_e32 v2, 1
	v_or3_b32 v4, v4, v5, v6
	v_lshlrev_b32_e32 v5, 5, v8
	v_ashrrev_i16_sdwa v1, v2, sext(v1) dst_sel:DWORD dst_unused:UNUSED_PAD src0_sel:DWORD src1_sel:BYTE_0
	s_movk_i32 s1, 0xb00
	v_and_b32_e32 v10, 32, v5
	v_bfe_i32 v11, v1, 0, 16
	v_mul_u32_u24_e32 v4, 0xb00, v4
	v_add_u32_e32 v1, v10, v11
	v_mul_lo_u32 v3, v3, s1
	v_add_lshl_u32 v128, v4, v1, 1
	v_add_lshl_u32 v130, v1, v3, 1
	v_bfe_i32 v1, v16, 27, 1
	v_lshrrev_b32_e32 v1, 22, v1
	v_add_u32_e32 v1, v0, v1
	v_and_b32_e32 v1, 0xfffffc00, v1
	v_sub_u32_e32 v0, v0, v1
	v_lshrrev_b32_e32 v1, 4, v0
	v_ashrrev_i32_e32 v3, 31, v16
	v_bitop3_b32 v0, v1, v0, 32 bitop3:0x6c
	v_lshrrev_b32_e32 v3, 26, v3
	v_ashrrev_i32_e32 v1, 31, v0
	v_add_u32_e32 v3, v16, v3
	v_lshrrev_b32_e32 v1, 26, v1
	v_ashrrev_i32_e32 v13, 6, v3
	v_add_u32_e32 v1, v0, v1
	v_lshlrev_b32_e32 v3, 3, v13
	v_ashrrev_i32_e32 v12, 6, v1
	v_and_b32_e32 v3, -16, v3
	s_add_u32 s15, s4, 0xf900000
	v_add_u32_e32 v3, v12, v3
	v_and_b32_e32 v4, 3, v12
	s_addc_u32 s20, s5, 0
	v_and_or_b32 v4, v3, s9, v4
	s_lshr_b32 s9, s3, 29
	s_add_i32 s9, s2, s9
	s_ashr_i32 s10, s9, 3
	s_and_b32 s9, s9, -8
	s_ashr_i32 s8, s0, 6
	s_sub_i32 s9, s2, s9
	s_ashr_i32 s40, s0, 8
	s_lshl_b32 s21, s8, 10
	s_lshl_b32 s22, s9, 6
	s_mul_i32 s11, s9, 0x41
	s_cmp_lt_i32 s9, 0
	s_cselect_b32 s9, s11, s22
	s_add_i32 s9, s9, s10
	s_ashr_i32 s10, s9, 31
	s_lshr_b32 s10, s10, 27
	s_add_i32 s10, s9, s10
	s_ashr_i32 s11, s10, 5
	s_and_b32 s10, s10, 0xffe0
	s_sub_i32 s9, s9, s10
	s_bfe_i32 s10, s9, 0x80000
	s_bfe_u32 s10, s10, 0x3000c
	s_add_i32 s10, s9, s10
	s_bfe_i32 s22, s10, 0x80000
	s_and_b32 s10, s10, 0xf8
	v_lshrrev_b32_e32 v5, 2, v3
	v_lshlrev_b32_e32 v6, 1, v3
	v_and_b32_e32 v1, 0xc0, v1
	s_sext_i32_i16 s22, s22
	s_sub_i32 s9, s9, s10
	v_and_b32_e32 v5, 4, v5
	v_and_b32_e32 v6, 24, v6
	v_sub_u32_e32 v0, v0, v1
	s_lshl_b32 s11, s11, 3
	s_sext_i32_i8 s9, s9
	s_ashr_i32 s10, s22, 3
	v_or3_b32 v4, v4, v5, v6
	v_lshlrev_b32_e32 v5, 5, v13
	v_ashrrev_i16_sdwa v0, v2, sext(v0) dst_sel:DWORD dst_unused:UNUSED_PAD src0_sel:DWORD src1_sel:BYTE_0
	s_lshr_b32 s41, s22, 3
	s_add_i32 s65, s11, s9
	s_mul_hi_i32 s11, s10, 0x160000
	s_mul_i32 s10, s10, 0x160000
	v_and_b32_e32 v14, 32, v5
	v_bfe_i32 v15, v0, 0, 16
	s_add_u32 s52, s6, s10
	v_mul_u32_u24_e32 v4, 0xb00, v4
	v_add_u32_e32 v0, v14, v15
	s_addc_u32 s53, s7, s11
	s_add_i32 s22, s21, 0
	v_add_lshl_u32 v132, v4, v0, 1
	s_add_i32 m0, s22, 0x10000
	s_mul_i32 s23, s65, 0x160000
	global_load_lds_dwordx4 v132, s[52:53]
	s_add_i32 m0, s22, 0x12000
	s_add_u32 s10, s52, 0xb0000
	global_load_lds_dwordx4 v128, s[52:53]
	s_addc_u32 s11, s53, 0
	s_add_i32 m0, s22, 0x14000
	s_mul_hi_i32 s9, s65, 0x160000
	global_load_lds_dwordx4 v132, s[10:11]
	s_add_i32 m0, s22, 0x16000
	s_add_u32 s50, s15, s23
	v_mul_lo_u32 v1, v3, s1
	s_addc_u32 s51, s20, s9
	s_add_i32 s23, s22, 0x2000
	v_add_lshl_u32 v134, v0, v1, 1
	global_load_lds_dwordx4 v128, s[10:11]
	s_mov_b32 m0, s22
	s_add_u32 s10, s50, 0xb0000
	global_load_lds_dwordx4 v134, s[50:51]
	s_mov_b32 m0, s23
	s_addc_u32 s11, s51, 0
	s_add_i32 s33, s22, 0x4000
	global_load_lds_dwordx4 v130, s[50:51]
	s_mov_b32 m0, s33
	s_add_i32 s58, s22, 0x6000
	global_load_lds_dwordx4 v134, s[10:11]
	s_mov_b32 m0, s58
	v_mov_b32_e32 v133, 0
	global_load_lds_dwordx4 v130, s[10:11]
	v_mov_b32_e32 v129, v133
	v_mov_b32_e32 v135, v133
	v_mov_b32_e32 v131, v133
	s_cmp_eq_u32 s40, 1
	s_mov_b32 s9, 0
	v_lshl_add_u64 v[6:7], s[52:53], 0, v[132:133]
	v_lshl_add_u64 v[4:5], s[52:53], 0, v[128:129]
	v_lshl_add_u64 v[0:1], s[50:51], 0, v[134:135]
	s_cselect_b64 s[10:11], -1, 0
	s_cmp_lg_u32 s40, 1
	v_lshl_add_u64 v[2:3], s[50:51], 0, v[130:131]
	s_cbranch_scc1 .LBB0_1438
	s_barrier

.LBB0_1452:
	ds_read_b128 v[150:153], v147
	ds_read_b128 v[154:157], v147 offset:1024
	ds_read_b128 v[158:161], v147 offset:2048
	ds_read_b128 v[162:165], v147 offset:3072
	ds_read_b128 v[166:169], v148
	ds_read_b128 v[170:173], v148 offset:1024
	ds_read_b128 v[174:177], v148 offset:2048
	ds_read_b128 v[178:181], v148 offset:3072
	s_add_u32 s52, s50, 0x100
	s_addc_u32 s53, s51, 0
	s_cmp_eq_u32 s71, 40
	s_cselect_b32 s57, s1, s53
	s_cselect_b32 s56, s0, s52
	s_cselect_b32 s55, s49, s70
	s_cselect_b32 s54, s48, s69
	v_lshl_add_u64 v[214:215], s[50:51], 0, v[136:137]
	s_add_i32 m0, s22, 0xc000
	ds_read_b128 v[182:185], v149
	ds_read_b128 v[186:189], v149 offset:1024
	ds_read_b128 v[190:193], v149 offset:2048
	ds_read_b128 v[194:197], v149 offset:3072
	ds_read_b128 v[198:201], v149 offset:4096
	ds_read_b128 v[202:205], v149 offset:5120
	ds_read_b128 v[206:209], v149 offset:6144
	ds_read_b128 v[210:213], v149 offset:7168
	global_load_lds_dwordx4 v[214:215], off
	v_lshl_add_u64 v[214:215], s[50:51], 0, v[138:139]
	s_add_i32 m0, s22, 0xe000
	s_nop 0
	global_load_lds_dwordx4 v[214:215], off
	s_waitcnt vmcnt(8)
	s_waitcnt lgkmcnt(0)
	s_barrier
	s_waitcnt lgkmcnt(0)
	v_mfma_f32_16x16x32_bf16 v[124:127], v[150:153], v[182:185], v[124:127]
	v_mfma_f32_16x16x32_bf16 v[120:123], v[158:161], v[182:185], v[120:123]
	v_mfma_f32_16x16x32_bf16 v[116:119], v[150:153], v[190:193], v[116:119]
	v_mfma_f32_16x16x32_bf16 v[108:111], v[158:161], v[190:193], v[108:111]
	v_mfma_f32_16x16x32_bf16 v[100:103], v[150:153], v[198:201], v[100:103]
	v_mfma_f32_16x16x32_bf16 v[92:95], v[158:161], v[198:201], v[92:95]
	v_mfma_f32_16x16x32_bf16 v[84:87], v[150:153], v[206:209], v[84:87]
	v_mfma_f32_16x16x32_bf16 v[76:79], v[158:161], v[206:209], v[76:79]
	v_mfma_f32_16x16x32_bf16 v[124:127], v[154:157], v[186:189], v[124:127]
	v_mfma_f32_16x16x32_bf16 v[120:123], v[162:165], v[186:189], v[120:123]
	v_mfma_f32_16x16x32_bf16 v[116:119], v[154:157], v[194:197], v[116:119]
	v_mfma_f32_16x16x32_bf16 v[108:111], v[162:165], v[194:197], v[108:111]
	v_mfma_f32_16x16x32_bf16 v[100:103], v[154:157], v[202:205], v[100:103]
	v_mfma_f32_16x16x32_bf16 v[92:95], v[162:165], v[202:205], v[92:95]
	v_mfma_f32_16x16x32_bf16 v[84:87], v[154:157], v[210:213], v[84:87]
	v_mfma_f32_16x16x32_bf16 v[76:79], v[162:165], v[210:213], v[76:79]
	v_mfma_f32_16x16x32_bf16 v[112:115], v[166:169], v[182:185], v[112:115]
	v_mfma_f32_16x16x32_bf16 v[104:107], v[174:177], v[182:185], v[104:107]
	v_mfma_f32_16x16x32_bf16 v[96:99], v[166:169], v[190:193], v[96:99]
	v_mfma_f32_16x16x32_bf16 v[88:91], v[174:177], v[190:193], v[88:91]
	v_mfma_f32_16x16x32_bf16 v[80:83], v[166:169], v[198:201], v[80:83]
	v_mfma_f32_16x16x32_bf16 v[72:75], v[174:177], v[198:201], v[72:75]
	v_mfma_f32_16x16x32_bf16 v[68:71], v[166:169], v[206:209], v[68:71]
	v_mfma_f32_16x16x32_bf16 v[64:67], v[174:177], v[206:209], v[64:67]
	v_mfma_f32_16x16x32_bf16 v[112:115], v[170:173], v[186:189], v[112:115]
	v_mfma_f32_16x16x32_bf16 v[104:107], v[178:181], v[186:189], v[104:107]
	v_mfma_f32_16x16x32_bf16 v[96:99], v[170:173], v[194:197], v[96:99]
	v_mfma_f32_16x16x32_bf16 v[88:91], v[178:181], v[194:197], v[88:91]
	v_mfma_f32_16x16x32_bf16 v[80:83], v[170:173], v[202:205], v[80:83]
	v_mfma_f32_16x16x32_bf16 v[72:75], v[178:181], v[202:205], v[72:75]
	v_mfma_f32_16x16x32_bf16 v[68:71], v[170:173], v[210:213], v[68:71]
	v_mfma_f32_16x16x32_bf16 v[64:67], v[178:181], v[210:213], v[64:67]
	s_barrier
	s_add_i32 s50, s62, s21
	v_lshl_add_u64 v[214:215], s[54:55], 0, v[132:133]
	s_mov_b32 m0, s50
	ds_read_b128 v[182:185], v149 offset:16384
	ds_read_b128 v[186:189], v149 offset:17408
	ds_read_b128 v[190:193], v149 offset:18432
	ds_read_b128 v[194:197], v149 offset:19456
	ds_read_b128 v[198:201], v149 offset:20480
	ds_read_b128 v[202:205], v149 offset:21504
	ds_read_b128 v[206:209], v149 offset:22528
	ds_read_b128 v[210:213], v149 offset:23552
	global_load_lds_dwordx4 v[214:215], off
	s_add_i32 m0, s50, 0x2000
	s_add_u32 s50, s54, 0xb0000
	v_lshl_add_u64 v[216:217], s[54:55], 0, v[128:129]
	s_addc_u32 s51, s55, 0
	s_add_i32 s72, s63, s21
	global_load_lds_dwordx4 v[216:217], off
	v_lshl_add_u64 v[218:219], s[50:51], 0, v[132:133]
	s_mov_b32 m0, s72
	v_lshl_add_u64 v[222:223], s[56:57], 0, v[130:131]
	global_load_lds_dwordx4 v[218:219], off
	v_lshl_add_u64 v[218:219], s[50:51], 0, v[128:129]
	s_add_i32 m0, s72, 0x2000
	s_nop 0
	global_load_lds_dwordx4 v[218:219], off
	v_lshl_add_u64 v[218:219], s[56:57], 0, v[134:135]
	s_mov_b32 m0, s22
	s_nop 0
	global_load_lds_dwordx4 v[218:219], off
	s_mov_b32 m0, s23
	s_nop 0
	global_load_lds_dwordx4 v[222:223], off
	s_waitcnt vmcnt(8)
	s_waitcnt lgkmcnt(0)
	s_barrier
	s_waitcnt lgkmcnt(0)
	v_mfma_f32_16x16x32_bf16 v[60:63], v[150:153], v[182:185], v[60:63]
	v_mfma_f32_16x16x32_bf16 v[56:59], v[158:161], v[182:185], v[56:59]
	v_mfma_f32_16x16x32_bf16 v[52:55], v[150:153], v[190:193], v[52:55]
	v_mfma_f32_16x16x32_bf16 v[44:47], v[158:161], v[190:193], v[44:47]
	v_mfma_f32_16x16x32_bf16 v[36:39], v[150:153], v[198:201], v[36:39]
	v_mfma_f32_16x16x32_bf16 v[28:31], v[158:161], v[198:201], v[28:31]
	v_mfma_f32_16x16x32_bf16 v[20:23], v[150:153], v[206:209], v[20:23]
	v_mfma_f32_16x16x32_bf16 v[12:15], v[158:161], v[206:209], v[12:15]
	v_mfma_f32_16x16x32_bf16 v[60:63], v[154:157], v[186:189], v[60:63]
	v_mfma_f32_16x16x32_bf16 v[56:59], v[162:165], v[186:189], v[56:59]
	v_mfma_f32_16x16x32_bf16 v[52:55], v[154:157], v[194:197], v[52:55]
	v_mfma_f32_16x16x32_bf16 v[44:47], v[162:165], v[194:197], v[44:47]
	v_mfma_f32_16x16x32_bf16 v[36:39], v[154:157], v[202:205], v[36:39]
	v_mfma_f32_16x16x32_bf16 v[28:31], v[162:165], v[202:205], v[28:31]
	v_mfma_f32_16x16x32_bf16 v[20:23], v[154:157], v[210:213], v[20:23]
	v_mfma_f32_16x16x32_bf16 v[12:15], v[162:165], v[210:213], v[12:15]
	v_mfma_f32_16x16x32_bf16 v[48:51], v[166:169], v[182:185], v[48:51]
	v_mfma_f32_16x16x32_bf16 v[40:43], v[174:177], v[182:185], v[40:43]
	v_mfma_f32_16x16x32_bf16 v[32:35], v[166:169], v[190:193], v[32:35]
	v_mfma_f32_16x16x32_bf16 v[24:27], v[174:177], v[190:193], v[24:27]
	v_mfma_f32_16x16x32_bf16 v[16:19], v[166:169], v[198:201], v[16:19]
	v_mfma_f32_16x16x32_bf16 v[8:11], v[174:177], v[198:201], v[8:11]
	v_mfma_f32_16x16x32_bf16 v[4:7], v[166:169], v[206:209], v[4:7]
	v_mfma_f32_16x16x32_bf16 v[0:3], v[174:177], v[206:209], v[0:3]
	v_mfma_f32_16x16x32_bf16 v[48:51], v[170:173], v[186:189], v[48:51]
	v_mfma_f32_16x16x32_bf16 v[40:43], v[178:181], v[186:189], v[40:43]
	v_mfma_f32_16x16x32_bf16 v[32:35], v[170:173], v[194:197], v[32:35]
	v_mfma_f32_16x16x32_bf16 v[24:27], v[178:181], v[194:197], v[24:27]
	v_mfma_f32_16x16x32_bf16 v[16:19], v[170:173], v[202:205], v[16:19]
	v_mfma_f32_16x16x32_bf16 v[8:11], v[178:181], v[202:205], v[8:11]
	v_mfma_f32_16x16x32_bf16 v[4:7], v[170:173], v[210:213], v[4:7]
	v_mfma_f32_16x16x32_bf16 v[0:3], v[178:181], v[210:213], v[0:3]
	s_barrier
	s_add_i32 s72, 0, 0x18000
	s_add_i32 s73, 0, 0x1c000
	v_add_u32_e32 v162, s72, v146
	v_add_u32_e32 v178, s73, v146
	ds_read_b128 v[150:153], v162
	ds_read_b128 v[154:157], v162 offset:1024
	ds_read_b128 v[158:161], v162 offset:2048
	ds_read_b128 v[162:165], v162 offset:3072
	ds_read_b128 v[166:169], v178
	ds_read_b128 v[170:173], v178 offset:1024
	ds_read_b128 v[174:177], v178 offset:2048
	ds_read_b128 v[178:181], v178 offset:3072
	s_add_u32 s50, s56, 0xb0000
	s_addc_u32 s51, s57, 0
	s_mov_b32 m0, s33
	v_lshl_add_u64 v[224:225], s[50:51], 0, v[134:135]
	ds_read_b128 v[182:185], v149 offset:32768
	ds_read_b128 v[186:189], v149 offset:33792
	ds_read_b128 v[190:193], v149 offset:34816
	ds_read_b128 v[194:197], v149 offset:35840
	ds_read_b128 v[198:201], v149 offset:36864
	ds_read_b128 v[202:205], v149 offset:37888
	ds_read_b128 v[206:209], v149 offset:38912
	ds_read_b128 v[210:213], v149 offset:39936
	global_load_lds_dwordx4 v[224:225], off
	v_lshl_add_u64 v[224:225], s[50:51], 0, v[130:131]
	s_mov_b32 m0, s58
	s_nop 0
	global_load_lds_dwordx4 v[224:225], off
	s_waitcnt vmcnt(8)
	s_waitcnt lgkmcnt(0)
	s_barrier
	s_waitcnt lgkmcnt(0)
	v_mfma_f32_16x16x32_bf16 v[124:127], v[150:153], v[182:185], v[124:127]
	v_mfma_f32_16x16x32_bf16 v[120:123], v[158:161], v[182:185], v[120:123]
	v_mfma_f32_16x16x32_bf16 v[116:119], v[150:153], v[190:193], v[116:119]
	v_mfma_f32_16x16x32_bf16 v[108:111], v[158:161], v[190:193], v[108:111]
	v_mfma_f32_16x16x32_bf16 v[100:103], v[150:153], v[198:201], v[100:103]
	v_mfma_f32_16x16x32_bf16 v[92:95], v[158:161], v[198:201], v[92:95]
	v_mfma_f32_16x16x32_bf16 v[84:87], v[150:153], v[206:209], v[84:87]
	v_mfma_f32_16x16x32_bf16 v[76:79], v[158:161], v[206:209], v[76:79]
	v_mfma_f32_16x16x32_bf16 v[124:127], v[154:157], v[186:189], v[124:127]
	v_mfma_f32_16x16x32_bf16 v[120:123], v[162:165], v[186:189], v[120:123]
	v_mfma_f32_16x16x32_bf16 v[116:119], v[154:157], v[194:197], v[116:119]
	v_mfma_f32_16x16x32_bf16 v[108:111], v[162:165], v[194:197], v[108:111]
	v_mfma_f32_16x16x32_bf16 v[100:103], v[154:157], v[202:205], v[100:103]
	v_mfma_f32_16x16x32_bf16 v[92:95], v[162:165], v[202:205], v[92:95]
	v_mfma_f32_16x16x32_bf16 v[84:87], v[154:157], v[210:213], v[84:87]
	v_mfma_f32_16x16x32_bf16 v[76:79], v[162:165], v[210:213], v[76:79]
	v_mfma_f32_16x16x32_bf16 v[112:115], v[166:169], v[182:185], v[112:115]
	v_mfma_f32_16x16x32_bf16 v[104:107], v[174:177], v[182:185], v[104:107]
	v_mfma_f32_16x16x32_bf16 v[96:99], v[166:169], v[190:193], v[96:99]
	v_mfma_f32_16x16x32_bf16 v[88:91], v[174:177], v[190:193], v[88:91]
	v_mfma_f32_16x16x32_bf16 v[80:83], v[166:169], v[198:201], v[80:83]
	v_mfma_f32_16x16x32_bf16 v[72:75], v[174:177], v[198:201], v[72:75]
	v_mfma_f32_16x16x32_bf16 v[68:71], v[166:169], v[206:209], v[68:71]
	v_mfma_f32_16x16x32_bf16 v[64:67], v[174:177], v[206:209], v[64:67]
	v_mfma_f32_16x16x32_bf16 v[112:115], v[170:173], v[186:189], v[112:115]
	v_mfma_f32_16x16x32_bf16 v[104:107], v[178:181], v[186:189], v[104:107]
	v_mfma_f32_16x16x32_bf16 v[96:99], v[170:173], v[194:197], v[96:99]
	v_mfma_f32_16x16x32_bf16 v[88:91], v[178:181], v[194:197], v[88:91]
	v_mfma_f32_16x16x32_bf16 v[80:83], v[170:173], v[202:205], v[80:83]
	v_mfma_f32_16x16x32_bf16 v[72:75], v[178:181], v[202:205], v[72:75]
	v_mfma_f32_16x16x32_bf16 v[68:71], v[170:173], v[210:213], v[68:71]
	v_mfma_f32_16x16x32_bf16 v[64:67], v[178:181], v[210:213], v[64:67]
	s_barrier
	s_add_i32 s50, s72, s21
	v_lshl_add_u64 v[214:215], v[214:215], 0, s[44:45]
	s_mov_b32 m0, s50
	ds_read_b128 v[182:185], v149 offset:49152
	ds_read_b128 v[186:189], v149 offset:50176
	ds_read_b128 v[190:193], v149 offset:51200
	ds_read_b128 v[194:197], v149 offset:52224
	ds_read_b128 v[198:201], v149 offset:53248
	ds_read_b128 v[202:205], v149 offset:54272
	ds_read_b128 v[206:209], v149 offset:55296
	ds_read_b128 v[210:213], v149 offset:56320
	global_load_lds_dwordx4 v[214:215], off
	s_add_i32 m0, s50, 0x2000
	s_add_u32 s50, s54, 0xb0080
	v_lshl_add_u64 v[214:215], v[216:217], 0, s[44:45]
	s_addc_u32 s51, s55, 0
	s_add_i32 s54, s73, s21
	global_load_lds_dwordx4 v[214:215], off
	v_lshl_add_u64 v[214:215], s[50:51], 0, v[132:133]
	s_mov_b32 m0, s54
	s_nop 0
	global_load_lds_dwordx4 v[214:215], off
	v_lshl_add_u64 v[214:215], s[50:51], 0, v[128:129]
	s_add_i32 m0, s54, 0x2000
	s_nop 0
	global_load_lds_dwordx4 v[214:215], off
	v_lshl_add_u64 v[214:215], v[218:219], 0, s[44:45]
	s_mov_b32 m0, s60
	s_nop 0
	global_load_lds_dwordx4 v[214:215], off
	v_lshl_add_u64 v[214:215], v[222:223], 0, s[44:45]
	s_mov_b32 m0, s61
	s_nop 0
	global_load_lds_dwordx4 v[214:215], off
	s_waitcnt vmcnt(8)
	s_waitcnt lgkmcnt(0)
	s_barrier
	s_waitcnt lgkmcnt(0)
	v_mfma_f32_16x16x32_bf16 v[60:63], v[150:153], v[182:185], v[60:63]
	v_mfma_f32_16x16x32_bf16 v[56:59], v[158:161], v[182:185], v[56:59]
	v_mfma_f32_16x16x32_bf16 v[52:55], v[150:153], v[190:193], v[52:55]
	v_mfma_f32_16x16x32_bf16 v[44:47], v[158:161], v[190:193], v[44:47]
	v_mfma_f32_16x16x32_bf16 v[36:39], v[150:153], v[198:201], v[36:39]
	v_mfma_f32_16x16x32_bf16 v[28:31], v[158:161], v[198:201], v[28:31]
	v_mfma_f32_16x16x32_bf16 v[20:23], v[150:153], v[206:209], v[20:23]
	v_mfma_f32_16x16x32_bf16 v[12:15], v[158:161], v[206:209], v[12:15]
	v_mfma_f32_16x16x32_bf16 v[60:63], v[154:157], v[186:189], v[60:63]
	v_mfma_f32_16x16x32_bf16 v[56:59], v[162:165], v[186:189], v[56:59]
	v_mfma_f32_16x16x32_bf16 v[52:55], v[154:157], v[194:197], v[52:55]
	v_mfma_f32_16x16x32_bf16 v[44:47], v[162:165], v[194:197], v[44:47]
	v_mfma_f32_16x16x32_bf16 v[36:39], v[154:157], v[202:205], v[36:39]
	v_mfma_f32_16x16x32_bf16 v[28:31], v[162:165], v[202:205], v[28:31]
	v_mfma_f32_16x16x32_bf16 v[20:23], v[154:157], v[210:213], v[20:23]
	v_mfma_f32_16x16x32_bf16 v[12:15], v[162:165], v[210:213], v[12:15]
	v_mfma_f32_16x16x32_bf16 v[48:51], v[166:169], v[182:185], v[48:51]
	v_mfma_f32_16x16x32_bf16 v[40:43], v[174:177], v[182:185], v[40:43]
	v_mfma_f32_16x16x32_bf16 v[32:35], v[166:169], v[190:193], v[32:35]
	v_mfma_f32_16x16x32_bf16 v[24:27], v[174:177], v[190:193], v[24:27]
	v_mfma_f32_16x16x32_bf16 v[16:19], v[166:169], v[198:201], v[16:19]
	v_mfma_f32_16x16x32_bf16 v[8:11], v[174:177], v[198:201], v[8:11]
	v_mfma_f32_16x16x32_bf16 v[4:7], v[166:169], v[206:209], v[4:7]
	v_mfma_f32_16x16x32_bf16 v[0:3], v[174:177], v[206:209], v[0:3]
	v_mfma_f32_16x16x32_bf16 v[48:51], v[170:173], v[186:189], v[48:51]
	v_mfma_f32_16x16x32_bf16 v[40:43], v[178:181], v[186:189], v[40:43]
	v_mfma_f32_16x16x32_bf16 v[32:35], v[170:173], v[194:197], v[32:35]
	v_mfma_f32_16x16x32_bf16 v[24:27], v[178:181], v[194:197], v[24:27]
	v_mfma_f32_16x16x32_bf16 v[16:19], v[170:173], v[202:205], v[16:19]
	v_mfma_f32_16x16x32_bf16 v[8:11], v[178:181], v[202:205], v[8:11]
	v_mfma_f32_16x16x32_bf16 v[4:7], v[170:173], v[210:213], v[4:7]
	v_mfma_f32_16x16x32_bf16 v[0:3], v[178:181], v[210:213], v[0:3]
	s_barrier
	s_add_i32 s71, s71, 2
	s_add_u32 s69, s69, 0x100
	s_addc_u32 s70, s70, 0
	s_cmp_gt_u32 s71, 41
	s_mov_b64 s[50:51], s[52:53]
	s_cbranch_scc0 .LBB0_1452
	s_and_b64 vcc, exec, s[46:47]
	s_cbranch_vccz .LBB0_1455
	s_barrier

.LBB0_1514:
	s_or_b64 exec, exec, s[0:1]
	s_waitcnt lgkmcnt(0)
	s_barrier
	s_setprio 0
	v_readlane_b32 s0, v245, 37
	v_lshlrev_b32_e32 v0, 3, v220
	v_and_b32_e32 v17, 0x1f8, v0
	v_lshlrev_b32_e32 v16, 2, v17
	v_readlane_b32 s6, v245, 43
	v_readlane_b32 s7, v245, 44
	s_nop 4
	global_load_dwordx4 v[0:3], v16, s[6:7] offset:16
	global_load_dwordx4 v[4:7], v16, s[6:7]
	global_load_dwordx4 v[8:11], v16, s[6:7] offset:2064
	global_load_dwordx4 v[12:15], v16, s[6:7] offset:2048
	v_readfirstlane_b32 s0, v220
	s_ashr_i32 s0, s0, 6
	v_readlane_b32 s1, v245, 38
	s_add_i32 s6, s0, s83
	s_add_i32 s1, s6, s34
	s_cmp_lt_i32 s1, 0x8200
	v_and_b32_e32 v106, 63, v220
	v_readlane_b32 s2, v245, 39
	v_readlane_b32 s3, v245, 40
	v_readlane_b32 s4, v245, 41
	v_readlane_b32 s5, v245, 42
	s_cbranch_scc0 .LBB0_1517
	v_mbcnt_hi_u32_b32 v18, -1, v221
	v_and_b32_e32 v20, 64, v18
	v_add_u32_e32 v20, 64, v20
	v_xor_b32_e32 v21, 1, v18
	v_cmp_lt_i32_e32 vcc, v21, v20
	s_ashr_i32 s1, s0, 31
	s_ashr_i32 s4, s83, 31
	v_cndmask_b32_e32 v21, v18, v21, vcc
	v_lshlrev_b32_e32 v107, 2, v21
	v_xor_b32_e32 v21, 2, v18
	v_cmp_lt_i32_e32 vcc, v21, v20
	s_add_u32 s0, s0, s83
	s_addc_u32 s1, s1, s4
	v_cndmask_b32_e32 v21, v18, v21, vcc
	v_lshlrev_b32_e32 v108, 2, v21
	v_xor_b32_e32 v21, 4, v18
	v_cmp_lt_i32_e32 vcc, v21, v20
	s_lshl_b64 s[4:5], s[0:1], 12
	s_add_u32 s4, s64, s4
	v_cndmask_b32_e32 v21, v18, v21, vcc
	v_lshlrev_b32_e32 v109, 2, v21
	v_xor_b32_e32 v21, 8, v18
	v_cmp_lt_i32_e32 vcc, v21, v20
	s_addc_u32 s5, s65, s5
	s_ashr_i32 s87, s86, 31
	v_cndmask_b32_e32 v21, v18, v21, vcc
	v_lshlrev_b32_e32 v110, 2, v21
	v_xor_b32_e32 v21, 16, v18
	v_cmp_lt_i32_e32 vcc, v21, v20
	v_mov_b32_e32 v19, 0
	s_lshl_b64 s[8:9], s[86:87], 12
	v_cndmask_b32_e32 v21, v18, v21, vcc
	v_lshlrev_b32_e32 v111, 2, v21
	v_xor_b32_e32 v21, 32, v18
	v_cmp_lt_i32_e32 vcc, v21, v20
	s_lshl_b64 s[0:1], s[0:1], 11
	s_add_u32 s0, s66, s0
	v_cndmask_b32_e32 v18, v18, v21, vcc
	v_lshlrev_b32_e32 v112, 2, v18
	v_lshlrev_b32_e32 v18, 1, v17
	v_lshl_add_u64 v[20:21], s[66:67], 0, v[18:19]
	v_mov_b32_e32 v17, v19
	v_lshlrev_b32_e32 v18, 5, v106
	s_mov_b64 s[2:3], 0xb800000
	v_lshl_add_u64 v[28:29], s[64:65], 0, v[16:17]
	v_lshl_add_u64 v[16:17], s[4:5], 0, v[18:19]
	s_mov_b64 s[4:5], 0x810
	v_lshlrev_b32_e32 v18, 4, v106
	s_addc_u32 s1, s67, s1
	v_lshl_add_u64 v[24:25], v[20:21], 0, s[2:3]
	s_mov_b64 s[2:3], 0x7700000
	v_lshl_add_u64 v[30:31], v[16:17], 0, s[4:5]
	v_lshl_add_u64 v[16:17], s[0:1], 0, v[18:19]
	v_lshl_add_u64 v[26:27], v[20:21], 0, s[2:3]
	v_lshl_add_u64 v[32:33], v[16:17], 0, s[2:3]
	s_lshl_b64 s[10:11], s[86:87], 11
	s_lshl_b32 s7, s96, 4
	s_mov_b32 s12, 0x3a800000
	s_mov_b32 s16, 0x358637bd
	s_mov_b32 s13, 0x800000
